# K-loops: removed the redundant lgkmcnt ladder inside MFMA segments and the s_nop 0 pads after LDS-DMA asm blocks
# speedup vs baseline: 1.0086x; 1.0009x over previous
; #define PG8_STAGE(bufoff, gbase, voff) do { if constexpr (VAR != 1 && VAR != 3) { _Pragma("unroll") for (int _i = 0; _i < 2; ++_i) \
;         asm volatile("s_mov_b32 m0, %2\n\ts_nop 0\n\tglobal_load_lds_dwordx4 %0, %1" :: "v"((voff)[_i]), "s"((const char*)(gbase)), "s"(ldsbase + (unsigned)((bufoff) + _i * 8192)) : "memory", "m0"); } } while (0)
; #define PG8_LDA(dst, b, h) do { if constexpr (VAR < 2) _Pragma("unroll") for (int m = 0; m < 4; ++m) _Pragma("unroll") for (int k = 0; k < 2; ++k) dst[m][k] = *(const LAS bf16x8*)(lds + PG8_SA(b, h) + aoff + m * 2048 + k * 1024); } while (0)
; #define PG8_LDB(dst, b, h) do { if constexpr (VAR < 2) _Pragma("unroll") for (int n = 0; n < 2; ++n) _Pragma("unroll") for (int k = 0; k < 2; ++k) dst[n][k] = *(const LAS bf16x8*)(lds + PG8_SB(b, h) + boff + n * 2048 + k * 1024); } while (0)
; #define PG8_WAIT_V(n) asm volatile("s_waitcnt vmcnt(" #n ")" ::: "memory")
; #define PG8_WAIT_L(n) asm volatile("s_waitcnt lgkmcnt(" #n ")" ::: "memory")
; #define PG8_BAR do { if constexpr (VAR != 3) __builtin_amdgcn_s_barrier(); } while (0)
; #define PG8_SCHED __builtin_amdgcn_sched_barrier(0)
;     ...
;         for (int t = 0; t < nt; t += 2) {
;             const bool last = (t == nt - 2);
;             const char* a1 = cA + (size_t)(t + 1) * kstep;
;             const char* a2 = last ? nA : cA + (size_t)(t + 2) * kstep; const char* b2 = last ? nB : cB + (size_t)(t + 2) * kstep;
;             const char* a3 = a2 + kstep; const char* b3 = b2 + kstep;
;             PG8_LDB(B0, 0, 0); PG8_LDB(B1, 0, 1); PG8_SCHED; PG8_LDA(At, 0, 0); PG8_STAGE(PG8_SA(1, 1), a1 + hstepA, voffA);
;             PG8_WAIT_V(8); PG8_WAIT_L(0); PG8_BAR; PG8_MMA(0, 0, At, B0); PG8_MMA(0, 1, At, B1); PG8_BAR; PG8_SCHED;
;             PG8_LDA(At, 0, 1); PG8_STAGE(PG8_SB(0, 0), b2, voffB); PG8_STAGE(PG8_SB(0, 1), b2 + hstepB, voffB); PG8_STAGE(PG8_SA(0, 0), a2, voffA);
;             PG8_WAIT_V(8); PG8_WAIT_L(0); PG8_BAR; PG8_MMA(1, 0, At, B0); PG8_MMA(1, 1, At, B1); PG8_BAR; PG8_SCHED;
.LBB0_346:
	ds_read_b128 v[156:159], v151
	ds_read_b128 v[160:163], v151 offset:1024
	ds_read_b128 v[164:167], v151 offset:2048
	ds_read_b128 v[168:171], v151 offset:3072
	ds_read_b128 v[172:175], v152
	ds_read_b128 v[176:179], v152 offset:1024
	ds_read_b128 v[180:183], v152 offset:2048
	ds_read_b128 v[184:187], v152 offset:3072
	s_cmp_eq_u32 vcc_hi, 60
	s_cselect_b32 s96, s15, s66
	s_cselect_b32 s97, s14, s67
	s_cselect_b32 s94, s65, s69
	s_cselect_b32 s95, s63, vcc_lo
	s_add_u32 s92, s96, 0x80
	s_addc_u32 s93, s97, 0
	ds_read_b128 v[188:191], v153
	ds_read_b128 v[192:195], v153 offset:1024
	ds_read_b128 v[196:199], v153 offset:2048
	ds_read_b128 v[200:203], v153 offset:3072
	ds_read_b128 v[204:207], v153 offset:4096
	ds_read_b128 v[208:211], v153 offset:5120
	ds_read_b128 v[212:215], v153 offset:6144
	ds_read_b128 v[216:219], v153 offset:7168
	s_mov_b32 m0, s56
	s_nop 0
	global_load_lds_dwordx4 v1, s[90:91]
	s_mov_b32 m0, s57
	s_nop 0
	global_load_lds_dwordx4 v147, s[90:91]
	s_waitcnt vmcnt(8)
	s_waitcnt lgkmcnt(0)
	s_barrier
	s_setprio 1
	v_mfma_f32_16x16x32_bf16 v[126:129], v[156:159], v[188:191], v[126:129]
	v_mfma_f32_16x16x32_bf16 v[122:125], v[164:167], v[188:191], v[122:125]
	v_mfma_f32_16x16x32_bf16 v[118:121], v[156:159], v[196:199], v[118:121]
	v_mfma_f32_16x16x32_bf16 v[110:113], v[164:167], v[196:199], v[110:113]
	v_mfma_f32_16x16x32_bf16 v[102:105], v[156:159], v[204:207], v[102:105]
	v_mfma_f32_16x16x32_bf16 v[94:97], v[164:167], v[204:207], v[94:97]
	v_mfma_f32_16x16x32_bf16 v[86:89], v[156:159], v[212:215], v[86:89]
	v_mfma_f32_16x16x32_bf16 v[78:81], v[164:167], v[212:215], v[78:81]
	v_mfma_f32_16x16x32_bf16 v[126:129], v[160:163], v[192:195], v[126:129]
	v_mfma_f32_16x16x32_bf16 v[122:125], v[168:171], v[192:195], v[122:125]
	v_mfma_f32_16x16x32_bf16 v[118:121], v[160:163], v[200:203], v[118:121]
	v_mfma_f32_16x16x32_bf16 v[110:113], v[168:171], v[200:203], v[110:113]
	v_mfma_f32_16x16x32_bf16 v[102:105], v[160:163], v[208:211], v[102:105]
	v_mfma_f32_16x16x32_bf16 v[94:97], v[168:171], v[208:211], v[94:97]
	v_mfma_f32_16x16x32_bf16 v[86:89], v[160:163], v[216:219], v[86:89]
	v_mfma_f32_16x16x32_bf16 v[78:81], v[168:171], v[216:219], v[78:81]
	s_setprio 0
	s_setprio 1
	v_mfma_f32_16x16x32_bf16 v[114:117], v[172:175], v[188:191], v[114:117]
	v_mfma_f32_16x16x32_bf16 v[106:109], v[180:183], v[188:191], v[106:109]
	v_mfma_f32_16x16x32_bf16 v[98:101], v[172:175], v[196:199], v[98:101]
	v_mfma_f32_16x16x32_bf16 v[90:93], v[180:183], v[196:199], v[90:93]
	v_mfma_f32_16x16x32_bf16 v[82:85], v[172:175], v[204:207], v[82:85]
	v_mfma_f32_16x16x32_bf16 v[74:77], v[180:183], v[204:207], v[74:77]
	v_mfma_f32_16x16x32_bf16 v[70:73], v[172:175], v[212:215], v[70:73]
	v_mfma_f32_16x16x32_bf16 v[66:69], v[180:183], v[212:215], v[66:69]
	v_mfma_f32_16x16x32_bf16 v[114:117], v[176:179], v[192:195], v[114:117]
	v_mfma_f32_16x16x32_bf16 v[106:109], v[184:187], v[192:195], v[106:109]
	v_mfma_f32_16x16x32_bf16 v[98:101], v[176:179], v[200:203], v[98:101]
	v_mfma_f32_16x16x32_bf16 v[90:93], v[184:187], v[200:203], v[90:93]
	v_mfma_f32_16x16x32_bf16 v[82:85], v[176:179], v[208:211], v[82:85]
	v_mfma_f32_16x16x32_bf16 v[74:77], v[184:187], v[208:211], v[74:77]
	v_mfma_f32_16x16x32_bf16 v[70:73], v[176:179], v[216:219], v[70:73]
	v_mfma_f32_16x16x32_bf16 v[66:69], v[184:187], v[216:219], v[66:69]
	s_setprio 0
	s_barrier
	ds_read_b128 v[188:191], v153 offset:16384
	ds_read_b128 v[192:195], v153 offset:17408
	ds_read_b128 v[196:199], v153 offset:18432
	ds_read_b128 v[200:203], v153 offset:19456
	ds_read_b128 v[204:207], v153 offset:20480
	ds_read_b128 v[208:211], v153 offset:21504
	ds_read_b128 v[212:215], v153 offset:22528
	ds_read_b128 v[216:219], v153 offset:23552
	s_mov_b32 m0, s25
	s_nop 0
	global_load_lds_dwordx4 v146, s[94:95]
	s_add_u32 s6, s94, 0x100000
	s_mov_b32 m0, s26
	s_nop 0
	global_load_lds_dwordx4 v148, s[94:95]
	s_addc_u32 s7, s95, 0
	s_mov_b32 m0, s27
	s_nop 0
	global_load_lds_dwordx4 v146, s[6:7]
	s_mov_b32 m0, s28
	s_nop 0
	global_load_lds_dwordx4 v148, s[6:7]
	s_mov_b32 m0, s19
	s_nop 0
	global_load_lds_dwordx4 v1, s[96:97]
	s_mov_b32 m0, s29
	s_nop 0
	global_load_lds_dwordx4 v147, s[96:97]
	s_waitcnt vmcnt(8)
	s_waitcnt lgkmcnt(0)
	s_barrier
	s_setprio 1
	v_mfma_f32_16x16x32_bf16 v[62:65], v[156:159], v[188:191], v[62:65]
	v_mfma_f32_16x16x32_bf16 v[58:61], v[164:167], v[188:191], v[58:61]
	v_mfma_f32_16x16x32_bf16 v[54:57], v[156:159], v[196:199], v[54:57]
	v_mfma_f32_16x16x32_bf16 v[46:49], v[164:167], v[196:199], v[46:49]
	v_mfma_f32_16x16x32_bf16 v[38:41], v[156:159], v[204:207], v[38:41]
	v_mfma_f32_16x16x32_bf16 v[30:33], v[164:167], v[204:207], v[30:33]
	v_mfma_f32_16x16x32_bf16 v[22:25], v[156:159], v[212:215], v[22:25]
	v_mfma_f32_16x16x32_bf16 v[14:17], v[164:167], v[212:215], v[14:17]
	v_mfma_f32_16x16x32_bf16 v[62:65], v[160:163], v[192:195], v[62:65]
	v_mfma_f32_16x16x32_bf16 v[58:61], v[168:171], v[192:195], v[58:61]
	v_mfma_f32_16x16x32_bf16 v[54:57], v[160:163], v[200:203], v[54:57]
	v_mfma_f32_16x16x32_bf16 v[46:49], v[168:171], v[200:203], v[46:49]
	v_mfma_f32_16x16x32_bf16 v[38:41], v[160:163], v[208:211], v[38:41]
	v_mfma_f32_16x16x32_bf16 v[30:33], v[168:171], v[208:211], v[30:33]
	v_mfma_f32_16x16x32_bf16 v[22:25], v[160:163], v[216:219], v[22:25]
	v_mfma_f32_16x16x32_bf16 v[14:17], v[168:171], v[216:219], v[14:17]
	s_setprio 0
	s_setprio 1
	v_mfma_f32_16x16x32_bf16 v[50:53], v[172:175], v[188:191], v[50:53]
	v_mfma_f32_16x16x32_bf16 v[42:45], v[180:183], v[188:191], v[42:45]
	v_mfma_f32_16x16x32_bf16 v[34:37], v[172:175], v[196:199], v[34:37]
	v_mfma_f32_16x16x32_bf16 v[26:29], v[180:183], v[196:199], v[26:29]
	v_mfma_f32_16x16x32_bf16 v[18:21], v[172:175], v[204:207], v[18:21]
	v_mfma_f32_16x16x32_bf16 v[10:13], v[180:183], v[204:207], v[10:13]
	v_mfma_f32_16x16x32_bf16 v[6:9], v[172:175], v[212:215], v[6:9]
	v_mfma_f32_16x16x32_bf16 v[2:5], v[180:183], v[212:215], v[2:5]
	v_mfma_f32_16x16x32_bf16 v[50:53], v[176:179], v[192:195], v[50:53]
	v_mfma_f32_16x16x32_bf16 v[42:45], v[184:187], v[192:195], v[42:45]
	v_mfma_f32_16x16x32_bf16 v[34:37], v[176:179], v[200:203], v[34:37]
	v_mfma_f32_16x16x32_bf16 v[26:29], v[184:187], v[200:203], v[26:29]
	v_mfma_f32_16x16x32_bf16 v[18:21], v[176:179], v[208:211], v[18:21]
	v_mfma_f32_16x16x32_bf16 v[10:13], v[184:187], v[208:211], v[10:13]
	v_mfma_f32_16x16x32_bf16 v[6:9], v[176:179], v[216:219], v[6:9]
	v_mfma_f32_16x16x32_bf16 v[2:5], v[184:187], v[216:219], v[2:5]
	s_setprio 0
	s_barrier
; #define PG8_STAGE(bufoff, gbase, voff) do { if constexpr (VAR != 1 && VAR != 3) { _Pragma("unroll") for (int _i = 0; _i < 2; ++_i) \
;         asm volatile("s_mov_b32 m0, %2\n\ts_nop 0\n\tglobal_load_lds_dwordx4 %0, %1" :: "v"((voff)[_i]), "s"((const char*)(gbase)), "s"(ldsbase + (unsigned)((bufoff) + _i * 8192)) : "memory", "m0"); } } while (0)
; #define PG8_LDA(dst, b, h) do { if constexpr (VAR < 2) _Pragma("unroll") for (int m = 0; m < 4; ++m) _Pragma("unroll") for (int k = 0; k < 2; ++k) dst[m][k] = *(const LAS bf16x8*)(lds + PG8_SA(b, h) + aoff + m * 2048 + k * 1024); } while (0)
; #define PG8_LDB(dst, b, h) do { if constexpr (VAR < 2) _Pragma("unroll") for (int n = 0; n < 2; ++n) _Pragma("unroll") for (int k = 0; k < 2; ++k) dst[n][k] = *(const LAS bf16x8*)(lds + PG8_SB(b, h) + boff + n * 2048 + k * 1024); } while (0)
; #define PG8_WAIT_V(n) asm volatile("s_waitcnt vmcnt(" #n ")" ::: "memory")
; #define PG8_WAIT_L(n) asm volatile("s_waitcnt lgkmcnt(" #n ")" ::: "memory")
; #define PG8_BAR do { if constexpr (VAR != 3) __builtin_amdgcn_s_barrier(); } while (0)
; #define PG8_SCHED __builtin_amdgcn_sched_barrier(0)
;     ...
;             PG8_LDB(B0, 1, 0); PG8_LDB(B1, 1, 1); PG8_SCHED; PG8_LDA(At, 1, 0); PG8_STAGE(PG8_SA(0, 1), a2 + hstepA, voffA);
;             PG8_WAIT_V(8); PG8_WAIT_L(0); PG8_BAR; PG8_MMA(0, 0, At, B0); PG8_MMA(0, 1, At, B1); PG8_BAR; PG8_SCHED;
;             PG8_LDA(At, 1, 1); PG8_STAGE(PG8_SB(1, 0), b3, voffB); PG8_STAGE(PG8_SB(1, 1), b3 + hstepB, voffB); PG8_STAGE(PG8_SA(1, 0), a3, voffA);
;             PG8_WAIT_V(8); PG8_WAIT_L(0); PG8_BAR; PG8_MMA(1, 0, At, B0); PG8_MMA(1, 1, At, B1); PG8_BAR; PG8_SCHED;
;         }
;         if (wr == 0) PG8_BAR;
	ds_read_b128 v[156:159], v154
	ds_read_b128 v[160:163], v154 offset:1024
	ds_read_b128 v[164:167], v154 offset:2048
	ds_read_b128 v[168:171], v154 offset:3072
	ds_read_b128 v[172:175], v155
	ds_read_b128 v[176:179], v155 offset:1024
	ds_read_b128 v[180:183], v155 offset:2048
	ds_read_b128 v[184:187], v155 offset:3072
	ds_read_b128 v[188:191], v153 offset:32768
	ds_read_b128 v[192:195], v153 offset:33792
	ds_read_b128 v[196:199], v153 offset:34816
	ds_read_b128 v[200:203], v153 offset:35840
	ds_read_b128 v[204:207], v153 offset:36864
	ds_read_b128 v[208:211], v153 offset:37888
	ds_read_b128 v[212:215], v153 offset:38912
	ds_read_b128 v[216:219], v153 offset:39936
	s_add_u32 s6, s96, 0x100000
	s_addc_u32 s7, s97, 0
	s_mov_b32 m0, s30
	s_nop 0
	global_load_lds_dwordx4 v1, s[6:7]
	s_mov_b32 m0, s31
	s_nop 0
	global_load_lds_dwordx4 v147, s[6:7]
	s_waitcnt vmcnt(8)
	s_waitcnt lgkmcnt(0)
	s_barrier
	s_setprio 1
	v_mfma_f32_16x16x32_bf16 v[126:129], v[156:159], v[188:191], v[126:129]
	v_mfma_f32_16x16x32_bf16 v[122:125], v[164:167], v[188:191], v[122:125]
	v_mfma_f32_16x16x32_bf16 v[118:121], v[156:159], v[196:199], v[118:121]
	v_mfma_f32_16x16x32_bf16 v[110:113], v[164:167], v[196:199], v[110:113]
	v_mfma_f32_16x16x32_bf16 v[102:105], v[156:159], v[204:207], v[102:105]
	v_mfma_f32_16x16x32_bf16 v[94:97], v[164:167], v[204:207], v[94:97]
	v_mfma_f32_16x16x32_bf16 v[86:89], v[156:159], v[212:215], v[86:89]
	v_mfma_f32_16x16x32_bf16 v[78:81], v[164:167], v[212:215], v[78:81]
	v_mfma_f32_16x16x32_bf16 v[126:129], v[160:163], v[192:195], v[126:129]
	v_mfma_f32_16x16x32_bf16 v[122:125], v[168:171], v[192:195], v[122:125]
	v_mfma_f32_16x16x32_bf16 v[118:121], v[160:163], v[200:203], v[118:121]
	v_mfma_f32_16x16x32_bf16 v[110:113], v[168:171], v[200:203], v[110:113]
	v_mfma_f32_16x16x32_bf16 v[102:105], v[160:163], v[208:211], v[102:105]
	v_mfma_f32_16x16x32_bf16 v[94:97], v[168:171], v[208:211], v[94:97]
	v_mfma_f32_16x16x32_bf16 v[86:89], v[160:163], v[216:219], v[86:89]
	v_mfma_f32_16x16x32_bf16 v[78:81], v[168:171], v[216:219], v[78:81]
	s_setprio 0
	s_setprio 1
	v_mfma_f32_16x16x32_bf16 v[114:117], v[172:175], v[188:191], v[114:117]
	v_mfma_f32_16x16x32_bf16 v[106:109], v[180:183], v[188:191], v[106:109]
	v_mfma_f32_16x16x32_bf16 v[98:101], v[172:175], v[196:199], v[98:101]
	v_mfma_f32_16x16x32_bf16 v[90:93], v[180:183], v[196:199], v[90:93]
	v_mfma_f32_16x16x32_bf16 v[82:85], v[172:175], v[204:207], v[82:85]
	v_mfma_f32_16x16x32_bf16 v[74:77], v[180:183], v[204:207], v[74:77]
	v_mfma_f32_16x16x32_bf16 v[70:73], v[172:175], v[212:215], v[70:73]
	v_mfma_f32_16x16x32_bf16 v[66:69], v[180:183], v[212:215], v[66:69]
	v_mfma_f32_16x16x32_bf16 v[114:117], v[176:179], v[192:195], v[114:117]
	v_mfma_f32_16x16x32_bf16 v[106:109], v[184:187], v[192:195], v[106:109]
	v_mfma_f32_16x16x32_bf16 v[98:101], v[176:179], v[200:203], v[98:101]
	v_mfma_f32_16x16x32_bf16 v[90:93], v[184:187], v[200:203], v[90:93]
	v_mfma_f32_16x16x32_bf16 v[82:85], v[176:179], v[208:211], v[82:85]
	v_mfma_f32_16x16x32_bf16 v[74:77], v[184:187], v[208:211], v[74:77]
	v_mfma_f32_16x16x32_bf16 v[70:73], v[176:179], v[216:219], v[70:73]
	v_mfma_f32_16x16x32_bf16 v[66:69], v[184:187], v[216:219], v[66:69]
	s_setprio 0
	s_barrier
	ds_read_b128 v[188:191], v153 offset:49152
	ds_read_b128 v[192:195], v153 offset:50176
	ds_read_b128 v[196:199], v153 offset:51200
	ds_read_b128 v[200:203], v153 offset:52224
	ds_read_b128 v[204:207], v153 offset:53248
	ds_read_b128 v[208:211], v153 offset:54272
	ds_read_b128 v[212:215], v153 offset:55296
	ds_read_b128 v[216:219], v153 offset:56320
	s_add_u32 s6, s94, 0x80
	s_addc_u32 s7, s95, 0
	s_mov_b32 m0, s33
	s_nop 0
	global_load_lds_dwordx4 v146, s[6:7]
	s_mov_b32 m0, s35
	s_nop 0
	global_load_lds_dwordx4 v148, s[6:7]
	s_add_u32 s6, s94, 0x100080
	s_addc_u32 s7, s95, 0
	s_mov_b32 m0, s54
	s_nop 0
	global_load_lds_dwordx4 v146, s[6:7]
	s_mov_b32 m0, s55
	s_nop 0
	global_load_lds_dwordx4 v148, s[6:7]
	s_mov_b32 m0, s52
	s_nop 0
	global_load_lds_dwordx4 v1, s[92:93]
	s_mov_b32 m0, s53
	s_nop 0
	global_load_lds_dwordx4 v147, s[92:93]
	s_waitcnt vmcnt(8)
	s_waitcnt lgkmcnt(0)
	s_barrier
	s_setprio 1
	v_mfma_f32_16x16x32_bf16 v[62:65], v[156:159], v[188:191], v[62:65]
	v_mfma_f32_16x16x32_bf16 v[58:61], v[164:167], v[188:191], v[58:61]
	v_mfma_f32_16x16x32_bf16 v[54:57], v[156:159], v[196:199], v[54:57]
	v_mfma_f32_16x16x32_bf16 v[46:49], v[164:167], v[196:199], v[46:49]
	v_mfma_f32_16x16x32_bf16 v[38:41], v[156:159], v[204:207], v[38:41]
	v_mfma_f32_16x16x32_bf16 v[30:33], v[164:167], v[204:207], v[30:33]
	v_mfma_f32_16x16x32_bf16 v[22:25], v[156:159], v[212:215], v[22:25]
	v_mfma_f32_16x16x32_bf16 v[14:17], v[164:167], v[212:215], v[14:17]
	v_mfma_f32_16x16x32_bf16 v[62:65], v[160:163], v[192:195], v[62:65]
	v_mfma_f32_16x16x32_bf16 v[58:61], v[168:171], v[192:195], v[58:61]
	v_mfma_f32_16x16x32_bf16 v[54:57], v[160:163], v[200:203], v[54:57]
	v_mfma_f32_16x16x32_bf16 v[46:49], v[168:171], v[200:203], v[46:49]
	v_mfma_f32_16x16x32_bf16 v[38:41], v[160:163], v[208:211], v[38:41]
	v_mfma_f32_16x16x32_bf16 v[30:33], v[168:171], v[208:211], v[30:33]
	v_mfma_f32_16x16x32_bf16 v[22:25], v[160:163], v[216:219], v[22:25]
	v_mfma_f32_16x16x32_bf16 v[14:17], v[168:171], v[216:219], v[14:17]
	s_setprio 0
	s_setprio 1
	v_mfma_f32_16x16x32_bf16 v[50:53], v[172:175], v[188:191], v[50:53]
	v_mfma_f32_16x16x32_bf16 v[42:45], v[180:183], v[188:191], v[42:45]
	v_mfma_f32_16x16x32_bf16 v[34:37], v[172:175], v[196:199], v[34:37]
	v_mfma_f32_16x16x32_bf16 v[26:29], v[180:183], v[196:199], v[26:29]
	v_mfma_f32_16x16x32_bf16 v[18:21], v[172:175], v[204:207], v[18:21]
	v_mfma_f32_16x16x32_bf16 v[10:13], v[180:183], v[204:207], v[10:13]
	v_mfma_f32_16x16x32_bf16 v[6:9], v[172:175], v[212:215], v[6:9]
	v_mfma_f32_16x16x32_bf16 v[2:5], v[180:183], v[212:215], v[2:5]
	v_mfma_f32_16x16x32_bf16 v[50:53], v[176:179], v[192:195], v[50:53]
	v_mfma_f32_16x16x32_bf16 v[42:45], v[184:187], v[192:195], v[42:45]
	v_mfma_f32_16x16x32_bf16 v[34:37], v[176:179], v[200:203], v[34:37]
	v_mfma_f32_16x16x32_bf16 v[26:29], v[184:187], v[200:203], v[26:29]
	v_mfma_f32_16x16x32_bf16 v[18:21], v[176:179], v[208:211], v[18:21]
	v_mfma_f32_16x16x32_bf16 v[10:13], v[184:187], v[208:211], v[10:13]
	v_mfma_f32_16x16x32_bf16 v[6:9], v[176:179], v[216:219], v[6:9]
	v_mfma_f32_16x16x32_bf16 v[2:5], v[184:187], v[216:219], v[2:5]
	s_setprio 0
	s_barrier
	s_add_i32 vcc_hi, vcc_hi, 2
	s_add_u32 s66, s66, 0x100
	s_addc_u32 s67, s67, 0
	s_add_u32 s69, s69, 0x100
	s_addc_u32 vcc_lo, vcc_lo, 0
	s_add_u32 s90, s90, 0x100
	s_addc_u32 s91, s91, 0
	s_cmp_gt_u32 vcc_hi, 61
	s_cbranch_scc0 .LBB0_346
	s_and_b64 vcc, exec, s[4:5]
	s_cbranch_vccz .LBB0_349
	s_barrier

; #define PG8_STAGE(bufoff, gbase, voff) do { if constexpr (VAR != 1 && VAR != 3) { _Pragma("unroll") for (int _i = 0; _i < 2; ++_i) \
;         asm volatile("s_mov_b32 m0, %2\n\ts_nop 0\n\tglobal_load_lds_dwordx4 %0, %1" :: "v"((voff)[_i]), "s"((const char*)(gbase)), "s"(ldsbase + (unsigned)((bufoff) + _i * 8192)) : "memory", "m0"); } } while (0)
; #define PG8_LDA(dst, b, h) do { if constexpr (VAR < 2) _Pragma("unroll") for (int m = 0; m < 4; ++m) _Pragma("unroll") for (int k = 0; k < 2; ++k) dst[m][k] = *(const LAS bf16x8*)(lds + PG8_SA(b, h) + aoff + m * 2048 + k * 1024); } while (0)
; #define PG8_LDB(dst, b, h) do { if constexpr (VAR < 2) _Pragma("unroll") for (int n = 0; n < 2; ++n) _Pragma("unroll") for (int k = 0; k < 2; ++k) dst[n][k] = *(const LAS bf16x8*)(lds + PG8_SB(b, h) + boff + n * 2048 + k * 1024); } while (0)
; #define PG8_WAIT_V(n) asm volatile("s_waitcnt vmcnt(" #n ")" ::: "memory")
; #define PG8_WAIT_L(n) asm volatile("s_waitcnt lgkmcnt(" #n ")" ::: "memory")
; #define PG8_BAR do { if constexpr (VAR != 3) __builtin_amdgcn_s_barrier(); } while (0)
; #define PG8_SCHED __builtin_amdgcn_sched_barrier(0)
;     ...
;         for (int t = 0; t < nt; t += 2) {
;             const bool last = (t == nt - 2);
;             const char* a1 = cA + (size_t)(t + 1) * kstep;
;             const char* a2 = last ? nA : cA + (size_t)(t + 2) * kstep; const char* b2 = last ? nB : cB + (size_t)(t + 2) * kstep;
;             const char* a3 = a2 + kstep; const char* b3 = b2 + kstep;
;             PG8_LDB(B0, 0, 0); PG8_LDB(B1, 0, 1); PG8_SCHED; PG8_LDA(At, 0, 0); PG8_STAGE(PG8_SA(1, 1), a1 + hstepA, voffA);
;             PG8_WAIT_V(8); PG8_WAIT_L(0); PG8_BAR; PG8_MMA(0, 0, At, B0); PG8_MMA(0, 1, At, B1); PG8_BAR; PG8_SCHED;
;             PG8_LDA(At, 0, 1); PG8_STAGE(PG8_SB(0, 0), b2, voffB); PG8_STAGE(PG8_SB(0, 1), b2 + hstepB, voffB); PG8_STAGE(PG8_SA(0, 0), a2, voffA);
;             PG8_WAIT_V(8); PG8_WAIT_L(0); PG8_BAR; PG8_MMA(1, 0, At, B0); PG8_MMA(1, 1, At, B1); PG8_BAR; PG8_SCHED;
.LBB0_539:
	ds_read_b128 v[138:141], v159
	ds_read_b128 v[164:167], v159 offset:1024
	ds_read_b128 v[168:171], v159 offset:2048
	ds_read_b128 v[172:175], v159 offset:3072
	ds_read_b128 v[176:179], v160
	ds_read_b128 v[180:183], v160 offset:1024
	ds_read_b128 v[184:187], v160 offset:2048
	ds_read_b128 v[188:191], v160 offset:3072
	s_cmp_eq_u32 s6, 28
	s_cselect_b32 s94, s15, vcc_lo
	s_cselect_b32 s95, s14, vcc_hi
	s_cselect_b32 s92, s73, s54
	s_cselect_b32 s93, s71, s55
	s_add_u32 s90, s94, 0x80
	s_addc_u32 s91, s95, 0
	ds_read_b128 v[192:195], v161
	ds_read_b128 v[196:199], v161 offset:1024
	ds_read_b128 v[200:203], v161 offset:2048
	ds_read_b128 v[204:207], v161 offset:3072
	ds_read_b128 v[208:211], v161 offset:4096
	ds_read_b128 v[212:215], v161 offset:5120
	ds_read_b128 v[216:219], v161 offset:6144
	ds_read_b128 v[220:223], v161 offset:7168
	s_mov_b32 m0, s57
	s_nop 0
	global_load_lds_dwordx4 v151, s[88:89]
	s_mov_b32 m0, s24
	s_nop 0
	global_load_lds_dwordx4 v153, s[88:89]
	s_waitcnt vmcnt(8)
	s_waitcnt lgkmcnt(0)
	s_barrier
	s_setprio 1
	v_mfma_i32_16x16x64_i8 v[126:129], v[138:141], v[192:195], v[126:129]
	v_mfma_i32_16x16x64_i8 v[118:121], v[168:171], v[192:195], v[118:121]
	v_mfma_i32_16x16x64_i8 v[110:113], v[138:141], v[200:203], v[110:113]
	v_mfma_i32_16x16x64_i8 v[102:105], v[168:171], v[200:203], v[102:105]
	v_mfma_i32_16x16x64_i8 v[94:97], v[138:141], v[208:211], v[94:97]
	v_mfma_i32_16x16x64_i8 v[86:89], v[168:171], v[208:211], v[86:89]
	v_mfma_i32_16x16x64_i8 v[78:81], v[138:141], v[216:219], v[78:81]
	v_mfma_i32_16x16x64_i8 v[70:73], v[168:171], v[216:219], v[70:73]
	v_mfma_i32_16x16x64_i8 v[126:129], v[164:167], v[196:199], v[126:129]
	v_mfma_i32_16x16x64_i8 v[118:121], v[172:175], v[196:199], v[118:121]
	v_mfma_i32_16x16x64_i8 v[110:113], v[164:167], v[204:207], v[110:113]
	v_mfma_i32_16x16x64_i8 v[102:105], v[172:175], v[204:207], v[102:105]
	v_mfma_i32_16x16x64_i8 v[94:97], v[164:167], v[212:215], v[94:97]
	v_mfma_i32_16x16x64_i8 v[86:89], v[172:175], v[212:215], v[86:89]
	v_mfma_i32_16x16x64_i8 v[78:81], v[164:167], v[220:223], v[78:81]
	v_mfma_i32_16x16x64_i8 v[70:73], v[172:175], v[220:223], v[70:73]
	s_setprio 0
	s_setprio 1
	v_mfma_i32_16x16x64_i8 v[122:125], v[176:179], v[192:195], v[122:125]
	v_mfma_i32_16x16x64_i8 v[114:117], v[184:187], v[192:195], v[114:117]
	v_mfma_i32_16x16x64_i8 v[106:109], v[176:179], v[200:203], v[106:109]
	v_mfma_i32_16x16x64_i8 v[98:101], v[184:187], v[200:203], v[98:101]
	v_mfma_i32_16x16x64_i8 v[90:93], v[176:179], v[208:211], v[90:93]
	v_mfma_i32_16x16x64_i8 v[82:85], v[184:187], v[208:211], v[82:85]
	v_mfma_i32_16x16x64_i8 v[74:77], v[176:179], v[216:219], v[74:77]
	v_mfma_i32_16x16x64_i8 v[66:69], v[184:187], v[216:219], v[66:69]
	v_mfma_i32_16x16x64_i8 v[122:125], v[180:183], v[196:199], v[122:125]
	v_mfma_i32_16x16x64_i8 v[114:117], v[188:191], v[196:199], v[114:117]
	v_mfma_i32_16x16x64_i8 v[106:109], v[180:183], v[204:207], v[106:109]
	v_mfma_i32_16x16x64_i8 v[98:101], v[188:191], v[204:207], v[98:101]
	v_mfma_i32_16x16x64_i8 v[90:93], v[180:183], v[212:215], v[90:93]
	v_mfma_i32_16x16x64_i8 v[82:85], v[188:191], v[212:215], v[82:85]
	v_mfma_i32_16x16x64_i8 v[74:77], v[180:183], v[220:223], v[74:77]
	v_mfma_i32_16x16x64_i8 v[66:69], v[188:191], v[220:223], v[66:69]
	s_setprio 0
	s_barrier
	ds_read_b128 v[192:195], v161 offset:16384
	ds_read_b128 v[196:199], v161 offset:17408
	ds_read_b128 v[200:203], v161 offset:18432
	ds_read_b128 v[204:207], v161 offset:19456
	ds_read_b128 v[208:211], v161 offset:20480
	ds_read_b128 v[212:215], v161 offset:21504
	ds_read_b128 v[216:219], v161 offset:22528
	ds_read_b128 v[220:223], v161 offset:23552
	s_mov_b32 m0, s29
	s_nop 0
	global_load_lds_dwordx4 v152, s[92:93]
	s_add_u32 s10, s92, 0x80000
	s_mov_b32 m0, s30
	s_nop 0
	global_load_lds_dwordx4 v154, s[92:93]
	s_addc_u32 s11, s93, 0
	s_mov_b32 m0, s31
	s_nop 0
	global_load_lds_dwordx4 v152, s[10:11]
	s_mov_b32 m0, s33
	s_nop 0
	global_load_lds_dwordx4 v154, s[10:11]
	s_mov_b32 m0, s26
	s_nop 0
	global_load_lds_dwordx4 v151, s[94:95]
	s_mov_b32 m0, s35
	s_nop 0
	global_load_lds_dwordx4 v153, s[94:95]
	s_waitcnt vmcnt(8)
	s_waitcnt lgkmcnt(0)
	s_barrier
	s_setprio 1
	v_mfma_i32_16x16x64_i8 v[62:65], v[138:141], v[192:195], v[62:65]
	v_mfma_i32_16x16x64_i8 v[54:57], v[168:171], v[192:195], v[54:57]
	v_mfma_i32_16x16x64_i8 v[46:49], v[138:141], v[200:203], v[46:49]
	v_mfma_i32_16x16x64_i8 v[38:41], v[168:171], v[200:203], v[38:41]
	v_mfma_i32_16x16x64_i8 v[30:33], v[138:141], v[208:211], v[30:33]
	v_mfma_i32_16x16x64_i8 v[22:25], v[168:171], v[208:211], v[22:25]
	v_mfma_i32_16x16x64_i8 v[14:17], v[138:141], v[216:219], v[14:17]
	v_mfma_i32_16x16x64_i8 v[6:9], v[168:171], v[216:219], v[6:9]
	v_mfma_i32_16x16x64_i8 v[62:65], v[164:167], v[196:199], v[62:65]
	v_mfma_i32_16x16x64_i8 v[54:57], v[172:175], v[196:199], v[54:57]
	v_mfma_i32_16x16x64_i8 v[46:49], v[164:167], v[204:207], v[46:49]
	v_mfma_i32_16x16x64_i8 v[38:41], v[172:175], v[204:207], v[38:41]
	v_mfma_i32_16x16x64_i8 v[30:33], v[164:167], v[212:215], v[30:33]
	v_mfma_i32_16x16x64_i8 v[22:25], v[172:175], v[212:215], v[22:25]
	v_mfma_i32_16x16x64_i8 v[14:17], v[164:167], v[220:223], v[14:17]
	v_mfma_i32_16x16x64_i8 v[6:9], v[172:175], v[220:223], v[6:9]
	s_setprio 0
	s_setprio 1
	v_mfma_i32_16x16x64_i8 v[58:61], v[176:179], v[192:195], v[58:61]
	v_mfma_i32_16x16x64_i8 v[50:53], v[184:187], v[192:195], v[50:53]
	v_mfma_i32_16x16x64_i8 v[42:45], v[176:179], v[200:203], v[42:45]
	v_mfma_i32_16x16x64_i8 v[34:37], v[184:187], v[200:203], v[34:37]
	v_mfma_i32_16x16x64_i8 v[26:29], v[176:179], v[208:211], v[26:29]
	v_mfma_i32_16x16x64_i8 v[18:21], v[184:187], v[208:211], v[18:21]
	v_mfma_i32_16x16x64_i8 v[10:13], v[176:179], v[216:219], v[10:13]
	v_mfma_i32_16x16x64_i8 v[2:5], v[184:187], v[216:219], v[2:5]
	v_mfma_i32_16x16x64_i8 v[58:61], v[180:183], v[196:199], v[58:61]
	v_mfma_i32_16x16x64_i8 v[50:53], v[188:191], v[196:199], v[50:53]
	v_mfma_i32_16x16x64_i8 v[42:45], v[180:183], v[204:207], v[42:45]
	v_mfma_i32_16x16x64_i8 v[34:37], v[188:191], v[204:207], v[34:37]
	v_mfma_i32_16x16x64_i8 v[26:29], v[180:183], v[212:215], v[26:29]
	v_mfma_i32_16x16x64_i8 v[18:21], v[188:191], v[212:215], v[18:21]
	v_mfma_i32_16x16x64_i8 v[10:13], v[180:183], v[220:223], v[10:13]
	v_mfma_i32_16x16x64_i8 v[2:5], v[188:191], v[220:223], v[2:5]
	s_setprio 0
	s_barrier
; #define PG8_STAGE(bufoff, gbase, voff) do { if constexpr (VAR != 1 && VAR != 3) { _Pragma("unroll") for (int _i = 0; _i < 2; ++_i) \
;         asm volatile("s_mov_b32 m0, %2\n\ts_nop 0\n\tglobal_load_lds_dwordx4 %0, %1" :: "v"((voff)[_i]), "s"((const char*)(gbase)), "s"(ldsbase + (unsigned)((bufoff) + _i * 8192)) : "memory", "m0"); } } while (0)
; #define PG8_LDA(dst, b, h) do { if constexpr (VAR < 2) _Pragma("unroll") for (int m = 0; m < 4; ++m) _Pragma("unroll") for (int k = 0; k < 2; ++k) dst[m][k] = *(const LAS bf16x8*)(lds + PG8_SA(b, h) + aoff + m * 2048 + k * 1024); } while (0)
; #define PG8_LDB(dst, b, h) do { if constexpr (VAR < 2) _Pragma("unroll") for (int n = 0; n < 2; ++n) _Pragma("unroll") for (int k = 0; k < 2; ++k) dst[n][k] = *(const LAS bf16x8*)(lds + PG8_SB(b, h) + boff + n * 2048 + k * 1024); } while (0)
; #define PG8_WAIT_V(n) asm volatile("s_waitcnt vmcnt(" #n ")" ::: "memory")
; #define PG8_WAIT_L(n) asm volatile("s_waitcnt lgkmcnt(" #n ")" ::: "memory")
; #define PG8_BAR do { if constexpr (VAR != 3) __builtin_amdgcn_s_barrier(); } while (0)
; #define PG8_SCHED __builtin_amdgcn_sched_barrier(0)
;     ...
;             PG8_LDB(B0, 1, 0); PG8_LDB(B1, 1, 1); PG8_SCHED; PG8_LDA(At, 1, 0); PG8_STAGE(PG8_SA(0, 1), a2 + hstepA, voffA);
;             PG8_WAIT_V(8); PG8_WAIT_L(0); PG8_BAR; PG8_MMA(0, 0, At, B0); PG8_MMA(0, 1, At, B1); PG8_BAR; PG8_SCHED;
;             PG8_LDA(At, 1, 1); PG8_STAGE(PG8_SB(1, 0), b3, voffB); PG8_STAGE(PG8_SB(1, 1), b3 + hstepB, voffB); PG8_STAGE(PG8_SA(1, 0), a3, voffA);
;             PG8_WAIT_V(8); PG8_WAIT_L(0); PG8_BAR; PG8_MMA(1, 0, At, B0); PG8_MMA(1, 1, At, B1); PG8_BAR; PG8_SCHED;
;         }
;         if (wr == 0) PG8_BAR;
	ds_read_b128 v[138:141], v162
	ds_read_b128 v[164:167], v162 offset:1024
	ds_read_b128 v[168:171], v162 offset:2048
	ds_read_b128 v[172:175], v162 offset:3072
	ds_read_b128 v[176:179], v163
	ds_read_b128 v[180:183], v163 offset:1024
	ds_read_b128 v[184:187], v163 offset:2048
	ds_read_b128 v[188:191], v163 offset:3072
	ds_read_b128 v[192:195], v161 offset:32768
	ds_read_b128 v[196:199], v161 offset:33792
	ds_read_b128 v[200:203], v161 offset:34816
	ds_read_b128 v[204:207], v161 offset:35840
	ds_read_b128 v[208:211], v161 offset:36864
	ds_read_b128 v[212:215], v161 offset:37888
	ds_read_b128 v[216:219], v161 offset:38912
	ds_read_b128 v[220:223], v161 offset:39936
	s_add_u32 s10, s94, 0x80000
	s_addc_u32 s11, s95, 0
	s_mov_b32 m0, s62
	s_nop 0
	global_load_lds_dwordx4 v151, s[10:11]
	s_mov_b32 m0, s63
	s_nop 0
	global_load_lds_dwordx4 v153, s[10:11]
	s_waitcnt vmcnt(8)
	s_waitcnt lgkmcnt(0)
	s_barrier
	s_setprio 1
	v_mfma_i32_16x16x64_i8 v[126:129], v[138:141], v[192:195], v[126:129]
	v_mfma_i32_16x16x64_i8 v[118:121], v[168:171], v[192:195], v[118:121]
	v_mfma_i32_16x16x64_i8 v[110:113], v[138:141], v[200:203], v[110:113]
	v_mfma_i32_16x16x64_i8 v[102:105], v[168:171], v[200:203], v[102:105]
	v_mfma_i32_16x16x64_i8 v[94:97], v[138:141], v[208:211], v[94:97]
	v_mfma_i32_16x16x64_i8 v[86:89], v[168:171], v[208:211], v[86:89]
	v_mfma_i32_16x16x64_i8 v[78:81], v[138:141], v[216:219], v[78:81]
	v_mfma_i32_16x16x64_i8 v[70:73], v[168:171], v[216:219], v[70:73]
	v_mfma_i32_16x16x64_i8 v[126:129], v[164:167], v[196:199], v[126:129]
	v_mfma_i32_16x16x64_i8 v[118:121], v[172:175], v[196:199], v[118:121]
	v_mfma_i32_16x16x64_i8 v[110:113], v[164:167], v[204:207], v[110:113]
	v_mfma_i32_16x16x64_i8 v[102:105], v[172:175], v[204:207], v[102:105]
	v_mfma_i32_16x16x64_i8 v[94:97], v[164:167], v[212:215], v[94:97]
	v_mfma_i32_16x16x64_i8 v[86:89], v[172:175], v[212:215], v[86:89]
	v_mfma_i32_16x16x64_i8 v[78:81], v[164:167], v[220:223], v[78:81]
	v_mfma_i32_16x16x64_i8 v[70:73], v[172:175], v[220:223], v[70:73]
	s_setprio 0
	s_setprio 1
	v_mfma_i32_16x16x64_i8 v[122:125], v[176:179], v[192:195], v[122:125]
	v_mfma_i32_16x16x64_i8 v[114:117], v[184:187], v[192:195], v[114:117]
	v_mfma_i32_16x16x64_i8 v[106:109], v[176:179], v[200:203], v[106:109]
	v_mfma_i32_16x16x64_i8 v[98:101], v[184:187], v[200:203], v[98:101]
	v_mfma_i32_16x16x64_i8 v[90:93], v[176:179], v[208:211], v[90:93]
	v_mfma_i32_16x16x64_i8 v[82:85], v[184:187], v[208:211], v[82:85]
	v_mfma_i32_16x16x64_i8 v[74:77], v[176:179], v[216:219], v[74:77]
	v_mfma_i32_16x16x64_i8 v[66:69], v[184:187], v[216:219], v[66:69]
	v_mfma_i32_16x16x64_i8 v[122:125], v[180:183], v[196:199], v[122:125]
	v_mfma_i32_16x16x64_i8 v[114:117], v[188:191], v[196:199], v[114:117]
	v_mfma_i32_16x16x64_i8 v[106:109], v[180:183], v[204:207], v[106:109]
	v_mfma_i32_16x16x64_i8 v[98:101], v[188:191], v[204:207], v[98:101]
	v_mfma_i32_16x16x64_i8 v[90:93], v[180:183], v[212:215], v[90:93]
	v_mfma_i32_16x16x64_i8 v[82:85], v[188:191], v[212:215], v[82:85]
	v_mfma_i32_16x16x64_i8 v[74:77], v[180:183], v[220:223], v[74:77]
	v_mfma_i32_16x16x64_i8 v[66:69], v[188:191], v[220:223], v[66:69]
	s_setprio 0
	s_barrier
	ds_read_b128 v[192:195], v161 offset:49152
	ds_read_b128 v[196:199], v161 offset:50176
	ds_read_b128 v[200:203], v161 offset:51200
	ds_read_b128 v[204:207], v161 offset:52224
	ds_read_b128 v[208:211], v161 offset:53248
	ds_read_b128 v[212:215], v161 offset:54272
	ds_read_b128 v[216:219], v161 offset:55296
	ds_read_b128 v[220:223], v161 offset:56320
	s_add_u32 s10, s92, 0x80
	s_addc_u32 s11, s93, 0
	s_mov_b32 m0, s87
	s_nop 0
	global_load_lds_dwordx4 v152, s[10:11]
	s_mov_b32 m0, s96
	s_nop 0
	global_load_lds_dwordx4 v154, s[10:11]
	s_add_u32 s10, s92, 0x80080
	s_addc_u32 s11, s93, 0
	s_mov_b32 m0, s53
	s_nop 0
	global_load_lds_dwordx4 v152, s[10:11]
	s_mov_b32 m0, s56
	s_nop 0
	global_load_lds_dwordx4 v154, s[10:11]
	s_mov_b32 m0, s97
	s_nop 0
	global_load_lds_dwordx4 v151, s[90:91]
	s_mov_b32 m0, s52
	s_nop 0
	global_load_lds_dwordx4 v153, s[90:91]
	s_waitcnt vmcnt(8)
	s_waitcnt lgkmcnt(0)
	s_barrier
	s_setprio 1
	v_mfma_i32_16x16x64_i8 v[62:65], v[138:141], v[192:195], v[62:65]
	v_mfma_i32_16x16x64_i8 v[54:57], v[168:171], v[192:195], v[54:57]
	v_mfma_i32_16x16x64_i8 v[46:49], v[138:141], v[200:203], v[46:49]
	v_mfma_i32_16x16x64_i8 v[38:41], v[168:171], v[200:203], v[38:41]
	v_mfma_i32_16x16x64_i8 v[30:33], v[138:141], v[208:211], v[30:33]
	v_mfma_i32_16x16x64_i8 v[22:25], v[168:171], v[208:211], v[22:25]
	v_mfma_i32_16x16x64_i8 v[14:17], v[138:141], v[216:219], v[14:17]
	v_mfma_i32_16x16x64_i8 v[6:9], v[168:171], v[216:219], v[6:9]
	v_mfma_i32_16x16x64_i8 v[62:65], v[164:167], v[196:199], v[62:65]
	v_mfma_i32_16x16x64_i8 v[54:57], v[172:175], v[196:199], v[54:57]
	v_mfma_i32_16x16x64_i8 v[46:49], v[164:167], v[204:207], v[46:49]
	v_mfma_i32_16x16x64_i8 v[38:41], v[172:175], v[204:207], v[38:41]
	v_mfma_i32_16x16x64_i8 v[30:33], v[164:167], v[212:215], v[30:33]
	v_mfma_i32_16x16x64_i8 v[22:25], v[172:175], v[212:215], v[22:25]
	v_mfma_i32_16x16x64_i8 v[14:17], v[164:167], v[220:223], v[14:17]
	v_mfma_i32_16x16x64_i8 v[6:9], v[172:175], v[220:223], v[6:9]
	s_setprio 0
	s_setprio 1
	v_mfma_i32_16x16x64_i8 v[58:61], v[176:179], v[192:195], v[58:61]
	v_mfma_i32_16x16x64_i8 v[50:53], v[184:187], v[192:195], v[50:53]
	v_mfma_i32_16x16x64_i8 v[42:45], v[176:179], v[200:203], v[42:45]
	v_mfma_i32_16x16x64_i8 v[34:37], v[184:187], v[200:203], v[34:37]
	v_mfma_i32_16x16x64_i8 v[26:29], v[176:179], v[208:211], v[26:29]
	v_mfma_i32_16x16x64_i8 v[18:21], v[184:187], v[208:211], v[18:21]
	v_mfma_i32_16x16x64_i8 v[10:13], v[176:179], v[216:219], v[10:13]
	v_mfma_i32_16x16x64_i8 v[2:5], v[184:187], v[216:219], v[2:5]
	v_mfma_i32_16x16x64_i8 v[58:61], v[180:183], v[196:199], v[58:61]
	v_mfma_i32_16x16x64_i8 v[50:53], v[188:191], v[196:199], v[50:53]
	v_mfma_i32_16x16x64_i8 v[42:45], v[180:183], v[204:207], v[42:45]
	v_mfma_i32_16x16x64_i8 v[34:37], v[188:191], v[204:207], v[34:37]
	v_mfma_i32_16x16x64_i8 v[26:29], v[180:183], v[212:215], v[26:29]
	v_mfma_i32_16x16x64_i8 v[18:21], v[188:191], v[212:215], v[18:21]
	v_mfma_i32_16x16x64_i8 v[10:13], v[180:183], v[220:223], v[10:13]
	v_mfma_i32_16x16x64_i8 v[2:5], v[188:191], v[220:223], v[2:5]
	s_setprio 0
	s_barrier
	s_add_i32 s6, s6, 2
	s_add_u32 vcc_lo, vcc_lo, 0x100
	s_addc_u32 vcc_hi, vcc_hi, 0
	s_add_u32 s54, s54, 0x100
	s_addc_u32 s55, s55, 0
	s_add_u32 s88, s88, 0x100
	s_addc_u32 s89, s89, 0
	s_cmp_gt_u32 s6, 29
	s_cbranch_scc0 .LBB0_539
	s_and_b64 vcc, exec, s[66:67]
	s_cbranch_vccz .LBB0_542
	s_barrier

; #define PG8_STAGE(bufoff, gbase, voff) do { if constexpr (VAR != 1 && VAR != 3) { _Pragma("unroll") for (int _i = 0; _i < 2; ++_i) \
;         asm volatile("s_mov_b32 m0, %2\n\ts_nop 0\n\tglobal_load_lds_dwordx4 %0, %1" :: "v"((voff)[_i]), "s"((const char*)(gbase)), "s"(ldsbase + (unsigned)((bufoff) + _i * 8192)) : "memory", "m0"); } } while (0)
; #define PG8_LDA(dst, b, h) do { if constexpr (VAR < 2) _Pragma("unroll") for (int m = 0; m < 4; ++m) _Pragma("unroll") for (int k = 0; k < 2; ++k) dst[m][k] = *(const LAS bf16x8*)(lds + PG8_SA(b, h) + aoff + m * 2048 + k * 1024); } while (0)
; #define PG8_LDB(dst, b, h) do { if constexpr (VAR < 2) _Pragma("unroll") for (int n = 0; n < 2; ++n) _Pragma("unroll") for (int k = 0; k < 2; ++k) dst[n][k] = *(const LAS bf16x8*)(lds + PG8_SB(b, h) + boff + n * 2048 + k * 1024); } while (0)
; #define PG8_WAIT_V(n) asm volatile("s_waitcnt vmcnt(" #n ")" ::: "memory")
; #define PG8_WAIT_L(n) asm volatile("s_waitcnt lgkmcnt(" #n ")" ::: "memory")
; #define PG8_BAR do { if constexpr (VAR != 3) __builtin_amdgcn_s_barrier(); } while (0)
; #define PG8_SCHED __builtin_amdgcn_sched_barrier(0)
;     ...
;         for (int t = 0; t < nt; t += 2) {
;             const bool last = (t == nt - 2);
;             const char* a1 = cA + (size_t)(t + 1) * kstep;
;             const char* a2 = last ? nA : cA + (size_t)(t + 2) * kstep; const char* b2 = last ? nB : cB + (size_t)(t + 2) * kstep;
;             const char* a3 = a2 + kstep; const char* b3 = b2 + kstep;
;             PG8_LDB(B0, 0, 0); PG8_LDB(B1, 0, 1); PG8_SCHED; PG8_LDA(At, 0, 0); PG8_STAGE(PG8_SA(1, 1), a1 + hstepA, voffA);
;             PG8_WAIT_V(8); PG8_WAIT_L(0); PG8_BAR; PG8_MMA(0, 0, At, B0); PG8_MMA(0, 1, At, B1); PG8_BAR; PG8_SCHED;
;             PG8_LDA(At, 0, 1); PG8_STAGE(PG8_SB(0, 0), b2, voffB); PG8_STAGE(PG8_SB(0, 1), b2 + hstepB, voffB); PG8_STAGE(PG8_SA(0, 0), a2, voffA);
;             PG8_WAIT_V(8); PG8_WAIT_L(0); PG8_BAR; PG8_MMA(1, 0, At, B0); PG8_MMA(1, 1, At, B1); PG8_BAR; PG8_SCHED;
.LBB0_561:
	ds_read_b128 v[136:139], v152
	ds_read_b128 v[140:143], v152 offset:1024
	ds_read_b128 v[158:161], v152 offset:2048
	ds_read_b128 v[162:165], v152 offset:3072
	ds_read_b128 v[166:169], v153
	ds_read_b128 v[170:173], v153 offset:1024
	ds_read_b128 v[174:177], v153 offset:2048
	ds_read_b128 v[178:181], v153 offset:3072
	s_cmp_eq_u32 s6, 60
	s_cselect_b32 s84, s14, s65
	s_cselect_b32 s85, s1, s92
	s_cselect_b32 s74, s61, s93
	s_cselect_b32 s75, s15, s94
	s_add_u32 s72, s84, 0x80
	s_addc_u32 s73, s85, 0
	ds_read_b128 v[182:185], v154
	ds_read_b128 v[186:189], v154 offset:1024
	ds_read_b128 v[190:193], v154 offset:2048
	ds_read_b128 v[194:197], v154 offset:3072
	ds_read_b128 v[198:201], v154 offset:4096
	ds_read_b128 v[202:205], v154 offset:5120
	ds_read_b128 v[206:209], v154 offset:6144
	ds_read_b128 v[210:213], v154 offset:7168
	s_mov_b32 m0, s86
	s_nop 0
	global_load_lds_dwordx4 v1, s[70:71]
	s_mov_b32 m0, s87
	s_nop 0
	global_load_lds_dwordx4 v147, s[70:71]
	s_waitcnt vmcnt(8)
	s_waitcnt lgkmcnt(0)
	s_barrier
	s_setprio 1
	v_mfma_f32_16x16x32_bf16 v[126:129], v[136:139], v[182:185], v[126:129]
	v_mfma_f32_16x16x32_bf16 v[118:121], v[158:161], v[182:185], v[118:121]
	v_mfma_f32_16x16x32_bf16 v[110:113], v[136:139], v[190:193], v[110:113]
	v_mfma_f32_16x16x32_bf16 v[102:105], v[158:161], v[190:193], v[102:105]
	v_mfma_f32_16x16x32_bf16 v[94:97], v[136:139], v[198:201], v[94:97]
	v_mfma_f32_16x16x32_bf16 v[86:89], v[158:161], v[198:201], v[86:89]
	v_mfma_f32_16x16x32_bf16 v[78:81], v[136:139], v[206:209], v[78:81]
	v_mfma_f32_16x16x32_bf16 v[70:73], v[158:161], v[206:209], v[70:73]
	v_mfma_f32_16x16x32_bf16 v[126:129], v[140:143], v[186:189], v[126:129]
	v_mfma_f32_16x16x32_bf16 v[118:121], v[162:165], v[186:189], v[118:121]
	v_mfma_f32_16x16x32_bf16 v[110:113], v[140:143], v[194:197], v[110:113]
	v_mfma_f32_16x16x32_bf16 v[102:105], v[162:165], v[194:197], v[102:105]
	v_mfma_f32_16x16x32_bf16 v[94:97], v[140:143], v[202:205], v[94:97]
	v_mfma_f32_16x16x32_bf16 v[86:89], v[162:165], v[202:205], v[86:89]
	v_mfma_f32_16x16x32_bf16 v[78:81], v[140:143], v[210:213], v[78:81]
	v_mfma_f32_16x16x32_bf16 v[70:73], v[162:165], v[210:213], v[70:73]
	s_setprio 0
	s_setprio 1
	v_mfma_f32_16x16x32_bf16 v[122:125], v[166:169], v[182:185], v[122:125]
	v_mfma_f32_16x16x32_bf16 v[114:117], v[174:177], v[182:185], v[114:117]
	v_mfma_f32_16x16x32_bf16 v[106:109], v[166:169], v[190:193], v[106:109]
	v_mfma_f32_16x16x32_bf16 v[98:101], v[174:177], v[190:193], v[98:101]
	v_mfma_f32_16x16x32_bf16 v[90:93], v[166:169], v[198:201], v[90:93]
	v_mfma_f32_16x16x32_bf16 v[82:85], v[174:177], v[198:201], v[82:85]
	v_mfma_f32_16x16x32_bf16 v[74:77], v[166:169], v[206:209], v[74:77]
	v_mfma_f32_16x16x32_bf16 v[66:69], v[174:177], v[206:209], v[66:69]
	v_mfma_f32_16x16x32_bf16 v[122:125], v[170:173], v[186:189], v[122:125]
	v_mfma_f32_16x16x32_bf16 v[114:117], v[178:181], v[186:189], v[114:117]
	v_mfma_f32_16x16x32_bf16 v[106:109], v[170:173], v[194:197], v[106:109]
	v_mfma_f32_16x16x32_bf16 v[98:101], v[178:181], v[194:197], v[98:101]
	v_mfma_f32_16x16x32_bf16 v[90:93], v[170:173], v[202:205], v[90:93]
	v_mfma_f32_16x16x32_bf16 v[82:85], v[178:181], v[202:205], v[82:85]
	v_mfma_f32_16x16x32_bf16 v[74:77], v[170:173], v[210:213], v[74:77]
	v_mfma_f32_16x16x32_bf16 v[66:69], v[178:181], v[210:213], v[66:69]
	s_setprio 0
	s_barrier
	ds_read_b128 v[182:185], v154 offset:16384
	ds_read_b128 v[186:189], v154 offset:17408
	ds_read_b128 v[190:193], v154 offset:18432
	ds_read_b128 v[194:197], v154 offset:19456
	ds_read_b128 v[198:201], v154 offset:20480
	ds_read_b128 v[202:205], v154 offset:21504
	ds_read_b128 v[206:209], v154 offset:22528
	ds_read_b128 v[210:213], v154 offset:23552
	s_mov_b32 m0, s21
	s_nop 0
	global_load_lds_dwordx4 v146, s[74:75]
	s_add_u32 s10, s74, 0x100000
	s_mov_b32 m0, s23
	s_nop 0
	global_load_lds_dwordx4 v148, s[74:75]
	s_addc_u32 s11, s75, 0
	s_mov_b32 m0, s29
	s_nop 0
	global_load_lds_dwordx4 v146, s[10:11]
	s_mov_b32 m0, s30
	s_nop 0
	global_load_lds_dwordx4 v148, s[10:11]
	s_mov_b32 m0, s25
	s_nop 0
	global_load_lds_dwordx4 v1, s[84:85]
	s_mov_b32 m0, s31
	s_nop 0
	global_load_lds_dwordx4 v147, s[84:85]
	s_waitcnt vmcnt(8)
	s_waitcnt lgkmcnt(0)
	s_barrier
	s_setprio 1
	v_mfma_f32_16x16x32_bf16 v[62:65], v[136:139], v[182:185], v[62:65]
	v_mfma_f32_16x16x32_bf16 v[54:57], v[158:161], v[182:185], v[54:57]
	v_mfma_f32_16x16x32_bf16 v[46:49], v[136:139], v[190:193], v[46:49]
	v_mfma_f32_16x16x32_bf16 v[38:41], v[158:161], v[190:193], v[38:41]
	v_mfma_f32_16x16x32_bf16 v[30:33], v[136:139], v[198:201], v[30:33]
	v_mfma_f32_16x16x32_bf16 v[22:25], v[158:161], v[198:201], v[22:25]
	v_mfma_f32_16x16x32_bf16 v[14:17], v[136:139], v[206:209], v[14:17]
	v_mfma_f32_16x16x32_bf16 v[6:9], v[158:161], v[206:209], v[6:9]
	v_mfma_f32_16x16x32_bf16 v[62:65], v[140:143], v[186:189], v[62:65]
	v_mfma_f32_16x16x32_bf16 v[54:57], v[162:165], v[186:189], v[54:57]
	v_mfma_f32_16x16x32_bf16 v[46:49], v[140:143], v[194:197], v[46:49]
	v_mfma_f32_16x16x32_bf16 v[38:41], v[162:165], v[194:197], v[38:41]
	v_mfma_f32_16x16x32_bf16 v[30:33], v[140:143], v[202:205], v[30:33]
	v_mfma_f32_16x16x32_bf16 v[22:25], v[162:165], v[202:205], v[22:25]
	v_mfma_f32_16x16x32_bf16 v[14:17], v[140:143], v[210:213], v[14:17]
	v_mfma_f32_16x16x32_bf16 v[6:9], v[162:165], v[210:213], v[6:9]
	s_setprio 0
	s_setprio 1
	v_mfma_f32_16x16x32_bf16 v[58:61], v[166:169], v[182:185], v[58:61]
	v_mfma_f32_16x16x32_bf16 v[50:53], v[174:177], v[182:185], v[50:53]
	v_mfma_f32_16x16x32_bf16 v[42:45], v[166:169], v[190:193], v[42:45]
	v_mfma_f32_16x16x32_bf16 v[34:37], v[174:177], v[190:193], v[34:37]
	v_mfma_f32_16x16x32_bf16 v[26:29], v[166:169], v[198:201], v[26:29]
	v_mfma_f32_16x16x32_bf16 v[18:21], v[174:177], v[198:201], v[18:21]
	v_mfma_f32_16x16x32_bf16 v[10:13], v[166:169], v[206:209], v[10:13]
	v_mfma_f32_16x16x32_bf16 v[2:5], v[174:177], v[206:209], v[2:5]
	v_mfma_f32_16x16x32_bf16 v[58:61], v[170:173], v[186:189], v[58:61]
	v_mfma_f32_16x16x32_bf16 v[50:53], v[178:181], v[186:189], v[50:53]
	v_mfma_f32_16x16x32_bf16 v[42:45], v[170:173], v[194:197], v[42:45]
	v_mfma_f32_16x16x32_bf16 v[34:37], v[178:181], v[194:197], v[34:37]
	v_mfma_f32_16x16x32_bf16 v[26:29], v[170:173], v[202:205], v[26:29]
	v_mfma_f32_16x16x32_bf16 v[18:21], v[178:181], v[202:205], v[18:21]
	v_mfma_f32_16x16x32_bf16 v[10:13], v[170:173], v[210:213], v[10:13]
	v_mfma_f32_16x16x32_bf16 v[2:5], v[178:181], v[210:213], v[2:5]
	s_setprio 0
	s_barrier
; #define PG8_STAGE(bufoff, gbase, voff) do { if constexpr (VAR != 1 && VAR != 3) { _Pragma("unroll") for (int _i = 0; _i < 2; ++_i) \
;         asm volatile("s_mov_b32 m0, %2\n\ts_nop 0\n\tglobal_load_lds_dwordx4 %0, %1" :: "v"((voff)[_i]), "s"((const char*)(gbase)), "s"(ldsbase + (unsigned)((bufoff) + _i * 8192)) : "memory", "m0"); } } while (0)
; #define PG8_LDA(dst, b, h) do { if constexpr (VAR < 2) _Pragma("unroll") for (int m = 0; m < 4; ++m) _Pragma("unroll") for (int k = 0; k < 2; ++k) dst[m][k] = *(const LAS bf16x8*)(lds + PG8_SA(b, h) + aoff + m * 2048 + k * 1024); } while (0)
; #define PG8_LDB(dst, b, h) do { if constexpr (VAR < 2) _Pragma("unroll") for (int n = 0; n < 2; ++n) _Pragma("unroll") for (int k = 0; k < 2; ++k) dst[n][k] = *(const LAS bf16x8*)(lds + PG8_SB(b, h) + boff + n * 2048 + k * 1024); } while (0)
; #define PG8_WAIT_V(n) asm volatile("s_waitcnt vmcnt(" #n ")" ::: "memory")
; #define PG8_WAIT_L(n) asm volatile("s_waitcnt lgkmcnt(" #n ")" ::: "memory")
; #define PG8_BAR do { if constexpr (VAR != 3) __builtin_amdgcn_s_barrier(); } while (0)
; #define PG8_SCHED __builtin_amdgcn_sched_barrier(0)
;     ...
;             PG8_LDB(B0, 1, 0); PG8_LDB(B1, 1, 1); PG8_SCHED; PG8_LDA(At, 1, 0); PG8_STAGE(PG8_SA(0, 1), a2 + hstepA, voffA);
;             PG8_WAIT_V(8); PG8_WAIT_L(0); PG8_BAR; PG8_MMA(0, 0, At, B0); PG8_MMA(0, 1, At, B1); PG8_BAR; PG8_SCHED;
;             PG8_LDA(At, 1, 1); PG8_STAGE(PG8_SB(1, 0), b3, voffB); PG8_STAGE(PG8_SB(1, 1), b3 + hstepB, voffB); PG8_STAGE(PG8_SA(1, 0), a3, voffA);
;             PG8_WAIT_V(8); PG8_WAIT_L(0); PG8_BAR; PG8_MMA(1, 0, At, B0); PG8_MMA(1, 1, At, B1); PG8_BAR; PG8_SCHED;
;         }
;         if (wr == 0) PG8_BAR;
	ds_read_b128 v[136:139], v155
	ds_read_b128 v[140:143], v155 offset:1024
	ds_read_b128 v[158:161], v155 offset:2048
	ds_read_b128 v[162:165], v155 offset:3072
	ds_read_b128 v[166:169], v156
	ds_read_b128 v[170:173], v156 offset:1024
	ds_read_b128 v[174:177], v156 offset:2048
	ds_read_b128 v[178:181], v156 offset:3072
	ds_read_b128 v[182:185], v154 offset:32768
	ds_read_b128 v[186:189], v154 offset:33792
	ds_read_b128 v[190:193], v154 offset:34816
	ds_read_b128 v[194:197], v154 offset:35840
	ds_read_b128 v[198:201], v154 offset:36864
	ds_read_b128 v[202:205], v154 offset:37888
	ds_read_b128 v[206:209], v154 offset:38912
	ds_read_b128 v[210:213], v154 offset:39936
	s_add_u32 s10, s84, 0x100000
	s_addc_u32 s11, s85, 0
	s_mov_b32 m0, s33
	s_nop 0
	global_load_lds_dwordx4 v1, s[10:11]
	s_mov_b32 m0, s35
	s_nop 0
	global_load_lds_dwordx4 v147, s[10:11]
	s_waitcnt vmcnt(8)
	s_waitcnt lgkmcnt(0)
	s_barrier
	s_setprio 1
	v_mfma_f32_16x16x32_bf16 v[126:129], v[136:139], v[182:185], v[126:129]
	v_mfma_f32_16x16x32_bf16 v[118:121], v[158:161], v[182:185], v[118:121]
	v_mfma_f32_16x16x32_bf16 v[110:113], v[136:139], v[190:193], v[110:113]
	v_mfma_f32_16x16x32_bf16 v[102:105], v[158:161], v[190:193], v[102:105]
	v_mfma_f32_16x16x32_bf16 v[94:97], v[136:139], v[198:201], v[94:97]
	v_mfma_f32_16x16x32_bf16 v[86:89], v[158:161], v[198:201], v[86:89]
	v_mfma_f32_16x16x32_bf16 v[78:81], v[136:139], v[206:209], v[78:81]
	v_mfma_f32_16x16x32_bf16 v[70:73], v[158:161], v[206:209], v[70:73]
	v_mfma_f32_16x16x32_bf16 v[126:129], v[140:143], v[186:189], v[126:129]
	v_mfma_f32_16x16x32_bf16 v[118:121], v[162:165], v[186:189], v[118:121]
	v_mfma_f32_16x16x32_bf16 v[110:113], v[140:143], v[194:197], v[110:113]
	v_mfma_f32_16x16x32_bf16 v[102:105], v[162:165], v[194:197], v[102:105]
	v_mfma_f32_16x16x32_bf16 v[94:97], v[140:143], v[202:205], v[94:97]
	v_mfma_f32_16x16x32_bf16 v[86:89], v[162:165], v[202:205], v[86:89]
	v_mfma_f32_16x16x32_bf16 v[78:81], v[140:143], v[210:213], v[78:81]
	v_mfma_f32_16x16x32_bf16 v[70:73], v[162:165], v[210:213], v[70:73]
	s_setprio 0
	s_setprio 1
	v_mfma_f32_16x16x32_bf16 v[122:125], v[166:169], v[182:185], v[122:125]
	v_mfma_f32_16x16x32_bf16 v[114:117], v[174:177], v[182:185], v[114:117]
	v_mfma_f32_16x16x32_bf16 v[106:109], v[166:169], v[190:193], v[106:109]
	v_mfma_f32_16x16x32_bf16 v[98:101], v[174:177], v[190:193], v[98:101]
	v_mfma_f32_16x16x32_bf16 v[90:93], v[166:169], v[198:201], v[90:93]
	v_mfma_f32_16x16x32_bf16 v[82:85], v[174:177], v[198:201], v[82:85]
	v_mfma_f32_16x16x32_bf16 v[74:77], v[166:169], v[206:209], v[74:77]
	v_mfma_f32_16x16x32_bf16 v[66:69], v[174:177], v[206:209], v[66:69]
	v_mfma_f32_16x16x32_bf16 v[122:125], v[170:173], v[186:189], v[122:125]
	v_mfma_f32_16x16x32_bf16 v[114:117], v[178:181], v[186:189], v[114:117]
	v_mfma_f32_16x16x32_bf16 v[106:109], v[170:173], v[194:197], v[106:109]
	v_mfma_f32_16x16x32_bf16 v[98:101], v[178:181], v[194:197], v[98:101]
	v_mfma_f32_16x16x32_bf16 v[90:93], v[170:173], v[202:205], v[90:93]
	v_mfma_f32_16x16x32_bf16 v[82:85], v[178:181], v[202:205], v[82:85]
	v_mfma_f32_16x16x32_bf16 v[74:77], v[170:173], v[210:213], v[74:77]
	v_mfma_f32_16x16x32_bf16 v[66:69], v[178:181], v[210:213], v[66:69]
	s_setprio 0
	s_barrier
	ds_read_b128 v[182:185], v154 offset:49152
	ds_read_b128 v[186:189], v154 offset:50176
	ds_read_b128 v[190:193], v154 offset:51200
	ds_read_b128 v[194:197], v154 offset:52224
	ds_read_b128 v[198:201], v154 offset:53248
	ds_read_b128 v[202:205], v154 offset:54272
	ds_read_b128 v[206:209], v154 offset:55296
	ds_read_b128 v[210:213], v154 offset:56320
	s_add_u32 s10, s74, 0x80
	s_addc_u32 s11, s75, 0
	s_mov_b32 m0, s52
	s_nop 0
	global_load_lds_dwordx4 v146, s[10:11]
	s_mov_b32 m0, s53
	s_nop 0
	global_load_lds_dwordx4 v148, s[10:11]
	s_add_u32 s10, s74, 0x100080
	s_addc_u32 s11, s75, 0
	s_mov_b32 m0, s62
	s_nop 0
	global_load_lds_dwordx4 v146, s[10:11]
	s_mov_b32 m0, s63
	s_nop 0
	global_load_lds_dwordx4 v148, s[10:11]
	s_mov_b32 m0, s56
	s_nop 0
	global_load_lds_dwordx4 v1, s[72:73]
	s_mov_b32 m0, s57
	s_nop 0
	global_load_lds_dwordx4 v147, s[72:73]
	s_waitcnt vmcnt(8)
	s_waitcnt lgkmcnt(0)
	s_barrier
	s_setprio 1
	v_mfma_f32_16x16x32_bf16 v[62:65], v[136:139], v[182:185], v[62:65]
	v_mfma_f32_16x16x32_bf16 v[54:57], v[158:161], v[182:185], v[54:57]
	v_mfma_f32_16x16x32_bf16 v[46:49], v[136:139], v[190:193], v[46:49]
	v_mfma_f32_16x16x32_bf16 v[38:41], v[158:161], v[190:193], v[38:41]
	v_mfma_f32_16x16x32_bf16 v[30:33], v[136:139], v[198:201], v[30:33]
	v_mfma_f32_16x16x32_bf16 v[22:25], v[158:161], v[198:201], v[22:25]
	v_mfma_f32_16x16x32_bf16 v[14:17], v[136:139], v[206:209], v[14:17]
	v_mfma_f32_16x16x32_bf16 v[6:9], v[158:161], v[206:209], v[6:9]
	v_mfma_f32_16x16x32_bf16 v[62:65], v[140:143], v[186:189], v[62:65]
	v_mfma_f32_16x16x32_bf16 v[54:57], v[162:165], v[186:189], v[54:57]
	v_mfma_f32_16x16x32_bf16 v[46:49], v[140:143], v[194:197], v[46:49]
	v_mfma_f32_16x16x32_bf16 v[38:41], v[162:165], v[194:197], v[38:41]
	v_mfma_f32_16x16x32_bf16 v[30:33], v[140:143], v[202:205], v[30:33]
	v_mfma_f32_16x16x32_bf16 v[22:25], v[162:165], v[202:205], v[22:25]
	v_mfma_f32_16x16x32_bf16 v[14:17], v[140:143], v[210:213], v[14:17]
	v_mfma_f32_16x16x32_bf16 v[6:9], v[162:165], v[210:213], v[6:9]
	s_setprio 0
	s_setprio 1
	v_mfma_f32_16x16x32_bf16 v[58:61], v[166:169], v[182:185], v[58:61]
	v_mfma_f32_16x16x32_bf16 v[50:53], v[174:177], v[182:185], v[50:53]
	v_mfma_f32_16x16x32_bf16 v[42:45], v[166:169], v[190:193], v[42:45]
	v_mfma_f32_16x16x32_bf16 v[34:37], v[174:177], v[190:193], v[34:37]
	v_mfma_f32_16x16x32_bf16 v[26:29], v[166:169], v[198:201], v[26:29]
	v_mfma_f32_16x16x32_bf16 v[18:21], v[174:177], v[198:201], v[18:21]
	v_mfma_f32_16x16x32_bf16 v[10:13], v[166:169], v[206:209], v[10:13]
	v_mfma_f32_16x16x32_bf16 v[2:5], v[174:177], v[206:209], v[2:5]
	v_mfma_f32_16x16x32_bf16 v[58:61], v[170:173], v[186:189], v[58:61]
	v_mfma_f32_16x16x32_bf16 v[50:53], v[178:181], v[186:189], v[50:53]
	v_mfma_f32_16x16x32_bf16 v[42:45], v[170:173], v[194:197], v[42:45]
	v_mfma_f32_16x16x32_bf16 v[34:37], v[178:181], v[194:197], v[34:37]
	v_mfma_f32_16x16x32_bf16 v[26:29], v[170:173], v[202:205], v[26:29]
	v_mfma_f32_16x16x32_bf16 v[18:21], v[178:181], v[202:205], v[18:21]
	v_mfma_f32_16x16x32_bf16 v[10:13], v[170:173], v[210:213], v[10:13]
	v_mfma_f32_16x16x32_bf16 v[2:5], v[178:181], v[210:213], v[2:5]
	s_setprio 0
	s_barrier
	s_add_i32 s6, s6, 2
	s_add_u32 s65, s65, 0x100
	s_addc_u32 s92, s92, 0
	s_add_u32 s93, s93, 0x100
	s_addc_u32 s94, s94, 0
	s_add_u32 s70, s70, 0x100
	s_addc_u32 s71, s71, 0
	s_cmp_gt_u32 s6, 61
	s_cbranch_scc0 .LBB0_561
	s_and_b64 vcc, exec, s[54:55]
	s_cbranch_vccz .LBB0_564
	s_barrier

; #define PG8_STAGE(bufoff, gbase, voff) do { if constexpr (VAR != 1 && VAR != 3) { _Pragma("unroll") for (int _i = 0; _i < 2; ++_i) \
;         asm volatile("s_mov_b32 m0, %2\n\ts_nop 0\n\tglobal_load_lds_dwordx4 %0, %1" :: "v"((voff)[_i]), "s"((const char*)(gbase)), "s"(ldsbase + (unsigned)((bufoff) + _i * 8192)) : "memory", "m0"); } } while (0)
; #define PG8_LDA(dst, b, h) do { if constexpr (VAR < 2) _Pragma("unroll") for (int m = 0; m < 4; ++m) _Pragma("unroll") for (int k = 0; k < 2; ++k) dst[m][k] = *(const LAS bf16x8*)(lds + PG8_SA(b, h) + aoff + m * 2048 + k * 1024); } while (0)
; #define PG8_LDB(dst, b, h) do { if constexpr (VAR < 2) _Pragma("unroll") for (int n = 0; n < 2; ++n) _Pragma("unroll") for (int k = 0; k < 2; ++k) dst[n][k] = *(const LAS bf16x8*)(lds + PG8_SB(b, h) + boff + n * 2048 + k * 1024); } while (0)
; #define PG8_WAIT_V(n) asm volatile("s_waitcnt vmcnt(" #n ")" ::: "memory")
; #define PG8_WAIT_L(n) asm volatile("s_waitcnt lgkmcnt(" #n ")" ::: "memory")
; #define PG8_BAR do { if constexpr (VAR != 3) __builtin_amdgcn_s_barrier(); } while (0)
; #define PG8_SCHED __builtin_amdgcn_sched_barrier(0)
;     ...
;         for (int t = 0; t < nt; t += 2) {
;             const bool last = (t == nt - 2);
;             const char* a1 = cA + (size_t)(t + 1) * kstep;
;             const char* a2 = last ? nA : cA + (size_t)(t + 2) * kstep; const char* b2 = last ? nB : cB + (size_t)(t + 2) * kstep;
;             const char* a3 = a2 + kstep; const char* b3 = b2 + kstep;
;             PG8_LDB(B0, 0, 0); PG8_LDB(B1, 0, 1); PG8_SCHED; PG8_LDA(At, 0, 0); PG8_STAGE(PG8_SA(1, 1), a1 + hstepA, voffA);
;             PG8_WAIT_V(8); PG8_WAIT_L(0); PG8_BAR; PG8_MMA(0, 0, At, B0); PG8_MMA(0, 1, At, B1); PG8_BAR; PG8_SCHED;
;             PG8_LDA(At, 0, 1); PG8_STAGE(PG8_SB(0, 0), b2, voffB); PG8_STAGE(PG8_SB(0, 1), b2 + hstepB, voffB); PG8_STAGE(PG8_SA(0, 0), a2, voffA);
;             PG8_WAIT_V(8); PG8_WAIT_L(0); PG8_BAR; PG8_MMA(1, 0, At, B0); PG8_MMA(1, 1, At, B1); PG8_BAR; PG8_SCHED;
.LBB0_673:
	ds_read_b128 v[150:153], v183
	ds_read_b128 v[154:157], v183 offset:1024
	ds_read_b128 v[158:161], v183 offset:2048
	ds_read_b128 v[162:165], v183 offset:3072
	ds_read_b128 v[166:169], v184
	ds_read_b128 v[188:191], v184 offset:1024
	ds_read_b128 v[192:195], v184 offset:2048
	ds_read_b128 v[196:199], v184 offset:3072
	s_cmp_eq_u32 s6, 12
	s_cselect_b32 s82, s0, s75
	s_cselect_b32 s83, s1, s92
	s_cselect_b32 s80, s76, s93
	s_cselect_b32 s81, s77, s94
	s_add_u32 s78, s82, 0x80
	s_addc_u32 s79, s83, 0
	ds_read_b128 v[200:203], v185
	ds_read_b128 v[204:207], v185 offset:1024
	ds_read_b128 v[208:211], v185 offset:2048
	ds_read_b128 v[212:215], v185 offset:3072
	ds_read_b128 v[216:219], v185 offset:4096
	ds_read_b128 v[220:223], v185 offset:5120
	ds_read_b128 v[224:227], v185 offset:6144
	ds_read_b128 v[228:231], v185 offset:7168
	s_mov_b32 m0, s85
	s_nop 0
	global_load_lds_dwordx4 v178, s[4:5]
	s_mov_b32 m0, s86
	s_nop 0
	global_load_lds_dwordx4 v180, s[4:5]
	s_waitcnt vmcnt(8)
	s_waitcnt lgkmcnt(0)
	s_barrier
	s_setprio 1
	v_mfma_f32_16x16x32_bf16 v[126:129], v[150:153], v[200:203], v[126:129]
	v_mfma_f32_16x16x32_bf16 v[122:125], v[158:161], v[200:203], v[122:125]
	v_mfma_f32_16x16x32_bf16 v[114:117], v[150:153], v[208:211], v[114:117]
	v_mfma_f32_16x16x32_bf16 v[106:109], v[158:161], v[208:211], v[106:109]
	v_mfma_f32_16x16x32_bf16 v[98:101], v[150:153], v[216:219], v[98:101]
	v_mfma_f32_16x16x32_bf16 v[90:93], v[158:161], v[216:219], v[90:93]
	v_mfma_f32_16x16x32_bf16 v[82:85], v[150:153], v[224:227], v[82:85]
	v_mfma_f32_16x16x32_bf16 v[74:77], v[158:161], v[224:227], v[74:77]
	v_mfma_f32_16x16x32_bf16 v[126:129], v[154:157], v[204:207], v[126:129]
	v_mfma_f32_16x16x32_bf16 v[122:125], v[162:165], v[204:207], v[122:125]
	v_mfma_f32_16x16x32_bf16 v[114:117], v[154:157], v[212:215], v[114:117]
	v_mfma_f32_16x16x32_bf16 v[106:109], v[162:165], v[212:215], v[106:109]
	v_mfma_f32_16x16x32_bf16 v[98:101], v[154:157], v[220:223], v[98:101]
	v_mfma_f32_16x16x32_bf16 v[90:93], v[162:165], v[220:223], v[90:93]
	v_mfma_f32_16x16x32_bf16 v[82:85], v[154:157], v[228:231], v[82:85]
	v_mfma_f32_16x16x32_bf16 v[74:77], v[162:165], v[228:231], v[74:77]
	s_setprio 0
	s_setprio 1
	v_mfma_f32_16x16x32_bf16 v[118:121], v[166:169], v[200:203], v[118:121]
	v_mfma_f32_16x16x32_bf16 v[110:113], v[192:195], v[200:203], v[110:113]
	v_mfma_f32_16x16x32_bf16 v[102:105], v[166:169], v[208:211], v[102:105]
	v_mfma_f32_16x16x32_bf16 v[94:97], v[192:195], v[208:211], v[94:97]
	v_mfma_f32_16x16x32_bf16 v[86:89], v[166:169], v[216:219], v[86:89]
	v_mfma_f32_16x16x32_bf16 v[78:81], v[192:195], v[216:219], v[78:81]
	v_mfma_f32_16x16x32_bf16 v[70:73], v[166:169], v[224:227], v[70:73]
	v_mfma_f32_16x16x32_bf16 v[66:69], v[192:195], v[224:227], v[66:69]
	v_mfma_f32_16x16x32_bf16 v[118:121], v[188:191], v[204:207], v[118:121]
	v_mfma_f32_16x16x32_bf16 v[110:113], v[196:199], v[204:207], v[110:113]
	v_mfma_f32_16x16x32_bf16 v[102:105], v[188:191], v[212:215], v[102:105]
	v_mfma_f32_16x16x32_bf16 v[94:97], v[196:199], v[212:215], v[94:97]
	v_mfma_f32_16x16x32_bf16 v[86:89], v[188:191], v[220:223], v[86:89]
	v_mfma_f32_16x16x32_bf16 v[78:81], v[196:199], v[220:223], v[78:81]
	v_mfma_f32_16x16x32_bf16 v[70:73], v[188:191], v[228:231], v[70:73]
	v_mfma_f32_16x16x32_bf16 v[66:69], v[196:199], v[228:231], v[66:69]
	s_setprio 0
	s_barrier
	ds_read_b128 v[200:203], v185 offset:16384
	ds_read_b128 v[204:207], v185 offset:17408
	ds_read_b128 v[208:211], v185 offset:18432
	ds_read_b128 v[212:215], v185 offset:19456
	ds_read_b128 v[216:219], v185 offset:20480
	ds_read_b128 v[220:223], v185 offset:21504
	ds_read_b128 v[224:227], v185 offset:22528
	ds_read_b128 v[228:231], v185 offset:23552
	s_mov_b32 m0, s24
	s_nop 0
	global_load_lds_dwordx4 v179, s[80:81]
	s_add_u32 s96, s80, 0x100000
	s_mov_b32 m0, s25
	s_nop 0
	global_load_lds_dwordx4 v181, s[80:81]
	s_addc_u32 s97, s81, 0
	s_mov_b32 m0, s26
	s_nop 0
	global_load_lds_dwordx4 v179, s[96:97]
	s_mov_b32 m0, s27
	s_nop 0
	global_load_lds_dwordx4 v181, s[96:97]
	s_mov_b32 m0, s15
	s_nop 0
	global_load_lds_dwordx4 v178, s[82:83]
	s_mov_b32 m0, s28
	s_nop 0
	global_load_lds_dwordx4 v180, s[82:83]
	s_waitcnt vmcnt(8)
	s_waitcnt lgkmcnt(0)
	s_barrier
	s_setprio 1
	v_mfma_f32_16x16x32_bf16 v[62:65], v[150:153], v[200:203], v[62:65]
	v_mfma_f32_16x16x32_bf16 v[58:61], v[158:161], v[200:203], v[58:61]
	v_mfma_f32_16x16x32_bf16 v[50:53], v[150:153], v[208:211], v[50:53]
	v_mfma_f32_16x16x32_bf16 v[42:45], v[158:161], v[208:211], v[42:45]
	v_mfma_f32_16x16x32_bf16 v[34:37], v[150:153], v[216:219], v[34:37]
	v_mfma_f32_16x16x32_bf16 v[26:29], v[158:161], v[216:219], v[26:29]
	v_mfma_f32_16x16x32_bf16 v[18:21], v[150:153], v[224:227], v[18:21]
	v_mfma_f32_16x16x32_bf16 v[10:13], v[158:161], v[224:227], v[10:13]
	v_mfma_f32_16x16x32_bf16 v[62:65], v[154:157], v[204:207], v[62:65]
	v_mfma_f32_16x16x32_bf16 v[58:61], v[162:165], v[204:207], v[58:61]
	v_mfma_f32_16x16x32_bf16 v[50:53], v[154:157], v[212:215], v[50:53]
	v_mfma_f32_16x16x32_bf16 v[42:45], v[162:165], v[212:215], v[42:45]
	v_mfma_f32_16x16x32_bf16 v[34:37], v[154:157], v[220:223], v[34:37]
	v_mfma_f32_16x16x32_bf16 v[26:29], v[162:165], v[220:223], v[26:29]
	v_mfma_f32_16x16x32_bf16 v[18:21], v[154:157], v[228:231], v[18:21]
	v_mfma_f32_16x16x32_bf16 v[10:13], v[162:165], v[228:231], v[10:13]
	s_setprio 0
	s_setprio 1
	v_mfma_f32_16x16x32_bf16 v[54:57], v[166:169], v[200:203], v[54:57]
	v_mfma_f32_16x16x32_bf16 v[46:49], v[192:195], v[200:203], v[46:49]
	v_mfma_f32_16x16x32_bf16 v[38:41], v[166:169], v[208:211], v[38:41]
	v_mfma_f32_16x16x32_bf16 v[30:33], v[192:195], v[208:211], v[30:33]
	v_mfma_f32_16x16x32_bf16 v[22:25], v[166:169], v[216:219], v[22:25]
	v_mfma_f32_16x16x32_bf16 v[14:17], v[192:195], v[216:219], v[14:17]
	v_mfma_f32_16x16x32_bf16 v[6:9], v[166:169], v[224:227], v[6:9]
	v_mfma_f32_16x16x32_bf16 v[2:5], v[192:195], v[224:227], v[2:5]
	v_mfma_f32_16x16x32_bf16 v[54:57], v[188:191], v[204:207], v[54:57]
	v_mfma_f32_16x16x32_bf16 v[46:49], v[196:199], v[204:207], v[46:49]
	v_mfma_f32_16x16x32_bf16 v[38:41], v[188:191], v[212:215], v[38:41]
	v_mfma_f32_16x16x32_bf16 v[30:33], v[196:199], v[212:215], v[30:33]
	v_mfma_f32_16x16x32_bf16 v[22:25], v[188:191], v[220:223], v[22:25]
	v_mfma_f32_16x16x32_bf16 v[14:17], v[196:199], v[220:223], v[14:17]
	v_mfma_f32_16x16x32_bf16 v[6:9], v[188:191], v[228:231], v[6:9]
	v_mfma_f32_16x16x32_bf16 v[2:5], v[196:199], v[228:231], v[2:5]
	s_setprio 0
	s_barrier
; #define PG8_STAGE(bufoff, gbase, voff) do { if constexpr (VAR != 1 && VAR != 3) { _Pragma("unroll") for (int _i = 0; _i < 2; ++_i) \
;         asm volatile("s_mov_b32 m0, %2\n\ts_nop 0\n\tglobal_load_lds_dwordx4 %0, %1" :: "v"((voff)[_i]), "s"((const char*)(gbase)), "s"(ldsbase + (unsigned)((bufoff) + _i * 8192)) : "memory", "m0"); } } while (0)
; #define PG8_LDA(dst, b, h) do { if constexpr (VAR < 2) _Pragma("unroll") for (int m = 0; m < 4; ++m) _Pragma("unroll") for (int k = 0; k < 2; ++k) dst[m][k] = *(const LAS bf16x8*)(lds + PG8_SA(b, h) + aoff + m * 2048 + k * 1024); } while (0)
; #define PG8_LDB(dst, b, h) do { if constexpr (VAR < 2) _Pragma("unroll") for (int n = 0; n < 2; ++n) _Pragma("unroll") for (int k = 0; k < 2; ++k) dst[n][k] = *(const LAS bf16x8*)(lds + PG8_SB(b, h) + boff + n * 2048 + k * 1024); } while (0)
; #define PG8_WAIT_V(n) asm volatile("s_waitcnt vmcnt(" #n ")" ::: "memory")
; #define PG8_WAIT_L(n) asm volatile("s_waitcnt lgkmcnt(" #n ")" ::: "memory")
; #define PG8_BAR do { if constexpr (VAR != 3) __builtin_amdgcn_s_barrier(); } while (0)
; #define PG8_SCHED __builtin_amdgcn_sched_barrier(0)
;     ...
;             PG8_LDB(B0, 1, 0); PG8_LDB(B1, 1, 1); PG8_SCHED; PG8_LDA(At, 1, 0); PG8_STAGE(PG8_SA(0, 1), a2 + hstepA, voffA);
;             PG8_WAIT_V(8); PG8_WAIT_L(0); PG8_BAR; PG8_MMA(0, 0, At, B0); PG8_MMA(0, 1, At, B1); PG8_BAR; PG8_SCHED;
;             PG8_LDA(At, 1, 1); PG8_STAGE(PG8_SB(1, 0), b3, voffB); PG8_STAGE(PG8_SB(1, 1), b3 + hstepB, voffB); PG8_STAGE(PG8_SA(1, 0), a3, voffA);
;             PG8_WAIT_V(8); PG8_WAIT_L(0); PG8_BAR; PG8_MMA(1, 0, At, B0); PG8_MMA(1, 1, At, B1); PG8_BAR; PG8_SCHED;
;         }
	ds_read_b128 v[150:153], v186
	ds_read_b128 v[154:157], v186 offset:1024
	ds_read_b128 v[158:161], v186 offset:2048
	ds_read_b128 v[162:165], v186 offset:3072
	ds_read_b128 v[166:169], v187
	ds_read_b128 v[188:191], v187 offset:1024
	ds_read_b128 v[192:195], v187 offset:2048
	ds_read_b128 v[196:199], v187 offset:3072
	ds_read_b128 v[200:203], v185 offset:32768
	ds_read_b128 v[204:207], v185 offset:33792
	ds_read_b128 v[208:211], v185 offset:34816
	ds_read_b128 v[212:215], v185 offset:35840
	ds_read_b128 v[216:219], v185 offset:36864
	ds_read_b128 v[220:223], v185 offset:37888
	ds_read_b128 v[224:227], v185 offset:38912
	ds_read_b128 v[228:231], v185 offset:39936
	s_add_u32 s82, s82, 0x200000
	s_addc_u32 s83, s83, 0
	s_mov_b32 m0, s29
	s_nop 0
	global_load_lds_dwordx4 v178, s[82:83]
	s_mov_b32 m0, s30
	s_nop 0
	global_load_lds_dwordx4 v180, s[82:83]
	s_waitcnt vmcnt(8)
	s_waitcnt lgkmcnt(0)
	s_barrier
	s_setprio 1
	v_mfma_f32_16x16x32_bf16 v[126:129], v[150:153], v[200:203], v[126:129]
	v_mfma_f32_16x16x32_bf16 v[122:125], v[158:161], v[200:203], v[122:125]
	v_mfma_f32_16x16x32_bf16 v[114:117], v[150:153], v[208:211], v[114:117]
	v_mfma_f32_16x16x32_bf16 v[106:109], v[158:161], v[208:211], v[106:109]
	v_mfma_f32_16x16x32_bf16 v[98:101], v[150:153], v[216:219], v[98:101]
	v_mfma_f32_16x16x32_bf16 v[90:93], v[158:161], v[216:219], v[90:93]
	v_mfma_f32_16x16x32_bf16 v[82:85], v[150:153], v[224:227], v[82:85]
	v_mfma_f32_16x16x32_bf16 v[74:77], v[158:161], v[224:227], v[74:77]
	v_mfma_f32_16x16x32_bf16 v[126:129], v[154:157], v[204:207], v[126:129]
	v_mfma_f32_16x16x32_bf16 v[122:125], v[162:165], v[204:207], v[122:125]
	v_mfma_f32_16x16x32_bf16 v[114:117], v[154:157], v[212:215], v[114:117]
	v_mfma_f32_16x16x32_bf16 v[106:109], v[162:165], v[212:215], v[106:109]
	v_mfma_f32_16x16x32_bf16 v[98:101], v[154:157], v[220:223], v[98:101]
	v_mfma_f32_16x16x32_bf16 v[90:93], v[162:165], v[220:223], v[90:93]
	v_mfma_f32_16x16x32_bf16 v[82:85], v[154:157], v[228:231], v[82:85]
	v_mfma_f32_16x16x32_bf16 v[74:77], v[162:165], v[228:231], v[74:77]
	s_setprio 0
	s_setprio 1
	v_mfma_f32_16x16x32_bf16 v[118:121], v[166:169], v[200:203], v[118:121]
	v_mfma_f32_16x16x32_bf16 v[110:113], v[192:195], v[200:203], v[110:113]
	v_mfma_f32_16x16x32_bf16 v[102:105], v[166:169], v[208:211], v[102:105]
	v_mfma_f32_16x16x32_bf16 v[94:97], v[192:195], v[208:211], v[94:97]
	v_mfma_f32_16x16x32_bf16 v[86:89], v[166:169], v[216:219], v[86:89]
	v_mfma_f32_16x16x32_bf16 v[78:81], v[192:195], v[216:219], v[78:81]
	v_mfma_f32_16x16x32_bf16 v[70:73], v[166:169], v[224:227], v[70:73]
	v_mfma_f32_16x16x32_bf16 v[66:69], v[192:195], v[224:227], v[66:69]
	v_mfma_f32_16x16x32_bf16 v[118:121], v[188:191], v[204:207], v[118:121]
	v_mfma_f32_16x16x32_bf16 v[110:113], v[196:199], v[204:207], v[110:113]
	v_mfma_f32_16x16x32_bf16 v[102:105], v[188:191], v[212:215], v[102:105]
	v_mfma_f32_16x16x32_bf16 v[94:97], v[196:199], v[212:215], v[94:97]
	v_mfma_f32_16x16x32_bf16 v[86:89], v[188:191], v[220:223], v[86:89]
	v_mfma_f32_16x16x32_bf16 v[78:81], v[196:199], v[220:223], v[78:81]
	v_mfma_f32_16x16x32_bf16 v[70:73], v[188:191], v[228:231], v[70:73]
	v_mfma_f32_16x16x32_bf16 v[66:69], v[196:199], v[228:231], v[66:69]
	s_setprio 0
	s_barrier
	ds_read_b128 v[200:203], v185 offset:49152
	ds_read_b128 v[204:207], v185 offset:50176
	ds_read_b128 v[208:211], v185 offset:51200
	ds_read_b128 v[212:215], v185 offset:52224
	ds_read_b128 v[216:219], v185 offset:53248
	ds_read_b128 v[220:223], v185 offset:54272
	ds_read_b128 v[224:227], v185 offset:55296
	ds_read_b128 v[228:231], v185 offset:56320
	s_add_u32 s82, s80, 0x80
	s_addc_u32 s83, s81, 0
	s_mov_b32 m0, s31
	s_nop 0
	global_load_lds_dwordx4 v179, s[82:83]
	s_add_u32 s80, s80, 0x100080
	s_mov_b32 m0, s33
	s_nop 0
	global_load_lds_dwordx4 v181, s[82:83]
	s_addc_u32 s81, s81, 0
	s_mov_b32 m0, s73
	s_nop 0
	global_load_lds_dwordx4 v179, s[80:81]
	s_mov_b32 m0, s84
	s_nop 0
	global_load_lds_dwordx4 v181, s[80:81]
	s_mov_b32 m0, s56
	s_nop 0
	global_load_lds_dwordx4 v178, s[78:79]
	s_mov_b32 m0, s57
	s_nop 0
	global_load_lds_dwordx4 v180, s[78:79]
	s_waitcnt vmcnt(8)
	s_waitcnt lgkmcnt(0)
	s_barrier
	s_setprio 1
	v_mfma_f32_16x16x32_bf16 v[62:65], v[150:153], v[200:203], v[62:65]
	v_mfma_f32_16x16x32_bf16 v[58:61], v[158:161], v[200:203], v[58:61]
	v_mfma_f32_16x16x32_bf16 v[50:53], v[150:153], v[208:211], v[50:53]
	v_mfma_f32_16x16x32_bf16 v[42:45], v[158:161], v[208:211], v[42:45]
	v_mfma_f32_16x16x32_bf16 v[34:37], v[150:153], v[216:219], v[34:37]
	v_mfma_f32_16x16x32_bf16 v[26:29], v[158:161], v[216:219], v[26:29]
	v_mfma_f32_16x16x32_bf16 v[18:21], v[150:153], v[224:227], v[18:21]
	v_mfma_f32_16x16x32_bf16 v[10:13], v[158:161], v[224:227], v[10:13]
	v_mfma_f32_16x16x32_bf16 v[62:65], v[154:157], v[204:207], v[62:65]
	v_mfma_f32_16x16x32_bf16 v[58:61], v[162:165], v[204:207], v[58:61]
	v_mfma_f32_16x16x32_bf16 v[50:53], v[154:157], v[212:215], v[50:53]
	v_mfma_f32_16x16x32_bf16 v[42:45], v[162:165], v[212:215], v[42:45]
	v_mfma_f32_16x16x32_bf16 v[34:37], v[154:157], v[220:223], v[34:37]
	v_mfma_f32_16x16x32_bf16 v[26:29], v[162:165], v[220:223], v[26:29]
	v_mfma_f32_16x16x32_bf16 v[18:21], v[154:157], v[228:231], v[18:21]
	v_mfma_f32_16x16x32_bf16 v[10:13], v[162:165], v[228:231], v[10:13]
	s_setprio 0
	s_setprio 1
	v_mfma_f32_16x16x32_bf16 v[54:57], v[166:169], v[200:203], v[54:57]
	v_mfma_f32_16x16x32_bf16 v[46:49], v[192:195], v[200:203], v[46:49]
	v_mfma_f32_16x16x32_bf16 v[38:41], v[166:169], v[208:211], v[38:41]
	v_mfma_f32_16x16x32_bf16 v[30:33], v[192:195], v[208:211], v[30:33]
	v_mfma_f32_16x16x32_bf16 v[22:25], v[166:169], v[216:219], v[22:25]
	v_mfma_f32_16x16x32_bf16 v[14:17], v[192:195], v[216:219], v[14:17]
	v_mfma_f32_16x16x32_bf16 v[6:9], v[166:169], v[224:227], v[6:9]
	v_mfma_f32_16x16x32_bf16 v[2:5], v[192:195], v[224:227], v[2:5]
	v_mfma_f32_16x16x32_bf16 v[54:57], v[188:191], v[204:207], v[54:57]
	v_mfma_f32_16x16x32_bf16 v[46:49], v[196:199], v[204:207], v[46:49]
	v_mfma_f32_16x16x32_bf16 v[38:41], v[188:191], v[212:215], v[38:41]
	v_mfma_f32_16x16x32_bf16 v[30:33], v[196:199], v[212:215], v[30:33]
	v_mfma_f32_16x16x32_bf16 v[22:25], v[188:191], v[220:223], v[22:25]
	v_mfma_f32_16x16x32_bf16 v[14:17], v[196:199], v[220:223], v[14:17]
	v_mfma_f32_16x16x32_bf16 v[6:9], v[188:191], v[228:231], v[6:9]
	v_mfma_f32_16x16x32_bf16 v[2:5], v[196:199], v[228:231], v[2:5]
	s_setprio 0
	s_barrier
	s_add_i32 s6, s6, 2
	s_add_u32 s75, s75, 0x100
	s_addc_u32 s92, s92, 0
	s_add_u32 s93, s93, 0x100
	s_addc_u32 s94, s94, 0
	s_add_u32 s4, s4, 0x100
	s_addc_u32 s5, s5, 0
	s_cmp_gt_u32 s6, 13
	s_cbranch_scc0 .LBB0_673
	s_and_b64 vcc, exec, s[70:71]
	s_cbranch_vccz .LBB0_676
	s_barrier

; #define PG8_STAGE(bufoff, gbase, voff) do { if constexpr (VAR != 1 && VAR != 3) { _Pragma("unroll") for (int _i = 0; _i < 2; ++_i) \
;         asm volatile("s_mov_b32 m0, %2\n\ts_nop 0\n\tglobal_load_lds_dwordx4 %0, %1" :: "v"((voff)[_i]), "s"((const char*)(gbase)), "s"(ldsbase + (unsigned)((bufoff) + _i * 8192)) : "memory", "m0"); } } while (0)
; #define PG8_LDA(dst, b, h) do { if constexpr (VAR < 2) _Pragma("unroll") for (int m = 0; m < 4; ++m) _Pragma("unroll") for (int k = 0; k < 2; ++k) dst[m][k] = *(const LAS bf16x8*)(lds + PG8_SA(b, h) + aoff + m * 2048 + k * 1024); } while (0)
; #define PG8_LDB(dst, b, h) do { if constexpr (VAR < 2) _Pragma("unroll") for (int n = 0; n < 2; ++n) _Pragma("unroll") for (int k = 0; k < 2; ++k) dst[n][k] = *(const LAS bf16x8*)(lds + PG8_SB(b, h) + boff + n * 2048 + k * 1024); } while (0)
; #define PG8_WAIT_V(n) asm volatile("s_waitcnt vmcnt(" #n ")" ::: "memory")
; #define PG8_WAIT_L(n) asm volatile("s_waitcnt lgkmcnt(" #n ")" ::: "memory")
; #define PG8_BAR do { if constexpr (VAR != 3) __builtin_amdgcn_s_barrier(); } while (0)
; #define PG8_SCHED __builtin_amdgcn_sched_barrier(0)
;     ...
;         for (int t = 0; t < nt; t += 2) {
;             const bool last = (t == nt - 2);
;             const char* a1 = cA + (size_t)(t + 1) * kstep;
;             const char* a2 = last ? nA : cA + (size_t)(t + 2) * kstep; const char* b2 = last ? nB : cB + (size_t)(t + 2) * kstep;
;             const char* a3 = a2 + kstep; const char* b3 = b2 + kstep;
;             PG8_LDB(B0, 0, 0); PG8_LDB(B1, 0, 1); PG8_SCHED; PG8_LDA(At, 0, 0); PG8_STAGE(PG8_SA(1, 1), a1 + hstepA, voffA);
;             PG8_WAIT_V(8); PG8_WAIT_L(0); PG8_BAR; PG8_MMA(0, 0, At, B0); PG8_MMA(0, 1, At, B1); PG8_BAR; PG8_SCHED;
;             PG8_LDA(At, 0, 1); PG8_STAGE(PG8_SB(0, 0), b2, voffB); PG8_STAGE(PG8_SB(0, 1), b2 + hstepB, voffB); PG8_STAGE(PG8_SA(0, 0), a2, voffA);
;             PG8_WAIT_V(8); PG8_WAIT_L(0); PG8_BAR; PG8_MMA(1, 0, At, B0); PG8_MMA(1, 1, At, B1); PG8_BAR; PG8_SCHED;
.LBB0_701:
	ds_read_b128 v[148:151], v1
	ds_read_b128 v[152:155], v1 offset:1024
	ds_read_b128 v[156:159], v1 offset:2048
	ds_read_b128 v[160:163], v1 offset:3072
	ds_read_b128 v[164:167], v143
	ds_read_b128 v[168:171], v143 offset:1024
	ds_read_b128 v[172:175], v143 offset:2048
	ds_read_b128 v[176:179], v143 offset:3072
	s_cmp_eq_u32 s6, 12
	s_cselect_b32 s70, s0, s57
	s_cselect_b32 s71, s1, s81
	s_cselect_b32 s68, s62, s82
	s_cselect_b32 s69, s63, s83
	s_add_u32 s66, s70, 0x80
	s_addc_u32 s67, s71, 0
	ds_read_b128 v[180:183], v144
	ds_read_b128 v[184:187], v144 offset:1024
	ds_read_b128 v[188:191], v144 offset:2048
	ds_read_b128 v[192:195], v144 offset:3072
	ds_read_b128 v[196:199], v144 offset:4096
	ds_read_b128 v[200:203], v144 offset:5120
	ds_read_b128 v[204:207], v144 offset:6144
	ds_read_b128 v[208:211], v144 offset:7168
	s_mov_b32 m0, s76
	s_nop 0
	global_load_lds_dwordx4 v138, s[64:65]
	s_mov_b32 m0, s77
	s_nop 0
	global_load_lds_dwordx4 v140, s[64:65]
	s_waitcnt vmcnt(8)
	s_waitcnt lgkmcnt(0)
	s_barrier
	s_setprio 1
	v_mfma_f32_16x16x32_bf16 v[126:129], v[148:151], v[180:183], v[126:129]
	v_mfma_f32_16x16x32_bf16 v[122:125], v[156:159], v[180:183], v[122:125]
	v_mfma_f32_16x16x32_bf16 v[118:121], v[148:151], v[188:191], v[118:121]
	v_mfma_f32_16x16x32_bf16 v[110:113], v[156:159], v[188:191], v[110:113]
	v_mfma_f32_16x16x32_bf16 v[102:105], v[148:151], v[196:199], v[102:105]
	v_mfma_f32_16x16x32_bf16 v[94:97], v[156:159], v[196:199], v[94:97]
	v_mfma_f32_16x16x32_bf16 v[86:89], v[148:151], v[204:207], v[86:89]
	v_mfma_f32_16x16x32_bf16 v[78:81], v[156:159], v[204:207], v[78:81]
	v_mfma_f32_16x16x32_bf16 v[126:129], v[152:155], v[184:187], v[126:129]
	v_mfma_f32_16x16x32_bf16 v[122:125], v[160:163], v[184:187], v[122:125]
	v_mfma_f32_16x16x32_bf16 v[118:121], v[152:155], v[192:195], v[118:121]
	v_mfma_f32_16x16x32_bf16 v[110:113], v[160:163], v[192:195], v[110:113]
	v_mfma_f32_16x16x32_bf16 v[102:105], v[152:155], v[200:203], v[102:105]
	v_mfma_f32_16x16x32_bf16 v[94:97], v[160:163], v[200:203], v[94:97]
	v_mfma_f32_16x16x32_bf16 v[86:89], v[152:155], v[208:211], v[86:89]
	v_mfma_f32_16x16x32_bf16 v[78:81], v[160:163], v[208:211], v[78:81]
	s_setprio 0
	s_setprio 1
	v_mfma_f32_16x16x32_bf16 v[114:117], v[164:167], v[180:183], v[114:117]
	v_mfma_f32_16x16x32_bf16 v[106:109], v[172:175], v[180:183], v[106:109]
	v_mfma_f32_16x16x32_bf16 v[98:101], v[164:167], v[188:191], v[98:101]
	v_mfma_f32_16x16x32_bf16 v[90:93], v[172:175], v[188:191], v[90:93]
	v_mfma_f32_16x16x32_bf16 v[82:85], v[164:167], v[196:199], v[82:85]
	v_mfma_f32_16x16x32_bf16 v[74:77], v[172:175], v[196:199], v[74:77]
	v_mfma_f32_16x16x32_bf16 v[70:73], v[164:167], v[204:207], v[70:73]
	v_mfma_f32_16x16x32_bf16 v[66:69], v[172:175], v[204:207], v[66:69]
	v_mfma_f32_16x16x32_bf16 v[114:117], v[168:171], v[184:187], v[114:117]
	v_mfma_f32_16x16x32_bf16 v[106:109], v[176:179], v[184:187], v[106:109]
	v_mfma_f32_16x16x32_bf16 v[98:101], v[168:171], v[192:195], v[98:101]
	v_mfma_f32_16x16x32_bf16 v[90:93], v[176:179], v[192:195], v[90:93]
	v_mfma_f32_16x16x32_bf16 v[82:85], v[168:171], v[200:203], v[82:85]
	v_mfma_f32_16x16x32_bf16 v[74:77], v[176:179], v[200:203], v[74:77]
	v_mfma_f32_16x16x32_bf16 v[70:73], v[168:171], v[208:211], v[70:73]
	v_mfma_f32_16x16x32_bf16 v[66:69], v[176:179], v[208:211], v[66:69]
	s_setprio 0
	s_barrier
	ds_read_b128 v[180:183], v144 offset:16384
	ds_read_b128 v[184:187], v144 offset:17408
	ds_read_b128 v[188:191], v144 offset:18432
	ds_read_b128 v[192:195], v144 offset:19456
	ds_read_b128 v[196:199], v144 offset:20480
	ds_read_b128 v[200:203], v144 offset:21504
	ds_read_b128 v[204:207], v144 offset:22528
	ds_read_b128 v[208:211], v144 offset:23552
	s_mov_b32 m0, s24
	s_nop 0
	global_load_lds_dwordx4 v139, s[68:69]
	s_add_u32 s84, s68, 0x200000
	s_mov_b32 m0, s25
	s_nop 0
	global_load_lds_dwordx4 v141, s[68:69]
	s_addc_u32 s85, s69, 0
	s_mov_b32 m0, s26
	s_nop 0
	global_load_lds_dwordx4 v139, s[84:85]
	s_mov_b32 m0, s27
	s_nop 0
	global_load_lds_dwordx4 v141, s[84:85]
	s_mov_b32 m0, s15
	s_nop 0
	global_load_lds_dwordx4 v138, s[70:71]
	s_mov_b32 m0, s28
	s_nop 0
	global_load_lds_dwordx4 v140, s[70:71]
	s_waitcnt vmcnt(8)
	s_waitcnt lgkmcnt(0)
	s_barrier
	s_setprio 1
	v_mfma_f32_16x16x32_bf16 v[62:65], v[148:151], v[180:183], v[62:65]
	v_mfma_f32_16x16x32_bf16 v[58:61], v[156:159], v[180:183], v[58:61]
	v_mfma_f32_16x16x32_bf16 v[54:57], v[148:151], v[188:191], v[54:57]
	v_mfma_f32_16x16x32_bf16 v[46:49], v[156:159], v[188:191], v[46:49]
	v_mfma_f32_16x16x32_bf16 v[38:41], v[148:151], v[196:199], v[38:41]
	v_mfma_f32_16x16x32_bf16 v[30:33], v[156:159], v[196:199], v[30:33]
	v_mfma_f32_16x16x32_bf16 v[22:25], v[148:151], v[204:207], v[22:25]
	v_mfma_f32_16x16x32_bf16 v[14:17], v[156:159], v[204:207], v[14:17]
	v_mfma_f32_16x16x32_bf16 v[62:65], v[152:155], v[184:187], v[62:65]
	v_mfma_f32_16x16x32_bf16 v[58:61], v[160:163], v[184:187], v[58:61]
	v_mfma_f32_16x16x32_bf16 v[54:57], v[152:155], v[192:195], v[54:57]
	v_mfma_f32_16x16x32_bf16 v[46:49], v[160:163], v[192:195], v[46:49]
	v_mfma_f32_16x16x32_bf16 v[38:41], v[152:155], v[200:203], v[38:41]
	v_mfma_f32_16x16x32_bf16 v[30:33], v[160:163], v[200:203], v[30:33]
	v_mfma_f32_16x16x32_bf16 v[22:25], v[152:155], v[208:211], v[22:25]
	v_mfma_f32_16x16x32_bf16 v[14:17], v[160:163], v[208:211], v[14:17]
	s_setprio 0
	s_setprio 1
	v_mfma_f32_16x16x32_bf16 v[50:53], v[164:167], v[180:183], v[50:53]
	v_mfma_f32_16x16x32_bf16 v[42:45], v[172:175], v[180:183], v[42:45]
	v_mfma_f32_16x16x32_bf16 v[34:37], v[164:167], v[188:191], v[34:37]
	v_mfma_f32_16x16x32_bf16 v[26:29], v[172:175], v[188:191], v[26:29]
	v_mfma_f32_16x16x32_bf16 v[18:21], v[164:167], v[196:199], v[18:21]
	v_mfma_f32_16x16x32_bf16 v[10:13], v[172:175], v[196:199], v[10:13]
	v_mfma_f32_16x16x32_bf16 v[6:9], v[164:167], v[204:207], v[6:9]
	v_mfma_f32_16x16x32_bf16 v[2:5], v[172:175], v[204:207], v[2:5]
	v_mfma_f32_16x16x32_bf16 v[50:53], v[168:171], v[184:187], v[50:53]
	v_mfma_f32_16x16x32_bf16 v[42:45], v[176:179], v[184:187], v[42:45]
	v_mfma_f32_16x16x32_bf16 v[34:37], v[168:171], v[192:195], v[34:37]
	v_mfma_f32_16x16x32_bf16 v[26:29], v[176:179], v[192:195], v[26:29]
	v_mfma_f32_16x16x32_bf16 v[18:21], v[168:171], v[200:203], v[18:21]
	v_mfma_f32_16x16x32_bf16 v[10:13], v[176:179], v[200:203], v[10:13]
	v_mfma_f32_16x16x32_bf16 v[6:9], v[168:171], v[208:211], v[6:9]
	v_mfma_f32_16x16x32_bf16 v[2:5], v[176:179], v[208:211], v[2:5]
	s_setprio 0
	s_barrier
; #define PG8_STAGE(bufoff, gbase, voff) do { if constexpr (VAR != 1 && VAR != 3) { _Pragma("unroll") for (int _i = 0; _i < 2; ++_i) \
;         asm volatile("s_mov_b32 m0, %2\n\ts_nop 0\n\tglobal_load_lds_dwordx4 %0, %1" :: "v"((voff)[_i]), "s"((const char*)(gbase)), "s"(ldsbase + (unsigned)((bufoff) + _i * 8192)) : "memory", "m0"); } } while (0)
; #define PG8_LDA(dst, b, h) do { if constexpr (VAR < 2) _Pragma("unroll") for (int m = 0; m < 4; ++m) _Pragma("unroll") for (int k = 0; k < 2; ++k) dst[m][k] = *(const LAS bf16x8*)(lds + PG8_SA(b, h) + aoff + m * 2048 + k * 1024); } while (0)
; #define PG8_LDB(dst, b, h) do { if constexpr (VAR < 2) _Pragma("unroll") for (int n = 0; n < 2; ++n) _Pragma("unroll") for (int k = 0; k < 2; ++k) dst[n][k] = *(const LAS bf16x8*)(lds + PG8_SB(b, h) + boff + n * 2048 + k * 1024); } while (0)
; #define PG8_WAIT_V(n) asm volatile("s_waitcnt vmcnt(" #n ")" ::: "memory")
; #define PG8_WAIT_L(n) asm volatile("s_waitcnt lgkmcnt(" #n ")" ::: "memory")
; #define PG8_BAR do { if constexpr (VAR != 3) __builtin_amdgcn_s_barrier(); } while (0)
; #define PG8_SCHED __builtin_amdgcn_sched_barrier(0)
;     ...
;             PG8_LDB(B0, 1, 0); PG8_LDB(B1, 1, 1); PG8_SCHED; PG8_LDA(At, 1, 0); PG8_STAGE(PG8_SA(0, 1), a2 + hstepA, voffA);
;             PG8_WAIT_V(8); PG8_WAIT_L(0); PG8_BAR; PG8_MMA(0, 0, At, B0); PG8_MMA(0, 1, At, B1); PG8_BAR; PG8_SCHED;
;             PG8_LDA(At, 1, 1); PG8_STAGE(PG8_SB(1, 0), b3, voffB); PG8_STAGE(PG8_SB(1, 1), b3 + hstepB, voffB); PG8_STAGE(PG8_SA(1, 0), a3, voffA);
;             PG8_WAIT_V(8); PG8_WAIT_L(0); PG8_BAR; PG8_MMA(1, 0, At, B0); PG8_MMA(1, 1, At, B1); PG8_BAR; PG8_SCHED;
;         }
	ds_read_b128 v[148:151], v145
	ds_read_b128 v[152:155], v145 offset:1024
	ds_read_b128 v[156:159], v145 offset:2048
	ds_read_b128 v[160:163], v145 offset:3072
	ds_read_b128 v[164:167], v146
	ds_read_b128 v[168:171], v146 offset:1024
	ds_read_b128 v[172:175], v146 offset:2048
	ds_read_b128 v[176:179], v146 offset:3072
	ds_read_b128 v[180:183], v144 offset:32768
	ds_read_b128 v[184:187], v144 offset:33792
	ds_read_b128 v[188:191], v144 offset:34816
	ds_read_b128 v[192:195], v144 offset:35840
	ds_read_b128 v[196:199], v144 offset:36864
	ds_read_b128 v[200:203], v144 offset:37888
	ds_read_b128 v[204:207], v144 offset:38912
	ds_read_b128 v[208:211], v144 offset:39936
	s_add_u32 s70, s70, 0x100000
	s_addc_u32 s71, s71, 0
	s_mov_b32 m0, s29
	s_nop 0
	global_load_lds_dwordx4 v138, s[70:71]
	s_mov_b32 m0, s30
	s_nop 0
	global_load_lds_dwordx4 v140, s[70:71]
	s_waitcnt vmcnt(8)
	s_waitcnt lgkmcnt(0)
	s_barrier
	s_setprio 1
	v_mfma_f32_16x16x32_bf16 v[126:129], v[148:151], v[180:183], v[126:129]
	v_mfma_f32_16x16x32_bf16 v[122:125], v[156:159], v[180:183], v[122:125]
	v_mfma_f32_16x16x32_bf16 v[118:121], v[148:151], v[188:191], v[118:121]
	v_mfma_f32_16x16x32_bf16 v[110:113], v[156:159], v[188:191], v[110:113]
	v_mfma_f32_16x16x32_bf16 v[102:105], v[148:151], v[196:199], v[102:105]
	v_mfma_f32_16x16x32_bf16 v[94:97], v[156:159], v[196:199], v[94:97]
	v_mfma_f32_16x16x32_bf16 v[86:89], v[148:151], v[204:207], v[86:89]
	v_mfma_f32_16x16x32_bf16 v[78:81], v[156:159], v[204:207], v[78:81]
	v_mfma_f32_16x16x32_bf16 v[126:129], v[152:155], v[184:187], v[126:129]
	v_mfma_f32_16x16x32_bf16 v[122:125], v[160:163], v[184:187], v[122:125]
	v_mfma_f32_16x16x32_bf16 v[118:121], v[152:155], v[192:195], v[118:121]
	v_mfma_f32_16x16x32_bf16 v[110:113], v[160:163], v[192:195], v[110:113]
	v_mfma_f32_16x16x32_bf16 v[102:105], v[152:155], v[200:203], v[102:105]
	v_mfma_f32_16x16x32_bf16 v[94:97], v[160:163], v[200:203], v[94:97]
	v_mfma_f32_16x16x32_bf16 v[86:89], v[152:155], v[208:211], v[86:89]
	v_mfma_f32_16x16x32_bf16 v[78:81], v[160:163], v[208:211], v[78:81]
	s_setprio 0
	s_setprio 1
	v_mfma_f32_16x16x32_bf16 v[114:117], v[164:167], v[180:183], v[114:117]
	v_mfma_f32_16x16x32_bf16 v[106:109], v[172:175], v[180:183], v[106:109]
	v_mfma_f32_16x16x32_bf16 v[98:101], v[164:167], v[188:191], v[98:101]
	v_mfma_f32_16x16x32_bf16 v[90:93], v[172:175], v[188:191], v[90:93]
	v_mfma_f32_16x16x32_bf16 v[82:85], v[164:167], v[196:199], v[82:85]
	v_mfma_f32_16x16x32_bf16 v[74:77], v[172:175], v[196:199], v[74:77]
	v_mfma_f32_16x16x32_bf16 v[70:73], v[164:167], v[204:207], v[70:73]
	v_mfma_f32_16x16x32_bf16 v[66:69], v[172:175], v[204:207], v[66:69]
	v_mfma_f32_16x16x32_bf16 v[114:117], v[168:171], v[184:187], v[114:117]
	v_mfma_f32_16x16x32_bf16 v[106:109], v[176:179], v[184:187], v[106:109]
	v_mfma_f32_16x16x32_bf16 v[98:101], v[168:171], v[192:195], v[98:101]
	v_mfma_f32_16x16x32_bf16 v[90:93], v[176:179], v[192:195], v[90:93]
	v_mfma_f32_16x16x32_bf16 v[82:85], v[168:171], v[200:203], v[82:85]
	v_mfma_f32_16x16x32_bf16 v[74:77], v[176:179], v[200:203], v[74:77]
	v_mfma_f32_16x16x32_bf16 v[70:73], v[168:171], v[208:211], v[70:73]
	v_mfma_f32_16x16x32_bf16 v[66:69], v[176:179], v[208:211], v[66:69]
	s_setprio 0
	s_barrier
	ds_read_b128 v[180:183], v144 offset:49152
	ds_read_b128 v[184:187], v144 offset:50176
	ds_read_b128 v[188:191], v144 offset:51200
	ds_read_b128 v[192:195], v144 offset:52224
	ds_read_b128 v[196:199], v144 offset:53248
	ds_read_b128 v[200:203], v144 offset:54272
	ds_read_b128 v[204:207], v144 offset:55296
	ds_read_b128 v[208:211], v144 offset:56320
	s_add_u32 s70, s68, 0x80
	s_addc_u32 s71, s69, 0
	s_mov_b32 m0, s31
	s_nop 0
	global_load_lds_dwordx4 v139, s[70:71]
	s_add_u32 s68, s68, 0x200080
	s_mov_b32 m0, s33
	s_nop 0
	global_load_lds_dwordx4 v141, s[70:71]
	s_addc_u32 s69, s69, 0
	s_mov_b32 m0, s74
	s_nop 0
	global_load_lds_dwordx4 v139, s[68:69]
	s_mov_b32 m0, s75
	s_nop 0
	global_load_lds_dwordx4 v141, s[68:69]
	s_mov_b32 m0, s72
	s_nop 0
	global_load_lds_dwordx4 v138, s[66:67]
	s_mov_b32 m0, s73
	s_nop 0
	global_load_lds_dwordx4 v140, s[66:67]
	s_waitcnt vmcnt(8)
	s_waitcnt lgkmcnt(0)
	s_barrier
	s_setprio 1
	v_mfma_f32_16x16x32_bf16 v[62:65], v[148:151], v[180:183], v[62:65]
	v_mfma_f32_16x16x32_bf16 v[58:61], v[156:159], v[180:183], v[58:61]
	v_mfma_f32_16x16x32_bf16 v[54:57], v[148:151], v[188:191], v[54:57]
	v_mfma_f32_16x16x32_bf16 v[46:49], v[156:159], v[188:191], v[46:49]
	v_mfma_f32_16x16x32_bf16 v[38:41], v[148:151], v[196:199], v[38:41]
	v_mfma_f32_16x16x32_bf16 v[30:33], v[156:159], v[196:199], v[30:33]
	v_mfma_f32_16x16x32_bf16 v[22:25], v[148:151], v[204:207], v[22:25]
	v_mfma_f32_16x16x32_bf16 v[14:17], v[156:159], v[204:207], v[14:17]
	v_mfma_f32_16x16x32_bf16 v[62:65], v[152:155], v[184:187], v[62:65]
	v_mfma_f32_16x16x32_bf16 v[58:61], v[160:163], v[184:187], v[58:61]
	v_mfma_f32_16x16x32_bf16 v[54:57], v[152:155], v[192:195], v[54:57]
	v_mfma_f32_16x16x32_bf16 v[46:49], v[160:163], v[192:195], v[46:49]
	v_mfma_f32_16x16x32_bf16 v[38:41], v[152:155], v[200:203], v[38:41]
	v_mfma_f32_16x16x32_bf16 v[30:33], v[160:163], v[200:203], v[30:33]
	v_mfma_f32_16x16x32_bf16 v[22:25], v[152:155], v[208:211], v[22:25]
	v_mfma_f32_16x16x32_bf16 v[14:17], v[160:163], v[208:211], v[14:17]
	s_setprio 0
	s_setprio 1
	v_mfma_f32_16x16x32_bf16 v[50:53], v[164:167], v[180:183], v[50:53]
	v_mfma_f32_16x16x32_bf16 v[42:45], v[172:175], v[180:183], v[42:45]
	v_mfma_f32_16x16x32_bf16 v[34:37], v[164:167], v[188:191], v[34:37]
	v_mfma_f32_16x16x32_bf16 v[26:29], v[172:175], v[188:191], v[26:29]
	v_mfma_f32_16x16x32_bf16 v[18:21], v[164:167], v[196:199], v[18:21]
	v_mfma_f32_16x16x32_bf16 v[10:13], v[172:175], v[196:199], v[10:13]
	v_mfma_f32_16x16x32_bf16 v[6:9], v[164:167], v[204:207], v[6:9]
	v_mfma_f32_16x16x32_bf16 v[2:5], v[172:175], v[204:207], v[2:5]
	v_mfma_f32_16x16x32_bf16 v[50:53], v[168:171], v[184:187], v[50:53]
	v_mfma_f32_16x16x32_bf16 v[42:45], v[176:179], v[184:187], v[42:45]
	v_mfma_f32_16x16x32_bf16 v[34:37], v[168:171], v[192:195], v[34:37]
	v_mfma_f32_16x16x32_bf16 v[26:29], v[176:179], v[192:195], v[26:29]
	v_mfma_f32_16x16x32_bf16 v[18:21], v[168:171], v[200:203], v[18:21]
	v_mfma_f32_16x16x32_bf16 v[10:13], v[176:179], v[200:203], v[10:13]
	v_mfma_f32_16x16x32_bf16 v[6:9], v[168:171], v[208:211], v[6:9]
	v_mfma_f32_16x16x32_bf16 v[2:5], v[176:179], v[208:211], v[2:5]
	s_setprio 0
	s_barrier
	s_add_i32 s6, s6, 2
	s_add_u32 s57, s57, 0x100
	s_addc_u32 s81, s81, 0
	s_add_u32 s82, s82, 0x100
	s_addc_u32 s83, s83, 0
	s_add_u32 s64, s64, 0x100
	s_addc_u32 s65, s65, 0
	s_cmp_gt_u32 s6, 13
	s_cbranch_scc0 .LBB0_701
	s_and_b64 vcc, exec, s[8:9]
	s_cbranch_vccz .LBB0_704
	s_barrier

; #define PG8_STAGE(bufoff, gbase, voff) do { if constexpr (VAR != 1 && VAR != 3) { _Pragma("unroll") for (int _i = 0; _i < 2; ++_i) \
;         asm volatile("s_mov_b32 m0, %2\n\ts_nop 0\n\tglobal_load_lds_dwordx4 %0, %1" :: "v"((voff)[_i]), "s"((const char*)(gbase)), "s"(ldsbase + (unsigned)((bufoff) + _i * 8192)) : "memory", "m0"); } } while (0)
; #define PG8_LDA(dst, b, h) do { if constexpr (VAR < 2) _Pragma("unroll") for (int m = 0; m < 4; ++m) _Pragma("unroll") for (int k = 0; k < 2; ++k) dst[m][k] = *(const LAS bf16x8*)(lds + PG8_SA(b, h) + aoff + m * 2048 + k * 1024); } while (0)
; #define PG8_LDB(dst, b, h) do { if constexpr (VAR < 2) _Pragma("unroll") for (int n = 0; n < 2; ++n) _Pragma("unroll") for (int k = 0; k < 2; ++k) dst[n][k] = *(const LAS bf16x8*)(lds + PG8_SB(b, h) + boff + n * 2048 + k * 1024); } while (0)
; #define PG8_WAIT_V(n) asm volatile("s_waitcnt vmcnt(" #n ")" ::: "memory")
; #define PG8_WAIT_L(n) asm volatile("s_waitcnt lgkmcnt(" #n ")" ::: "memory")
; #define PG8_BAR do { if constexpr (VAR != 3) __builtin_amdgcn_s_barrier(); } while (0)
; #define PG8_SCHED __builtin_amdgcn_sched_barrier(0)
;     ...
;         for (int t = 0; t < nt; t += 2) {
;             const bool last = (t == nt - 2);
;             const char* a1 = cA + (size_t)(t + 1) * kstep;
;             const char* a2 = last ? nA : cA + (size_t)(t + 2) * kstep; const char* b2 = last ? nB : cB + (size_t)(t + 2) * kstep;
;             const char* a3 = a2 + kstep; const char* b3 = b2 + kstep;
;             PG8_LDB(B0, 0, 0); PG8_LDB(B1, 0, 1); PG8_SCHED; PG8_LDA(At, 0, 0); PG8_STAGE(PG8_SA(1, 1), a1 + hstepA, voffA);
;             PG8_WAIT_V(8); PG8_WAIT_L(0); PG8_BAR; PG8_MMA(0, 0, At, B0); PG8_MMA(0, 1, At, B1); PG8_BAR; PG8_SCHED;
;             PG8_LDA(At, 0, 1); PG8_STAGE(PG8_SB(0, 0), b2, voffB); PG8_STAGE(PG8_SB(0, 1), b2 + hstepB, voffB); PG8_STAGE(PG8_SA(0, 0), a2, voffA);
;             PG8_WAIT_V(8); PG8_WAIT_L(0); PG8_BAR; PG8_MMA(1, 0, At, B0); PG8_MMA(1, 1, At, B1); PG8_BAR; PG8_SCHED;
.LBB0_789:
	ds_read_b128 v[98:101], v191
	ds_read_b128 v[110:113], v191 offset:1024
	ds_read_b128 v[122:125], v191 offset:2048
	ds_read_b128 v[134:137], v191 offset:3072
	ds_read_b128 v[138:141], v192
	ds_read_b128 v[150:153], v192 offset:1024
	ds_read_b128 v[154:157], v192 offset:2048
	ds_read_b128 v[162:165], v192 offset:3072
	s_cmp_eq_u32 vcc_hi, 60
	s_cselect_b32 s86, s15, s27
	s_cselect_b32 s87, s14, s71
	s_cselect_b32 s84, s26, s73
	s_cselect_b32 s85, s25, vcc_lo
	s_add_u32 s82, s86, 0x80
	s_addc_u32 s83, s87, 0
	ds_read_b128 v[166:169], v193
	ds_read_b128 v[170:173], v193 offset:1024
	ds_read_b128 v[174:177], v193 offset:2048
	ds_read_b128 v[178:181], v193 offset:3072
	ds_read_b128 v[198:201], v193 offset:4096
	ds_read_b128 v[202:205], v193 offset:5120
	ds_read_b128 v[206:209], v193 offset:6144
	ds_read_b128 v[210:213], v193 offset:7168
	s_mov_b32 m0, s31
	s_nop 0
	global_load_lds_dwordx4 v184, s[80:81]
	s_mov_b32 m0, s19
	s_nop 0
	global_load_lds_dwordx4 v186, s[80:81]
	s_waitcnt vmcnt(8)
	s_waitcnt lgkmcnt(0)
	s_barrier
	s_setprio 1
	v_mfma_f32_16x16x32_bf16 v[146:149], v[98:101], v[166:169], v[146:149]
	v_mfma_f32_16x16x32_bf16 v[142:145], v[122:125], v[166:169], v[142:145]
	v_mfma_f32_16x16x32_bf16 v[118:121], v[98:101], v[174:177], v[118:121]
	v_mfma_f32_16x16x32_bf16 v[114:117], v[122:125], v[174:177], v[114:117]
	v_mfma_f32_16x16x32_bf16 v[94:97], v[98:101], v[198:201], v[94:97]
	v_mfma_f32_16x16x32_bf16 v[90:93], v[122:125], v[198:201], v[90:93]
	v_mfma_f32_16x16x32_bf16 v[78:81], v[98:101], v[206:209], v[78:81]
	v_mfma_f32_16x16x32_bf16 v[74:77], v[122:125], v[206:209], v[74:77]
	v_mfma_f32_16x16x32_bf16 v[146:149], v[110:113], v[170:173], v[146:149]
	v_mfma_f32_16x16x32_bf16 v[142:145], v[134:137], v[170:173], v[142:145]
	v_mfma_f32_16x16x32_bf16 v[118:121], v[110:113], v[178:181], v[118:121]
	v_mfma_f32_16x16x32_bf16 v[114:117], v[134:137], v[178:181], v[114:117]
	v_mfma_f32_16x16x32_bf16 v[94:97], v[110:113], v[202:205], v[94:97]
	v_mfma_f32_16x16x32_bf16 v[90:93], v[134:137], v[202:205], v[90:93]
	v_mfma_f32_16x16x32_bf16 v[78:81], v[110:113], v[210:213], v[78:81]
	v_mfma_f32_16x16x32_bf16 v[74:77], v[134:137], v[210:213], v[74:77]
	s_setprio 0
	s_setprio 1
	v_mfma_f32_16x16x32_bf16 v[130:133], v[138:141], v[166:169], v[130:133]
	v_mfma_f32_16x16x32_bf16 v[126:129], v[154:157], v[166:169], v[126:129]
	v_mfma_f32_16x16x32_bf16 v[106:109], v[138:141], v[174:177], v[106:109]
	v_mfma_f32_16x16x32_bf16 v[102:105], v[154:157], v[174:177], v[102:105]
	v_mfma_f32_16x16x32_bf16 v[86:89], v[138:141], v[198:201], v[86:89]
	v_mfma_f32_16x16x32_bf16 v[82:85], v[154:157], v[198:201], v[82:85]
	v_mfma_f32_16x16x32_bf16 v[70:73], v[138:141], v[206:209], v[70:73]
	v_mfma_f32_16x16x32_bf16 v[66:69], v[154:157], v[206:209], v[66:69]
	v_mfma_f32_16x16x32_bf16 v[130:133], v[150:153], v[170:173], v[130:133]
	v_mfma_f32_16x16x32_bf16 v[126:129], v[162:165], v[170:173], v[126:129]
	v_mfma_f32_16x16x32_bf16 v[106:109], v[150:153], v[178:181], v[106:109]
	v_mfma_f32_16x16x32_bf16 v[102:105], v[162:165], v[178:181], v[102:105]
	v_mfma_f32_16x16x32_bf16 v[86:89], v[150:153], v[202:205], v[86:89]
	v_mfma_f32_16x16x32_bf16 v[82:85], v[162:165], v[202:205], v[82:85]
	v_mfma_f32_16x16x32_bf16 v[70:73], v[150:153], v[210:213], v[70:73]
	v_mfma_f32_16x16x32_bf16 v[66:69], v[162:165], v[210:213], v[66:69]
	s_setprio 0
	s_barrier
	ds_read_b128 v[166:169], v193 offset:16384
	ds_read_b128 v[170:173], v193 offset:17408
	ds_read_b128 v[174:177], v193 offset:18432
	ds_read_b128 v[178:181], v193 offset:19456
	ds_read_b128 v[198:201], v193 offset:20480
	ds_read_b128 v[202:205], v193 offset:21504
	ds_read_b128 v[206:209], v193 offset:22528
	ds_read_b128 v[210:213], v193 offset:23552
	s_mov_b32 m0, s91
	s_nop 0
	global_load_lds_dwordx4 v185, s[84:85]
	s_add_u32 s88, s84, 0x100000
	s_mov_b32 m0, s92
	s_nop 0
	global_load_lds_dwordx4 v187, s[84:85]
	s_addc_u32 s89, s85, 0
	s_mov_b32 m0, s93
	s_nop 0
	global_load_lds_dwordx4 v185, s[88:89]
	s_mov_b32 m0, s94
	s_nop 0
	global_load_lds_dwordx4 v187, s[88:89]
	s_mov_b32 m0, s35
	s_nop 0
	global_load_lds_dwordx4 v184, s[86:87]
	s_mov_b32 m0, s79
	s_nop 0
	global_load_lds_dwordx4 v186, s[86:87]
	s_waitcnt vmcnt(8)
	s_waitcnt lgkmcnt(0)
	s_barrier
	s_setprio 1
	v_mfma_f32_16x16x32_bf16 v[62:65], v[98:101], v[166:169], v[62:65]
	v_mfma_f32_16x16x32_bf16 v[58:61], v[122:125], v[166:169], v[58:61]
	v_mfma_f32_16x16x32_bf16 v[46:49], v[98:101], v[174:177], v[46:49]
	v_mfma_f32_16x16x32_bf16 v[42:45], v[122:125], v[174:177], v[42:45]
	v_mfma_f32_16x16x32_bf16 v[30:33], v[98:101], v[198:201], v[30:33]
	v_mfma_f32_16x16x32_bf16 v[26:29], v[122:125], v[198:201], v[26:29]
	v_mfma_f32_16x16x32_bf16 v[14:17], v[98:101], v[206:209], v[14:17]
	v_mfma_f32_16x16x32_bf16 v[10:13], v[122:125], v[206:209], v[10:13]
	v_mfma_f32_16x16x32_bf16 v[62:65], v[110:113], v[170:173], v[62:65]
	v_mfma_f32_16x16x32_bf16 v[58:61], v[134:137], v[170:173], v[58:61]
	v_mfma_f32_16x16x32_bf16 v[46:49], v[110:113], v[178:181], v[46:49]
	v_mfma_f32_16x16x32_bf16 v[42:45], v[134:137], v[178:181], v[42:45]
	v_mfma_f32_16x16x32_bf16 v[30:33], v[110:113], v[202:205], v[30:33]
	v_mfma_f32_16x16x32_bf16 v[26:29], v[134:137], v[202:205], v[26:29]
	v_mfma_f32_16x16x32_bf16 v[14:17], v[110:113], v[210:213], v[14:17]
	v_mfma_f32_16x16x32_bf16 v[10:13], v[134:137], v[210:213], v[10:13]
	s_setprio 0
	s_setprio 1
	v_mfma_f32_16x16x32_bf16 v[54:57], v[138:141], v[166:169], v[54:57]
	v_mfma_f32_16x16x32_bf16 v[50:53], v[154:157], v[166:169], v[50:53]
	v_mfma_f32_16x16x32_bf16 v[38:41], v[138:141], v[174:177], v[38:41]
	v_mfma_f32_16x16x32_bf16 v[34:37], v[154:157], v[174:177], v[34:37]
	v_mfma_f32_16x16x32_bf16 v[22:25], v[138:141], v[198:201], v[22:25]
	v_mfma_f32_16x16x32_bf16 v[18:21], v[154:157], v[198:201], v[18:21]
	v_mfma_f32_16x16x32_bf16 v[6:9], v[138:141], v[206:209], v[6:9]
	v_mfma_f32_16x16x32_bf16 v[2:5], v[154:157], v[206:209], v[2:5]
	v_mfma_f32_16x16x32_bf16 v[54:57], v[150:153], v[170:173], v[54:57]
	v_mfma_f32_16x16x32_bf16 v[50:53], v[162:165], v[170:173], v[50:53]
	v_mfma_f32_16x16x32_bf16 v[38:41], v[150:153], v[178:181], v[38:41]
	v_mfma_f32_16x16x32_bf16 v[34:37], v[162:165], v[178:181], v[34:37]
	v_mfma_f32_16x16x32_bf16 v[22:25], v[150:153], v[202:205], v[22:25]
	v_mfma_f32_16x16x32_bf16 v[18:21], v[162:165], v[202:205], v[18:21]
	v_mfma_f32_16x16x32_bf16 v[6:9], v[150:153], v[210:213], v[6:9]
	v_mfma_f32_16x16x32_bf16 v[2:5], v[162:165], v[210:213], v[2:5]
	s_setprio 0
	s_barrier
; #define PG8_STAGE(bufoff, gbase, voff) do { if constexpr (VAR != 1 && VAR != 3) { _Pragma("unroll") for (int _i = 0; _i < 2; ++_i) \
;         asm volatile("s_mov_b32 m0, %2\n\ts_nop 0\n\tglobal_load_lds_dwordx4 %0, %1" :: "v"((voff)[_i]), "s"((const char*)(gbase)), "s"(ldsbase + (unsigned)((bufoff) + _i * 8192)) : "memory", "m0"); } } while (0)
; #define PG8_LDA(dst, b, h) do { if constexpr (VAR < 2) _Pragma("unroll") for (int m = 0; m < 4; ++m) _Pragma("unroll") for (int k = 0; k < 2; ++k) dst[m][k] = *(const LAS bf16x8*)(lds + PG8_SA(b, h) + aoff + m * 2048 + k * 1024); } while (0)
; #define PG8_LDB(dst, b, h) do { if constexpr (VAR < 2) _Pragma("unroll") for (int n = 0; n < 2; ++n) _Pragma("unroll") for (int k = 0; k < 2; ++k) dst[n][k] = *(const LAS bf16x8*)(lds + PG8_SB(b, h) + boff + n * 2048 + k * 1024); } while (0)
; #define PG8_WAIT_V(n) asm volatile("s_waitcnt vmcnt(" #n ")" ::: "memory")
; #define PG8_WAIT_L(n) asm volatile("s_waitcnt lgkmcnt(" #n ")" ::: "memory")
; #define PG8_BAR do { if constexpr (VAR != 3) __builtin_amdgcn_s_barrier(); } while (0)
; #define PG8_SCHED __builtin_amdgcn_sched_barrier(0)
;     ...
;             PG8_LDB(B0, 1, 0); PG8_LDB(B1, 1, 1); PG8_SCHED; PG8_LDA(At, 1, 0); PG8_STAGE(PG8_SA(0, 1), a2 + hstepA, voffA);
;             PG8_WAIT_V(8); PG8_WAIT_L(0); PG8_BAR; PG8_MMA(0, 0, At, B0); PG8_MMA(0, 1, At, B1); PG8_BAR; PG8_SCHED;
;             PG8_LDA(At, 1, 1); PG8_STAGE(PG8_SB(1, 0), b3, voffB); PG8_STAGE(PG8_SB(1, 1), b3 + hstepB, voffB); PG8_STAGE(PG8_SA(1, 0), a3, voffA);
;             PG8_WAIT_V(8); PG8_WAIT_L(0); PG8_BAR; PG8_MMA(1, 0, At, B0); PG8_MMA(1, 1, At, B1); PG8_BAR; PG8_SCHED;
;         }
	ds_read_b128 v[98:101], v194
	ds_read_b128 v[110:113], v194 offset:1024
	ds_read_b128 v[122:125], v194 offset:2048
	ds_read_b128 v[134:137], v194 offset:3072
	ds_read_b128 v[138:141], v195
	ds_read_b128 v[150:153], v195 offset:1024
	ds_read_b128 v[154:157], v195 offset:2048
	ds_read_b128 v[162:165], v195 offset:3072
	ds_read_b128 v[166:169], v193 offset:32768
	ds_read_b128 v[170:173], v193 offset:33792
	ds_read_b128 v[174:177], v193 offset:34816
	ds_read_b128 v[178:181], v193 offset:35840
	ds_read_b128 v[198:201], v193 offset:36864
	ds_read_b128 v[202:205], v193 offset:37888
	ds_read_b128 v[206:209], v193 offset:38912
	ds_read_b128 v[210:213], v193 offset:39936
	s_add_u32 s86, s86, 0x100000
	s_addc_u32 s87, s87, 0
	s_mov_b32 m0, s95
	s_nop 0
	global_load_lds_dwordx4 v184, s[86:87]
	s_mov_b32 m0, s96
	s_nop 0
	global_load_lds_dwordx4 v186, s[86:87]
	s_waitcnt vmcnt(8)
	s_waitcnt lgkmcnt(0)
	s_barrier
	s_setprio 1
	v_mfma_f32_16x16x32_bf16 v[146:149], v[98:101], v[166:169], v[146:149]
	v_mfma_f32_16x16x32_bf16 v[142:145], v[122:125], v[166:169], v[142:145]
	v_mfma_f32_16x16x32_bf16 v[118:121], v[98:101], v[174:177], v[118:121]
	v_mfma_f32_16x16x32_bf16 v[114:117], v[122:125], v[174:177], v[114:117]
	v_mfma_f32_16x16x32_bf16 v[94:97], v[98:101], v[198:201], v[94:97]
	v_mfma_f32_16x16x32_bf16 v[90:93], v[122:125], v[198:201], v[90:93]
	v_mfma_f32_16x16x32_bf16 v[78:81], v[98:101], v[206:209], v[78:81]
	v_mfma_f32_16x16x32_bf16 v[74:77], v[122:125], v[206:209], v[74:77]
	v_mfma_f32_16x16x32_bf16 v[146:149], v[110:113], v[170:173], v[146:149]
	v_mfma_f32_16x16x32_bf16 v[142:145], v[134:137], v[170:173], v[142:145]
	v_mfma_f32_16x16x32_bf16 v[118:121], v[110:113], v[178:181], v[118:121]
	v_mfma_f32_16x16x32_bf16 v[114:117], v[134:137], v[178:181], v[114:117]
	v_mfma_f32_16x16x32_bf16 v[94:97], v[110:113], v[202:205], v[94:97]
	v_mfma_f32_16x16x32_bf16 v[90:93], v[134:137], v[202:205], v[90:93]
	v_mfma_f32_16x16x32_bf16 v[78:81], v[110:113], v[210:213], v[78:81]
	v_mfma_f32_16x16x32_bf16 v[74:77], v[134:137], v[210:213], v[74:77]
	s_setprio 0
	s_setprio 1
	v_mfma_f32_16x16x32_bf16 v[130:133], v[138:141], v[166:169], v[130:133]
	v_mfma_f32_16x16x32_bf16 v[126:129], v[154:157], v[166:169], v[126:129]
	v_mfma_f32_16x16x32_bf16 v[106:109], v[138:141], v[174:177], v[106:109]
	v_mfma_f32_16x16x32_bf16 v[102:105], v[154:157], v[174:177], v[102:105]
	v_mfma_f32_16x16x32_bf16 v[86:89], v[138:141], v[198:201], v[86:89]
	v_mfma_f32_16x16x32_bf16 v[82:85], v[154:157], v[198:201], v[82:85]
	v_mfma_f32_16x16x32_bf16 v[70:73], v[138:141], v[206:209], v[70:73]
	v_mfma_f32_16x16x32_bf16 v[66:69], v[154:157], v[206:209], v[66:69]
	v_mfma_f32_16x16x32_bf16 v[130:133], v[150:153], v[170:173], v[130:133]
	v_mfma_f32_16x16x32_bf16 v[126:129], v[162:165], v[170:173], v[126:129]
	v_mfma_f32_16x16x32_bf16 v[106:109], v[150:153], v[178:181], v[106:109]
	v_mfma_f32_16x16x32_bf16 v[102:105], v[162:165], v[178:181], v[102:105]
	v_mfma_f32_16x16x32_bf16 v[86:89], v[150:153], v[202:205], v[86:89]
	v_mfma_f32_16x16x32_bf16 v[82:85], v[162:165], v[202:205], v[82:85]
	v_mfma_f32_16x16x32_bf16 v[70:73], v[150:153], v[210:213], v[70:73]
	v_mfma_f32_16x16x32_bf16 v[66:69], v[162:165], v[210:213], v[66:69]
	s_setprio 0
	s_barrier
	ds_read_b128 v[166:169], v193 offset:49152
	ds_read_b128 v[170:173], v193 offset:50176
	ds_read_b128 v[174:177], v193 offset:51200
	ds_read_b128 v[178:181], v193 offset:52224
	ds_read_b128 v[198:201], v193 offset:53248
	ds_read_b128 v[202:205], v193 offset:54272
	ds_read_b128 v[206:209], v193 offset:55296
	ds_read_b128 v[210:213], v193 offset:56320
	s_add_u32 s86, s84, 0x80
	s_addc_u32 s87, s85, 0
	s_mov_b32 m0, s64
	s_nop 0
	global_load_lds_dwordx4 v185, s[86:87]
	s_add_u32 s84, s84, 0x100080
	s_mov_b32 m0, s65
	s_nop 0
	global_load_lds_dwordx4 v187, s[86:87]
	s_addc_u32 s85, s85, 0
	s_mov_b32 m0, s33
	s_nop 0
	global_load_lds_dwordx4 v185, s[84:85]
	s_mov_b32 m0, s30
	s_nop 0
	global_load_lds_dwordx4 v187, s[84:85]
	s_mov_b32 m0, s17
	s_nop 0
	global_load_lds_dwordx4 v184, s[82:83]
	s_mov_b32 m0, s28
	s_nop 0
	global_load_lds_dwordx4 v186, s[82:83]
	s_waitcnt vmcnt(8)
	s_waitcnt lgkmcnt(0)
	s_barrier
	s_setprio 1
	v_mfma_f32_16x16x32_bf16 v[62:65], v[98:101], v[166:169], v[62:65]
	v_mfma_f32_16x16x32_bf16 v[58:61], v[122:125], v[166:169], v[58:61]
	v_mfma_f32_16x16x32_bf16 v[46:49], v[98:101], v[174:177], v[46:49]
	v_mfma_f32_16x16x32_bf16 v[42:45], v[122:125], v[174:177], v[42:45]
	v_mfma_f32_16x16x32_bf16 v[30:33], v[98:101], v[198:201], v[30:33]
	v_mfma_f32_16x16x32_bf16 v[26:29], v[122:125], v[198:201], v[26:29]
	v_mfma_f32_16x16x32_bf16 v[14:17], v[98:101], v[206:209], v[14:17]
	v_mfma_f32_16x16x32_bf16 v[10:13], v[122:125], v[206:209], v[10:13]
	v_mfma_f32_16x16x32_bf16 v[62:65], v[110:113], v[170:173], v[62:65]
	v_mfma_f32_16x16x32_bf16 v[58:61], v[134:137], v[170:173], v[58:61]
	v_mfma_f32_16x16x32_bf16 v[46:49], v[110:113], v[178:181], v[46:49]
	v_mfma_f32_16x16x32_bf16 v[42:45], v[134:137], v[178:181], v[42:45]
	v_mfma_f32_16x16x32_bf16 v[30:33], v[110:113], v[202:205], v[30:33]
	v_mfma_f32_16x16x32_bf16 v[26:29], v[134:137], v[202:205], v[26:29]
	v_mfma_f32_16x16x32_bf16 v[14:17], v[110:113], v[210:213], v[14:17]
	v_mfma_f32_16x16x32_bf16 v[10:13], v[134:137], v[210:213], v[10:13]
	s_setprio 0
	s_setprio 1
	v_mfma_f32_16x16x32_bf16 v[54:57], v[138:141], v[166:169], v[54:57]
	v_mfma_f32_16x16x32_bf16 v[50:53], v[154:157], v[166:169], v[50:53]
	v_mfma_f32_16x16x32_bf16 v[38:41], v[138:141], v[174:177], v[38:41]
	v_mfma_f32_16x16x32_bf16 v[34:37], v[154:157], v[174:177], v[34:37]
	v_mfma_f32_16x16x32_bf16 v[22:25], v[138:141], v[198:201], v[22:25]
	v_mfma_f32_16x16x32_bf16 v[18:21], v[154:157], v[198:201], v[18:21]
	v_mfma_f32_16x16x32_bf16 v[6:9], v[138:141], v[206:209], v[6:9]
	v_mfma_f32_16x16x32_bf16 v[2:5], v[154:157], v[206:209], v[2:5]
	v_mfma_f32_16x16x32_bf16 v[54:57], v[150:153], v[170:173], v[54:57]
	v_mfma_f32_16x16x32_bf16 v[50:53], v[162:165], v[170:173], v[50:53]
	v_mfma_f32_16x16x32_bf16 v[38:41], v[150:153], v[178:181], v[38:41]
	v_mfma_f32_16x16x32_bf16 v[34:37], v[162:165], v[178:181], v[34:37]
	v_mfma_f32_16x16x32_bf16 v[22:25], v[150:153], v[202:205], v[22:25]
	v_mfma_f32_16x16x32_bf16 v[18:21], v[162:165], v[202:205], v[18:21]
	v_mfma_f32_16x16x32_bf16 v[6:9], v[150:153], v[210:213], v[6:9]
	v_mfma_f32_16x16x32_bf16 v[2:5], v[162:165], v[210:213], v[2:5]
	s_setprio 0
	s_barrier
	s_add_i32 vcc_hi, vcc_hi, 2
	s_add_u32 s27, s27, 0x100
	s_addc_u32 s71, s71, 0
	s_add_u32 s73, s73, 0x100
	s_addc_u32 vcc_lo, vcc_lo, 0
	s_add_u32 s80, s80, 0x100
	s_addc_u32 s81, s81, 0
	s_cmp_gt_u32 vcc_hi, 61
	s_cbranch_scc0 .LBB0_789
	s_and_b64 vcc, exec, s[68:69]
	s_cbranch_vccz .LBB0_792
	s_barrier

; #define PG8_STAGE(bufoff, gbase, voff) do { if constexpr (VAR != 1 && VAR != 3) { _Pragma("unroll") for (int _i = 0; _i < 2; ++_i) \
;         asm volatile("s_mov_b32 m0, %2\n\ts_nop 0\n\tglobal_load_lds_dwordx4 %0, %1" :: "v"((voff)[_i]), "s"((const char*)(gbase)), "s"(ldsbase + (unsigned)((bufoff) + _i * 8192)) : "memory", "m0"); } } while (0)
; #define PG8_LDA(dst, b, h) do { if constexpr (VAR < 2) _Pragma("unroll") for (int m = 0; m < 4; ++m) _Pragma("unroll") for (int k = 0; k < 2; ++k) dst[m][k] = *(const LAS bf16x8*)(lds + PG8_SA(b, h) + aoff + m * 2048 + k * 1024); } while (0)
; #define PG8_LDB(dst, b, h) do { if constexpr (VAR < 2) _Pragma("unroll") for (int n = 0; n < 2; ++n) _Pragma("unroll") for (int k = 0; k < 2; ++k) dst[n][k] = *(const LAS bf16x8*)(lds + PG8_SB(b, h) + boff + n * 2048 + k * 1024); } while (0)
; #define PG8_WAIT_V(n) asm volatile("s_waitcnt vmcnt(" #n ")" ::: "memory")
; #define PG8_WAIT_L(n) asm volatile("s_waitcnt lgkmcnt(" #n ")" ::: "memory")
; #define PG8_BAR do { if constexpr (VAR != 3) __builtin_amdgcn_s_barrier(); } while (0)
; #define PG8_SCHED __builtin_amdgcn_sched_barrier(0)
;     ...
;         for (int t = 0; t < nt; t += 2) {
;             const bool last = (t == nt - 2);
;             const char* a1 = cA + (size_t)(t + 1) * kstep;
;             const char* a2 = last ? nA : cA + (size_t)(t + 2) * kstep; const char* b2 = last ? nB : cB + (size_t)(t + 2) * kstep;
;             const char* a3 = a2 + kstep; const char* b3 = b2 + kstep;
;             PG8_LDB(B0, 0, 0); PG8_LDB(B1, 0, 1); PG8_SCHED; PG8_LDA(At, 0, 0); PG8_STAGE(PG8_SA(1, 1), a1 + hstepA, voffA);
;             PG8_WAIT_V(8); PG8_WAIT_L(0); PG8_BAR; PG8_MMA(0, 0, At, B0); PG8_MMA(0, 1, At, B1); PG8_BAR; PG8_SCHED;
;             PG8_LDA(At, 0, 1); PG8_STAGE(PG8_SB(0, 0), b2, voffB); PG8_STAGE(PG8_SB(0, 1), b2 + hstepB, voffB); PG8_STAGE(PG8_SA(0, 0), a2, voffA);
;             PG8_WAIT_V(8); PG8_WAIT_L(0); PG8_BAR; PG8_MMA(1, 0, At, B0); PG8_MMA(1, 1, At, B1); PG8_BAR; PG8_SCHED;
.LBB0_892:
	ds_read_b128 v[134:137], v201
	ds_read_b128 v[138:141], v201 offset:1024
	ds_read_b128 v[142:145], v201 offset:2048
	ds_read_b128 v[146:149], v201 offset:3072
	ds_read_b128 v[150:153], v202
	ds_read_b128 v[154:157], v202 offset:1024
	ds_read_b128 v[158:161], v202 offset:2048
	ds_read_b128 v[162:165], v202 offset:3072
	s_cmp_eq_u32 s85, 60
	s_cselect_b32 s72, s24, s25
	s_cselect_b32 s73, s1, s39
	s_cselect_b32 s70, s60, s59
	s_cselect_b32 s71, s61, s84
	s_add_u32 s68, s72, 0x80
	s_addc_u32 s69, s73, 0
	ds_read_b128 v[166:169], v203
	ds_read_b128 v[210:213], v203 offset:1024
	ds_read_b128 v[214:217], v203 offset:2048
	ds_read_b128 v[218:221], v203 offset:3072
	ds_read_b128 v[222:225], v203 offset:4096
	ds_read_b128 v[226:229], v203 offset:5120
	ds_read_b128 v[230:233], v203 offset:6144
	ds_read_b128 v[234:237], v203 offset:7168
	s_mov_b32 m0, s77
	s_nop 0
	global_load_lds_dwordx4 v1, s[6:7]
	s_mov_b32 m0, s79
	s_nop 0
	global_load_lds_dwordx4 v173, s[6:7]
	s_waitcnt vmcnt(8)
	s_waitcnt lgkmcnt(0)
	s_barrier
	s_setprio 1
	v_mfma_f32_16x16x32_bf16 v[126:129], v[134:137], v[166:169], v[126:129]
	v_mfma_f32_16x16x32_bf16 v[122:125], v[142:145], v[166:169], v[122:125]
	v_mfma_f32_16x16x32_bf16 v[110:113], v[134:137], v[214:217], v[110:113]
	v_mfma_f32_16x16x32_bf16 v[106:109], v[142:145], v[214:217], v[106:109]
	v_mfma_f32_16x16x32_bf16 v[94:97], v[134:137], v[222:225], v[94:97]
	v_mfma_f32_16x16x32_bf16 v[90:93], v[142:145], v[222:225], v[90:93]
	v_mfma_f32_16x16x32_bf16 v[78:81], v[134:137], v[230:233], v[78:81]
	v_mfma_f32_16x16x32_bf16 v[74:77], v[142:145], v[230:233], v[74:77]
	v_mfma_f32_16x16x32_bf16 v[126:129], v[138:141], v[210:213], v[126:129]
	v_mfma_f32_16x16x32_bf16 v[122:125], v[146:149], v[210:213], v[122:125]
	v_mfma_f32_16x16x32_bf16 v[110:113], v[138:141], v[218:221], v[110:113]
	v_mfma_f32_16x16x32_bf16 v[106:109], v[146:149], v[218:221], v[106:109]
	v_mfma_f32_16x16x32_bf16 v[94:97], v[138:141], v[226:229], v[94:97]
	v_mfma_f32_16x16x32_bf16 v[90:93], v[146:149], v[226:229], v[90:93]
	v_mfma_f32_16x16x32_bf16 v[78:81], v[138:141], v[234:237], v[78:81]
	v_mfma_f32_16x16x32_bf16 v[74:77], v[146:149], v[234:237], v[74:77]
	s_setprio 0
	s_setprio 1
	v_mfma_f32_16x16x32_bf16 v[118:121], v[150:153], v[166:169], v[118:121]
	v_mfma_f32_16x16x32_bf16 v[114:117], v[158:161], v[166:169], v[114:117]
	v_mfma_f32_16x16x32_bf16 v[102:105], v[150:153], v[214:217], v[102:105]
	v_mfma_f32_16x16x32_bf16 v[98:101], v[158:161], v[214:217], v[98:101]
	v_mfma_f32_16x16x32_bf16 v[86:89], v[150:153], v[222:225], v[86:89]
	v_mfma_f32_16x16x32_bf16 v[82:85], v[158:161], v[222:225], v[82:85]
	v_mfma_f32_16x16x32_bf16 v[70:73], v[150:153], v[230:233], v[70:73]
	v_mfma_f32_16x16x32_bf16 v[66:69], v[158:161], v[230:233], v[66:69]
	v_mfma_f32_16x16x32_bf16 v[118:121], v[154:157], v[210:213], v[118:121]
	v_mfma_f32_16x16x32_bf16 v[114:117], v[162:165], v[210:213], v[114:117]
	v_mfma_f32_16x16x32_bf16 v[102:105], v[154:157], v[218:221], v[102:105]
	v_mfma_f32_16x16x32_bf16 v[98:101], v[162:165], v[218:221], v[98:101]
	v_mfma_f32_16x16x32_bf16 v[86:89], v[154:157], v[226:229], v[86:89]
	v_mfma_f32_16x16x32_bf16 v[82:85], v[162:165], v[226:229], v[82:85]
	v_mfma_f32_16x16x32_bf16 v[70:73], v[154:157], v[234:237], v[70:73]
	v_mfma_f32_16x16x32_bf16 v[66:69], v[162:165], v[234:237], v[66:69]
	s_setprio 0
	s_barrier
	ds_read_b128 v[166:169], v203 offset:16384
	ds_read_b128 v[210:213], v203 offset:17408
	ds_read_b128 v[214:217], v203 offset:18432
	ds_read_b128 v[218:221], v203 offset:19456
	ds_read_b128 v[222:225], v203 offset:20480
	ds_read_b128 v[226:229], v203 offset:21504
	ds_read_b128 v[230:233], v203 offset:22528
	ds_read_b128 v[234:237], v203 offset:23552
	s_mov_b32 m0, s17
	s_nop 0
	global_load_lds_dwordx4 v172, s[70:71]
	s_add_u32 s86, s70, 0x100000
	s_mov_b32 m0, s19
	s_nop 0
	global_load_lds_dwordx4 v174, s[70:71]
	s_addc_u32 s87, s71, 0
	s_mov_b32 m0, s23
	s_nop 0
	global_load_lds_dwordx4 v172, s[86:87]
	s_mov_b32 m0, s26
	s_nop 0
	global_load_lds_dwordx4 v174, s[86:87]
	s_mov_b32 m0, s15
	s_nop 0
	global_load_lds_dwordx4 v1, s[72:73]
	s_mov_b32 m0, s27
	s_nop 0
	global_load_lds_dwordx4 v173, s[72:73]
	s_waitcnt vmcnt(8)
	s_waitcnt lgkmcnt(0)
	s_barrier
	s_setprio 1
	v_mfma_f32_16x16x32_bf16 v[62:65], v[134:137], v[166:169], v[62:65]
	v_mfma_f32_16x16x32_bf16 v[58:61], v[142:145], v[166:169], v[58:61]
	v_mfma_f32_16x16x32_bf16 v[46:49], v[134:137], v[214:217], v[46:49]
	v_mfma_f32_16x16x32_bf16 v[42:45], v[142:145], v[214:217], v[42:45]
	v_mfma_f32_16x16x32_bf16 v[30:33], v[134:137], v[222:225], v[30:33]
	v_mfma_f32_16x16x32_bf16 v[26:29], v[142:145], v[222:225], v[26:29]
	v_mfma_f32_16x16x32_bf16 v[14:17], v[134:137], v[230:233], v[14:17]
	v_mfma_f32_16x16x32_bf16 v[10:13], v[142:145], v[230:233], v[10:13]
	v_mfma_f32_16x16x32_bf16 v[62:65], v[138:141], v[210:213], v[62:65]
	v_mfma_f32_16x16x32_bf16 v[58:61], v[146:149], v[210:213], v[58:61]
	v_mfma_f32_16x16x32_bf16 v[46:49], v[138:141], v[218:221], v[46:49]
	v_mfma_f32_16x16x32_bf16 v[42:45], v[146:149], v[218:221], v[42:45]
	v_mfma_f32_16x16x32_bf16 v[30:33], v[138:141], v[226:229], v[30:33]
	v_mfma_f32_16x16x32_bf16 v[26:29], v[146:149], v[226:229], v[26:29]
	v_mfma_f32_16x16x32_bf16 v[14:17], v[138:141], v[234:237], v[14:17]
	v_mfma_f32_16x16x32_bf16 v[10:13], v[146:149], v[234:237], v[10:13]
	s_setprio 0
	s_setprio 1
	v_mfma_f32_16x16x32_bf16 v[54:57], v[150:153], v[166:169], v[54:57]
	v_mfma_f32_16x16x32_bf16 v[50:53], v[158:161], v[166:169], v[50:53]
	v_mfma_f32_16x16x32_bf16 v[38:41], v[150:153], v[214:217], v[38:41]
	v_mfma_f32_16x16x32_bf16 v[34:37], v[158:161], v[214:217], v[34:37]
	v_mfma_f32_16x16x32_bf16 v[22:25], v[150:153], v[222:225], v[22:25]
	v_mfma_f32_16x16x32_bf16 v[18:21], v[158:161], v[222:225], v[18:21]
	v_mfma_f32_16x16x32_bf16 v[6:9], v[150:153], v[230:233], v[6:9]
	v_mfma_f32_16x16x32_bf16 v[2:5], v[158:161], v[230:233], v[2:5]
	v_mfma_f32_16x16x32_bf16 v[54:57], v[154:157], v[210:213], v[54:57]
	v_mfma_f32_16x16x32_bf16 v[50:53], v[162:165], v[210:213], v[50:53]
	v_mfma_f32_16x16x32_bf16 v[38:41], v[154:157], v[218:221], v[38:41]
	v_mfma_f32_16x16x32_bf16 v[34:37], v[162:165], v[218:221], v[34:37]
	v_mfma_f32_16x16x32_bf16 v[22:25], v[154:157], v[226:229], v[22:25]
	v_mfma_f32_16x16x32_bf16 v[18:21], v[162:165], v[226:229], v[18:21]
	v_mfma_f32_16x16x32_bf16 v[6:9], v[154:157], v[234:237], v[6:9]
	v_mfma_f32_16x16x32_bf16 v[2:5], v[162:165], v[234:237], v[2:5]
	s_setprio 0
	s_barrier
; #define PG8_STAGE(bufoff, gbase, voff) do { if constexpr (VAR != 1 && VAR != 3) { _Pragma("unroll") for (int _i = 0; _i < 2; ++_i) \
;         asm volatile("s_mov_b32 m0, %2\n\ts_nop 0\n\tglobal_load_lds_dwordx4 %0, %1" :: "v"((voff)[_i]), "s"((const char*)(gbase)), "s"(ldsbase + (unsigned)((bufoff) + _i * 8192)) : "memory", "m0"); } } while (0)
; #define PG8_LDA(dst, b, h) do { if constexpr (VAR < 2) _Pragma("unroll") for (int m = 0; m < 4; ++m) _Pragma("unroll") for (int k = 0; k < 2; ++k) dst[m][k] = *(const LAS bf16x8*)(lds + PG8_SA(b, h) + aoff + m * 2048 + k * 1024); } while (0)
; #define PG8_LDB(dst, b, h) do { if constexpr (VAR < 2) _Pragma("unroll") for (int n = 0; n < 2; ++n) _Pragma("unroll") for (int k = 0; k < 2; ++k) dst[n][k] = *(const LAS bf16x8*)(lds + PG8_SB(b, h) + boff + n * 2048 + k * 1024); } while (0)
; #define PG8_WAIT_V(n) asm volatile("s_waitcnt vmcnt(" #n ")" ::: "memory")
; #define PG8_WAIT_L(n) asm volatile("s_waitcnt lgkmcnt(" #n ")" ::: "memory")
; #define PG8_BAR do { if constexpr (VAR != 3) __builtin_amdgcn_s_barrier(); } while (0)
; #define PG8_SCHED __builtin_amdgcn_sched_barrier(0)
;     ...
;             PG8_LDB(B0, 1, 0); PG8_LDB(B1, 1, 1); PG8_SCHED; PG8_LDA(At, 1, 0); PG8_STAGE(PG8_SA(0, 1), a2 + hstepA, voffA);
;             PG8_WAIT_V(8); PG8_WAIT_L(0); PG8_BAR; PG8_MMA(0, 0, At, B0); PG8_MMA(0, 1, At, B1); PG8_BAR; PG8_SCHED;
;             PG8_LDA(At, 1, 1); PG8_STAGE(PG8_SB(1, 0), b3, voffB); PG8_STAGE(PG8_SB(1, 1), b3 + hstepB, voffB); PG8_STAGE(PG8_SA(1, 0), a3, voffA);
;             PG8_WAIT_V(8); PG8_WAIT_L(0); PG8_BAR; PG8_MMA(1, 0, At, B0); PG8_MMA(1, 1, At, B1); PG8_BAR; PG8_SCHED;
;         }
	ds_read_b128 v[134:137], v204
	ds_read_b128 v[138:141], v204 offset:1024
	ds_read_b128 v[142:145], v204 offset:2048
	ds_read_b128 v[146:149], v204 offset:3072
	ds_read_b128 v[150:153], v205
	ds_read_b128 v[154:157], v205 offset:1024
	ds_read_b128 v[158:161], v205 offset:2048
	ds_read_b128 v[162:165], v205 offset:3072
	ds_read_b128 v[166:169], v203 offset:32768
	ds_read_b128 v[210:213], v203 offset:33792
	ds_read_b128 v[214:217], v203 offset:34816
	ds_read_b128 v[218:221], v203 offset:35840
	ds_read_b128 v[222:225], v203 offset:36864
	ds_read_b128 v[226:229], v203 offset:37888
	ds_read_b128 v[230:233], v203 offset:38912
	ds_read_b128 v[234:237], v203 offset:39936
	s_add_u32 s72, s72, 0x100000
	s_addc_u32 s73, s73, 0
	s_mov_b32 m0, s28
	s_nop 0
	global_load_lds_dwordx4 v1, s[72:73]
	s_mov_b32 m0, s29
	s_nop 0
	global_load_lds_dwordx4 v173, s[72:73]
	s_waitcnt vmcnt(8)
	s_waitcnt lgkmcnt(0)
	s_barrier
	s_setprio 1
	v_mfma_f32_16x16x32_bf16 v[126:129], v[134:137], v[166:169], v[126:129]
	v_mfma_f32_16x16x32_bf16 v[122:125], v[142:145], v[166:169], v[122:125]
	v_mfma_f32_16x16x32_bf16 v[110:113], v[134:137], v[214:217], v[110:113]
	v_mfma_f32_16x16x32_bf16 v[106:109], v[142:145], v[214:217], v[106:109]
	v_mfma_f32_16x16x32_bf16 v[94:97], v[134:137], v[222:225], v[94:97]
	v_mfma_f32_16x16x32_bf16 v[90:93], v[142:145], v[222:225], v[90:93]
	v_mfma_f32_16x16x32_bf16 v[78:81], v[134:137], v[230:233], v[78:81]
	v_mfma_f32_16x16x32_bf16 v[74:77], v[142:145], v[230:233], v[74:77]
	v_mfma_f32_16x16x32_bf16 v[126:129], v[138:141], v[210:213], v[126:129]
	v_mfma_f32_16x16x32_bf16 v[122:125], v[146:149], v[210:213], v[122:125]
	v_mfma_f32_16x16x32_bf16 v[110:113], v[138:141], v[218:221], v[110:113]
	v_mfma_f32_16x16x32_bf16 v[106:109], v[146:149], v[218:221], v[106:109]
	v_mfma_f32_16x16x32_bf16 v[94:97], v[138:141], v[226:229], v[94:97]
	v_mfma_f32_16x16x32_bf16 v[90:93], v[146:149], v[226:229], v[90:93]
	v_mfma_f32_16x16x32_bf16 v[78:81], v[138:141], v[234:237], v[78:81]
	v_mfma_f32_16x16x32_bf16 v[74:77], v[146:149], v[234:237], v[74:77]
	s_setprio 0
	s_setprio 1
	v_mfma_f32_16x16x32_bf16 v[118:121], v[150:153], v[166:169], v[118:121]
	v_mfma_f32_16x16x32_bf16 v[114:117], v[158:161], v[166:169], v[114:117]
	v_mfma_f32_16x16x32_bf16 v[102:105], v[150:153], v[214:217], v[102:105]
	v_mfma_f32_16x16x32_bf16 v[98:101], v[158:161], v[214:217], v[98:101]
	v_mfma_f32_16x16x32_bf16 v[86:89], v[150:153], v[222:225], v[86:89]
	v_mfma_f32_16x16x32_bf16 v[82:85], v[158:161], v[222:225], v[82:85]
	v_mfma_f32_16x16x32_bf16 v[70:73], v[150:153], v[230:233], v[70:73]
	v_mfma_f32_16x16x32_bf16 v[66:69], v[158:161], v[230:233], v[66:69]
	v_mfma_f32_16x16x32_bf16 v[118:121], v[154:157], v[210:213], v[118:121]
	v_mfma_f32_16x16x32_bf16 v[114:117], v[162:165], v[210:213], v[114:117]
	v_mfma_f32_16x16x32_bf16 v[102:105], v[154:157], v[218:221], v[102:105]
	v_mfma_f32_16x16x32_bf16 v[98:101], v[162:165], v[218:221], v[98:101]
	v_mfma_f32_16x16x32_bf16 v[86:89], v[154:157], v[226:229], v[86:89]
	v_mfma_f32_16x16x32_bf16 v[82:85], v[162:165], v[226:229], v[82:85]
	v_mfma_f32_16x16x32_bf16 v[70:73], v[154:157], v[234:237], v[70:73]
	v_mfma_f32_16x16x32_bf16 v[66:69], v[162:165], v[234:237], v[66:69]
	s_setprio 0
	s_barrier
	ds_read_b128 v[166:169], v203 offset:49152
	ds_read_b128 v[210:213], v203 offset:50176
	ds_read_b128 v[214:217], v203 offset:51200
	ds_read_b128 v[218:221], v203 offset:52224
	ds_read_b128 v[222:225], v203 offset:53248
	ds_read_b128 v[226:229], v203 offset:54272
	ds_read_b128 v[230:233], v203 offset:55296
	ds_read_b128 v[234:237], v203 offset:56320
	s_add_u32 s72, s70, 0x80
	s_addc_u32 s73, s71, 0
	s_mov_b32 m0, s33
	s_nop 0
	global_load_lds_dwordx4 v172, s[72:73]
	s_add_u32 s70, s70, 0x100080
	s_mov_b32 m0, s35
	s_nop 0
	global_load_lds_dwordx4 v174, s[72:73]
	s_addc_u32 s71, s71, 0
	s_mov_b32 m0, s75
	s_nop 0
	global_load_lds_dwordx4 v172, s[70:71]
	s_mov_b32 m0, s76
	s_nop 0
	global_load_lds_dwordx4 v174, s[70:71]
	s_mov_b32 m0, s67
	s_nop 0
	global_load_lds_dwordx4 v1, s[68:69]
	s_mov_b32 m0, s74
	s_nop 0
	global_load_lds_dwordx4 v173, s[68:69]
	s_waitcnt vmcnt(8)
	s_waitcnt lgkmcnt(0)
	s_barrier
	s_setprio 1
	v_mfma_f32_16x16x32_bf16 v[62:65], v[134:137], v[166:169], v[62:65]
	v_mfma_f32_16x16x32_bf16 v[58:61], v[142:145], v[166:169], v[58:61]
	v_mfma_f32_16x16x32_bf16 v[46:49], v[134:137], v[214:217], v[46:49]
	v_mfma_f32_16x16x32_bf16 v[42:45], v[142:145], v[214:217], v[42:45]
	v_mfma_f32_16x16x32_bf16 v[30:33], v[134:137], v[222:225], v[30:33]
	v_mfma_f32_16x16x32_bf16 v[26:29], v[142:145], v[222:225], v[26:29]
	v_mfma_f32_16x16x32_bf16 v[14:17], v[134:137], v[230:233], v[14:17]
	v_mfma_f32_16x16x32_bf16 v[10:13], v[142:145], v[230:233], v[10:13]
	v_mfma_f32_16x16x32_bf16 v[62:65], v[138:141], v[210:213], v[62:65]
	v_mfma_f32_16x16x32_bf16 v[58:61], v[146:149], v[210:213], v[58:61]
	v_mfma_f32_16x16x32_bf16 v[46:49], v[138:141], v[218:221], v[46:49]
	v_mfma_f32_16x16x32_bf16 v[42:45], v[146:149], v[218:221], v[42:45]
	v_mfma_f32_16x16x32_bf16 v[30:33], v[138:141], v[226:229], v[30:33]
	v_mfma_f32_16x16x32_bf16 v[26:29], v[146:149], v[226:229], v[26:29]
	v_mfma_f32_16x16x32_bf16 v[14:17], v[138:141], v[234:237], v[14:17]
	v_mfma_f32_16x16x32_bf16 v[10:13], v[146:149], v[234:237], v[10:13]
	s_setprio 0
	s_setprio 1
	v_mfma_f32_16x16x32_bf16 v[54:57], v[150:153], v[166:169], v[54:57]
	v_mfma_f32_16x16x32_bf16 v[50:53], v[158:161], v[166:169], v[50:53]
	v_mfma_f32_16x16x32_bf16 v[38:41], v[150:153], v[214:217], v[38:41]
	v_mfma_f32_16x16x32_bf16 v[34:37], v[158:161], v[214:217], v[34:37]
	v_mfma_f32_16x16x32_bf16 v[22:25], v[150:153], v[222:225], v[22:25]
	v_mfma_f32_16x16x32_bf16 v[18:21], v[158:161], v[222:225], v[18:21]
	v_mfma_f32_16x16x32_bf16 v[6:9], v[150:153], v[230:233], v[6:9]
	v_mfma_f32_16x16x32_bf16 v[2:5], v[158:161], v[230:233], v[2:5]
	v_mfma_f32_16x16x32_bf16 v[54:57], v[154:157], v[210:213], v[54:57]
	v_mfma_f32_16x16x32_bf16 v[50:53], v[162:165], v[210:213], v[50:53]
	v_mfma_f32_16x16x32_bf16 v[38:41], v[154:157], v[218:221], v[38:41]
	v_mfma_f32_16x16x32_bf16 v[34:37], v[162:165], v[218:221], v[34:37]
	v_mfma_f32_16x16x32_bf16 v[22:25], v[154:157], v[226:229], v[22:25]
	v_mfma_f32_16x16x32_bf16 v[18:21], v[162:165], v[226:229], v[18:21]
	v_mfma_f32_16x16x32_bf16 v[6:9], v[154:157], v[234:237], v[6:9]
	v_mfma_f32_16x16x32_bf16 v[2:5], v[162:165], v[234:237], v[2:5]
	s_setprio 0
	s_barrier
	s_add_i32 s85, s85, 2
	s_add_u32 s25, s25, 0x100
	s_addc_u32 s39, s39, 0
	s_add_u32 s59, s59, 0x100
	s_addc_u32 s84, s84, 0
	s_add_u32 s6, s6, 0x100
	s_addc_u32 s7, s7, 0
	s_cmp_gt_u32 s85, 61
	s_cbranch_scc0 .LBB0_892
	s_and_b64 vcc, exec, s[10:11]
	s_cbranch_vccz .LBB0_895
	s_barrier

; #define PG8_STAGE(bufoff, gbase, voff) do { if constexpr (VAR != 1 && VAR != 3) { _Pragma("unroll") for (int _i = 0; _i < 2; ++_i) \
;         asm volatile("s_mov_b32 m0, %2\n\ts_nop 0\n\tglobal_load_lds_dwordx4 %0, %1" :: "v"((voff)[_i]), "s"((const char*)(gbase)), "s"(ldsbase + (unsigned)((bufoff) + _i * 8192)) : "memory", "m0"); } } while (0)
; #define PG8_LDA(dst, b, h) do { if constexpr (VAR < 2) _Pragma("unroll") for (int m = 0; m < 4; ++m) _Pragma("unroll") for (int k = 0; k < 2; ++k) dst[m][k] = *(const LAS bf16x8*)(lds + PG8_SA(b, h) + aoff + m * 2048 + k * 1024); } while (0)
; #define PG8_LDB(dst, b, h) do { if constexpr (VAR < 2) _Pragma("unroll") for (int n = 0; n < 2; ++n) _Pragma("unroll") for (int k = 0; k < 2; ++k) dst[n][k] = *(const LAS bf16x8*)(lds + PG8_SB(b, h) + boff + n * 2048 + k * 1024); } while (0)
; #define PG8_WAIT_V(n) asm volatile("s_waitcnt vmcnt(" #n ")" ::: "memory")
; #define PG8_WAIT_L(n) asm volatile("s_waitcnt lgkmcnt(" #n ")" ::: "memory")
; #define PG8_BAR do { if constexpr (VAR != 3) __builtin_amdgcn_s_barrier(); } while (0)
; #define PG8_SCHED __builtin_amdgcn_sched_barrier(0)
;     ...
;         for (int t = 0; t < nt; t += 2) {
;             const bool last = (t == nt - 2);
;             const char* a1 = cA + (size_t)(t + 1) * kstep;
;             const char* a2 = last ? nA : cA + (size_t)(t + 2) * kstep; const char* b2 = last ? nB : cB + (size_t)(t + 2) * kstep;
;             const char* a3 = a2 + kstep; const char* b3 = b2 + kstep;
;             PG8_LDB(B0, 0, 0); PG8_LDB(B1, 0, 1); PG8_SCHED; PG8_LDA(At, 0, 0); PG8_STAGE(PG8_SA(1, 1), a1 + hstepA, voffA);
;             PG8_WAIT_V(8); PG8_WAIT_L(0); PG8_BAR; PG8_MMA(0, 0, At, B0); PG8_MMA(0, 1, At, B1); PG8_BAR; PG8_SCHED;
;             PG8_LDA(At, 0, 1); PG8_STAGE(PG8_SB(0, 0), b2, voffB); PG8_STAGE(PG8_SB(0, 1), b2 + hstepB, voffB); PG8_STAGE(PG8_SA(0, 0), a2, voffA);
;             PG8_WAIT_V(8); PG8_WAIT_L(0); PG8_BAR; PG8_MMA(1, 0, At, B0); PG8_MMA(1, 1, At, B1); PG8_BAR; PG8_SCHED;
.LBB0_1002:
	ds_read_b128 v[130:133], v183
	ds_read_b128 v[134:137], v183 offset:1024
	ds_read_b128 v[138:141], v183 offset:2048
	ds_read_b128 v[142:145], v183 offset:3072
	ds_read_b128 v[146:149], v184
	ds_read_b128 v[150:153], v184 offset:1024
	ds_read_b128 v[154:157], v184 offset:2048
	ds_read_b128 v[162:165], v184 offset:3072
	s_cmp_eq_u32 s86, 12
	s_cselect_b32 s78, s25, s63
	s_cselect_b32 s79, s24, s65
	s_cselect_b32 s76, s66, s84
	s_cselect_b32 s77, s67, s85
	s_add_u32 s74, s78, 0x80
	s_addc_u32 s75, s79, 0
	ds_read_b128 v[166:169], v185
	ds_read_b128 v[170:173], v185 offset:1024
	ds_read_b128 v[190:193], v185 offset:2048
	ds_read_b128 v[194:197], v185 offset:3072
	ds_read_b128 v[198:201], v185 offset:4096
	ds_read_b128 v[202:205], v185 offset:5120
	ds_read_b128 v[206:209], v185 offset:6144
	ds_read_b128 v[210:213], v185 offset:7168
	s_mov_b32 m0, s82
	s_nop 0
	global_load_lds_dwordx4 v176, s[12:13]
	s_mov_b32 m0, s83
	s_nop 0
	global_load_lds_dwordx4 v178, s[12:13]
	s_waitcnt vmcnt(8)
	s_waitcnt lgkmcnt(0)
	s_barrier
	s_setprio 1
	v_mfma_f32_16x16x32_bf16 v[126:129], v[130:133], v[166:169], v[126:129]
	v_mfma_f32_16x16x32_bf16 v[122:125], v[138:141], v[166:169], v[122:125]
	v_mfma_f32_16x16x32_bf16 v[110:113], v[130:133], v[190:193], v[110:113]
	v_mfma_f32_16x16x32_bf16 v[106:109], v[138:141], v[190:193], v[106:109]
	v_mfma_f32_16x16x32_bf16 v[94:97], v[130:133], v[198:201], v[94:97]
	v_mfma_f32_16x16x32_bf16 v[90:93], v[138:141], v[198:201], v[90:93]
	v_mfma_f32_16x16x32_bf16 v[78:81], v[130:133], v[206:209], v[78:81]
	v_mfma_f32_16x16x32_bf16 v[74:77], v[138:141], v[206:209], v[74:77]
	v_mfma_f32_16x16x32_bf16 v[126:129], v[134:137], v[170:173], v[126:129]
	v_mfma_f32_16x16x32_bf16 v[122:125], v[142:145], v[170:173], v[122:125]
	v_mfma_f32_16x16x32_bf16 v[110:113], v[134:137], v[194:197], v[110:113]
	v_mfma_f32_16x16x32_bf16 v[106:109], v[142:145], v[194:197], v[106:109]
	v_mfma_f32_16x16x32_bf16 v[94:97], v[134:137], v[202:205], v[94:97]
	v_mfma_f32_16x16x32_bf16 v[90:93], v[142:145], v[202:205], v[90:93]
	v_mfma_f32_16x16x32_bf16 v[78:81], v[134:137], v[210:213], v[78:81]
	v_mfma_f32_16x16x32_bf16 v[74:77], v[142:145], v[210:213], v[74:77]
	s_setprio 0
	s_setprio 1
	v_mfma_f32_16x16x32_bf16 v[118:121], v[146:149], v[166:169], v[118:121]
	v_mfma_f32_16x16x32_bf16 v[114:117], v[154:157], v[166:169], v[114:117]
	v_mfma_f32_16x16x32_bf16 v[102:105], v[146:149], v[190:193], v[102:105]
	v_mfma_f32_16x16x32_bf16 v[98:101], v[154:157], v[190:193], v[98:101]
	v_mfma_f32_16x16x32_bf16 v[86:89], v[146:149], v[198:201], v[86:89]
	v_mfma_f32_16x16x32_bf16 v[82:85], v[154:157], v[198:201], v[82:85]
	v_mfma_f32_16x16x32_bf16 v[70:73], v[146:149], v[206:209], v[70:73]
	v_mfma_f32_16x16x32_bf16 v[66:69], v[154:157], v[206:209], v[66:69]
	v_mfma_f32_16x16x32_bf16 v[118:121], v[150:153], v[170:173], v[118:121]
	v_mfma_f32_16x16x32_bf16 v[114:117], v[162:165], v[170:173], v[114:117]
	v_mfma_f32_16x16x32_bf16 v[102:105], v[150:153], v[194:197], v[102:105]
	v_mfma_f32_16x16x32_bf16 v[98:101], v[162:165], v[194:197], v[98:101]
	v_mfma_f32_16x16x32_bf16 v[86:89], v[150:153], v[202:205], v[86:89]
	v_mfma_f32_16x16x32_bf16 v[82:85], v[162:165], v[202:205], v[82:85]
	v_mfma_f32_16x16x32_bf16 v[70:73], v[150:153], v[210:213], v[70:73]
	v_mfma_f32_16x16x32_bf16 v[66:69], v[162:165], v[210:213], v[66:69]
	s_setprio 0
	s_barrier
	ds_read_b128 v[166:169], v185 offset:16384
	ds_read_b128 v[170:173], v185 offset:17408
	ds_read_b128 v[190:193], v185 offset:18432
	ds_read_b128 v[194:197], v185 offset:19456
	ds_read_b128 v[198:201], v185 offset:20480
	ds_read_b128 v[202:205], v185 offset:21504
	ds_read_b128 v[206:209], v185 offset:22528
	ds_read_b128 v[210:213], v185 offset:23552
	s_mov_b32 m0, s17
	s_nop 0
	global_load_lds_dwordx4 v177, s[76:77]
	s_add_u32 s88, s76, 0x40000
	s_mov_b32 m0, s19
	s_nop 0
	global_load_lds_dwordx4 v179, s[76:77]
	s_addc_u32 s89, s77, 0
	s_mov_b32 m0, s23
	s_nop 0
	global_load_lds_dwordx4 v177, s[88:89]
	s_mov_b32 m0, s26
	s_nop 0
	global_load_lds_dwordx4 v179, s[88:89]
	s_mov_b32 m0, s15
	s_nop 0
	global_load_lds_dwordx4 v176, s[78:79]
	s_mov_b32 m0, s27
	s_nop 0
	global_load_lds_dwordx4 v178, s[78:79]
	s_waitcnt vmcnt(8)
	s_waitcnt lgkmcnt(0)
	s_barrier
	s_setprio 1
	v_mfma_f32_16x16x32_bf16 v[62:65], v[130:133], v[166:169], v[62:65]
	v_mfma_f32_16x16x32_bf16 v[58:61], v[138:141], v[166:169], v[58:61]
	v_mfma_f32_16x16x32_bf16 v[46:49], v[130:133], v[190:193], v[46:49]
	v_mfma_f32_16x16x32_bf16 v[42:45], v[138:141], v[190:193], v[42:45]
	v_mfma_f32_16x16x32_bf16 v[30:33], v[130:133], v[198:201], v[30:33]
	v_mfma_f32_16x16x32_bf16 v[26:29], v[138:141], v[198:201], v[26:29]
	v_mfma_f32_16x16x32_bf16 v[14:17], v[130:133], v[206:209], v[14:17]
	v_mfma_f32_16x16x32_bf16 v[10:13], v[138:141], v[206:209], v[10:13]
	v_mfma_f32_16x16x32_bf16 v[62:65], v[134:137], v[170:173], v[62:65]
	v_mfma_f32_16x16x32_bf16 v[58:61], v[142:145], v[170:173], v[58:61]
	v_mfma_f32_16x16x32_bf16 v[46:49], v[134:137], v[194:197], v[46:49]
	v_mfma_f32_16x16x32_bf16 v[42:45], v[142:145], v[194:197], v[42:45]
	v_mfma_f32_16x16x32_bf16 v[30:33], v[134:137], v[202:205], v[30:33]
	v_mfma_f32_16x16x32_bf16 v[26:29], v[142:145], v[202:205], v[26:29]
	v_mfma_f32_16x16x32_bf16 v[14:17], v[134:137], v[210:213], v[14:17]
	v_mfma_f32_16x16x32_bf16 v[10:13], v[142:145], v[210:213], v[10:13]
	s_setprio 0
	s_setprio 1
	v_mfma_f32_16x16x32_bf16 v[54:57], v[146:149], v[166:169], v[54:57]
	v_mfma_f32_16x16x32_bf16 v[50:53], v[154:157], v[166:169], v[50:53]
	v_mfma_f32_16x16x32_bf16 v[38:41], v[146:149], v[190:193], v[38:41]
	v_mfma_f32_16x16x32_bf16 v[34:37], v[154:157], v[190:193], v[34:37]
	v_mfma_f32_16x16x32_bf16 v[22:25], v[146:149], v[198:201], v[22:25]
	v_mfma_f32_16x16x32_bf16 v[18:21], v[154:157], v[198:201], v[18:21]
	v_mfma_f32_16x16x32_bf16 v[6:9], v[146:149], v[206:209], v[6:9]
	v_mfma_f32_16x16x32_bf16 v[2:5], v[154:157], v[206:209], v[2:5]
	v_mfma_f32_16x16x32_bf16 v[54:57], v[150:153], v[170:173], v[54:57]
	v_mfma_f32_16x16x32_bf16 v[50:53], v[162:165], v[170:173], v[50:53]
	v_mfma_f32_16x16x32_bf16 v[38:41], v[150:153], v[194:197], v[38:41]
	v_mfma_f32_16x16x32_bf16 v[34:37], v[162:165], v[194:197], v[34:37]
	v_mfma_f32_16x16x32_bf16 v[22:25], v[150:153], v[202:205], v[22:25]
	v_mfma_f32_16x16x32_bf16 v[18:21], v[162:165], v[202:205], v[18:21]
	v_mfma_f32_16x16x32_bf16 v[6:9], v[150:153], v[210:213], v[6:9]
	v_mfma_f32_16x16x32_bf16 v[2:5], v[162:165], v[210:213], v[2:5]
	s_setprio 0
	s_barrier
; #define PG8_STAGE(bufoff, gbase, voff) do { if constexpr (VAR != 1 && VAR != 3) { _Pragma("unroll") for (int _i = 0; _i < 2; ++_i) \
;         asm volatile("s_mov_b32 m0, %2\n\ts_nop 0\n\tglobal_load_lds_dwordx4 %0, %1" :: "v"((voff)[_i]), "s"((const char*)(gbase)), "s"(ldsbase + (unsigned)((bufoff) + _i * 8192)) : "memory", "m0"); } } while (0)
; #define PG8_LDA(dst, b, h) do { if constexpr (VAR < 2) _Pragma("unroll") for (int m = 0; m < 4; ++m) _Pragma("unroll") for (int k = 0; k < 2; ++k) dst[m][k] = *(const LAS bf16x8*)(lds + PG8_SA(b, h) + aoff + m * 2048 + k * 1024); } while (0)
; #define PG8_LDB(dst, b, h) do { if constexpr (VAR < 2) _Pragma("unroll") for (int n = 0; n < 2; ++n) _Pragma("unroll") for (int k = 0; k < 2; ++k) dst[n][k] = *(const LAS bf16x8*)(lds + PG8_SB(b, h) + boff + n * 2048 + k * 1024); } while (0)
; #define PG8_WAIT_V(n) asm volatile("s_waitcnt vmcnt(" #n ")" ::: "memory")
; #define PG8_WAIT_L(n) asm volatile("s_waitcnt lgkmcnt(" #n ")" ::: "memory")
; #define PG8_BAR do { if constexpr (VAR != 3) __builtin_amdgcn_s_barrier(); } while (0)
; #define PG8_SCHED __builtin_amdgcn_sched_barrier(0)
;     ...
;             PG8_LDB(B0, 1, 0); PG8_LDB(B1, 1, 1); PG8_SCHED; PG8_LDA(At, 1, 0); PG8_STAGE(PG8_SA(0, 1), a2 + hstepA, voffA);
;             PG8_WAIT_V(8); PG8_WAIT_L(0); PG8_BAR; PG8_MMA(0, 0, At, B0); PG8_MMA(0, 1, At, B1); PG8_BAR; PG8_SCHED;
;             PG8_LDA(At, 1, 1); PG8_STAGE(PG8_SB(1, 0), b3, voffB); PG8_STAGE(PG8_SB(1, 1), b3 + hstepB, voffB); PG8_STAGE(PG8_SA(1, 0), a3, voffA);
;             PG8_WAIT_V(8); PG8_WAIT_L(0); PG8_BAR; PG8_MMA(1, 0, At, B0); PG8_MMA(1, 1, At, B1); PG8_BAR; PG8_SCHED;
;         }
	ds_read_b128 v[130:133], v186
	ds_read_b128 v[134:137], v186 offset:1024
	ds_read_b128 v[138:141], v186 offset:2048
	ds_read_b128 v[142:145], v186 offset:3072
	ds_read_b128 v[146:149], v187
	ds_read_b128 v[150:153], v187 offset:1024
	ds_read_b128 v[154:157], v187 offset:2048
	ds_read_b128 v[162:165], v187 offset:3072
	ds_read_b128 v[166:169], v185 offset:32768
	ds_read_b128 v[170:173], v185 offset:33792
	ds_read_b128 v[190:193], v185 offset:34816
	ds_read_b128 v[194:197], v185 offset:35840
	ds_read_b128 v[198:201], v185 offset:36864
	ds_read_b128 v[202:205], v185 offset:37888
	ds_read_b128 v[206:209], v185 offset:38912
	ds_read_b128 v[210:213], v185 offset:39936
	s_add_u32 s78, s78, 0x40000
	s_addc_u32 s79, s79, 0
	s_mov_b32 m0, s28
	s_nop 0
	global_load_lds_dwordx4 v176, s[78:79]
	s_mov_b32 m0, s29
	s_nop 0
	global_load_lds_dwordx4 v178, s[78:79]
	s_waitcnt vmcnt(8)
	s_waitcnt lgkmcnt(0)
	s_barrier
	s_setprio 1
	v_mfma_f32_16x16x32_bf16 v[126:129], v[130:133], v[166:169], v[126:129]
	v_mfma_f32_16x16x32_bf16 v[122:125], v[138:141], v[166:169], v[122:125]
	v_mfma_f32_16x16x32_bf16 v[110:113], v[130:133], v[190:193], v[110:113]
	v_mfma_f32_16x16x32_bf16 v[106:109], v[138:141], v[190:193], v[106:109]
	v_mfma_f32_16x16x32_bf16 v[94:97], v[130:133], v[198:201], v[94:97]
	v_mfma_f32_16x16x32_bf16 v[90:93], v[138:141], v[198:201], v[90:93]
	v_mfma_f32_16x16x32_bf16 v[78:81], v[130:133], v[206:209], v[78:81]
	v_mfma_f32_16x16x32_bf16 v[74:77], v[138:141], v[206:209], v[74:77]
	v_mfma_f32_16x16x32_bf16 v[126:129], v[134:137], v[170:173], v[126:129]
	v_mfma_f32_16x16x32_bf16 v[122:125], v[142:145], v[170:173], v[122:125]
	v_mfma_f32_16x16x32_bf16 v[110:113], v[134:137], v[194:197], v[110:113]
	v_mfma_f32_16x16x32_bf16 v[106:109], v[142:145], v[194:197], v[106:109]
	v_mfma_f32_16x16x32_bf16 v[94:97], v[134:137], v[202:205], v[94:97]
	v_mfma_f32_16x16x32_bf16 v[90:93], v[142:145], v[202:205], v[90:93]
	v_mfma_f32_16x16x32_bf16 v[78:81], v[134:137], v[210:213], v[78:81]
	v_mfma_f32_16x16x32_bf16 v[74:77], v[142:145], v[210:213], v[74:77]
	s_setprio 0
	s_setprio 1
	v_mfma_f32_16x16x32_bf16 v[118:121], v[146:149], v[166:169], v[118:121]
	v_mfma_f32_16x16x32_bf16 v[114:117], v[154:157], v[166:169], v[114:117]
	v_mfma_f32_16x16x32_bf16 v[102:105], v[146:149], v[190:193], v[102:105]
	v_mfma_f32_16x16x32_bf16 v[98:101], v[154:157], v[190:193], v[98:101]
	v_mfma_f32_16x16x32_bf16 v[86:89], v[146:149], v[198:201], v[86:89]
	v_mfma_f32_16x16x32_bf16 v[82:85], v[154:157], v[198:201], v[82:85]
	v_mfma_f32_16x16x32_bf16 v[70:73], v[146:149], v[206:209], v[70:73]
	v_mfma_f32_16x16x32_bf16 v[66:69], v[154:157], v[206:209], v[66:69]
	v_mfma_f32_16x16x32_bf16 v[118:121], v[150:153], v[170:173], v[118:121]
	v_mfma_f32_16x16x32_bf16 v[114:117], v[162:165], v[170:173], v[114:117]
	v_mfma_f32_16x16x32_bf16 v[102:105], v[150:153], v[194:197], v[102:105]
	v_mfma_f32_16x16x32_bf16 v[98:101], v[162:165], v[194:197], v[98:101]
	v_mfma_f32_16x16x32_bf16 v[86:89], v[150:153], v[202:205], v[86:89]
	v_mfma_f32_16x16x32_bf16 v[82:85], v[162:165], v[202:205], v[82:85]
	v_mfma_f32_16x16x32_bf16 v[70:73], v[150:153], v[210:213], v[70:73]
	v_mfma_f32_16x16x32_bf16 v[66:69], v[162:165], v[210:213], v[66:69]
	s_setprio 0
	s_barrier
	ds_read_b128 v[166:169], v185 offset:49152
	ds_read_b128 v[170:173], v185 offset:50176
	ds_read_b128 v[190:193], v185 offset:51200
	ds_read_b128 v[194:197], v185 offset:52224
	ds_read_b128 v[198:201], v185 offset:53248
	ds_read_b128 v[202:205], v185 offset:54272
	ds_read_b128 v[206:209], v185 offset:55296
	ds_read_b128 v[210:213], v185 offset:56320
	s_add_u32 s78, s76, 0x80
	s_addc_u32 s79, s77, 0
	s_mov_b32 m0, s33
	s_nop 0
	global_load_lds_dwordx4 v177, s[78:79]
	s_add_u32 s76, s76, 0x40080
	s_mov_b32 m0, s35
	s_nop 0
	global_load_lds_dwordx4 v179, s[78:79]
	s_addc_u32 s77, s77, 0
	s_mov_b32 m0, s80
	s_nop 0
	global_load_lds_dwordx4 v177, s[76:77]
	s_mov_b32 m0, s81
	s_nop 0
	global_load_lds_dwordx4 v179, s[76:77]
	s_mov_b32 m0, s71
	s_nop 0
	global_load_lds_dwordx4 v176, s[74:75]
	s_mov_b32 m0, s73
	s_nop 0
	global_load_lds_dwordx4 v178, s[74:75]
	s_waitcnt vmcnt(8)
	s_waitcnt lgkmcnt(0)
	s_barrier
	s_setprio 1
	v_mfma_f32_16x16x32_bf16 v[62:65], v[130:133], v[166:169], v[62:65]
	v_mfma_f32_16x16x32_bf16 v[58:61], v[138:141], v[166:169], v[58:61]
	v_mfma_f32_16x16x32_bf16 v[46:49], v[130:133], v[190:193], v[46:49]
	v_mfma_f32_16x16x32_bf16 v[42:45], v[138:141], v[190:193], v[42:45]
	v_mfma_f32_16x16x32_bf16 v[30:33], v[130:133], v[198:201], v[30:33]
	v_mfma_f32_16x16x32_bf16 v[26:29], v[138:141], v[198:201], v[26:29]
	v_mfma_f32_16x16x32_bf16 v[14:17], v[130:133], v[206:209], v[14:17]
	v_mfma_f32_16x16x32_bf16 v[10:13], v[138:141], v[206:209], v[10:13]
	v_mfma_f32_16x16x32_bf16 v[62:65], v[134:137], v[170:173], v[62:65]
	v_mfma_f32_16x16x32_bf16 v[58:61], v[142:145], v[170:173], v[58:61]
	v_mfma_f32_16x16x32_bf16 v[46:49], v[134:137], v[194:197], v[46:49]
	v_mfma_f32_16x16x32_bf16 v[42:45], v[142:145], v[194:197], v[42:45]
	v_mfma_f32_16x16x32_bf16 v[30:33], v[134:137], v[202:205], v[30:33]
	v_mfma_f32_16x16x32_bf16 v[26:29], v[142:145], v[202:205], v[26:29]
	v_mfma_f32_16x16x32_bf16 v[14:17], v[134:137], v[210:213], v[14:17]
	v_mfma_f32_16x16x32_bf16 v[10:13], v[142:145], v[210:213], v[10:13]
	s_setprio 0
	s_setprio 1
	v_mfma_f32_16x16x32_bf16 v[54:57], v[146:149], v[166:169], v[54:57]
	v_mfma_f32_16x16x32_bf16 v[50:53], v[154:157], v[166:169], v[50:53]
	v_mfma_f32_16x16x32_bf16 v[38:41], v[146:149], v[190:193], v[38:41]
	v_mfma_f32_16x16x32_bf16 v[34:37], v[154:157], v[190:193], v[34:37]
	v_mfma_f32_16x16x32_bf16 v[22:25], v[146:149], v[198:201], v[22:25]
	v_mfma_f32_16x16x32_bf16 v[18:21], v[154:157], v[198:201], v[18:21]
	v_mfma_f32_16x16x32_bf16 v[6:9], v[146:149], v[206:209], v[6:9]
	v_mfma_f32_16x16x32_bf16 v[2:5], v[154:157], v[206:209], v[2:5]
	v_mfma_f32_16x16x32_bf16 v[54:57], v[150:153], v[170:173], v[54:57]
	v_mfma_f32_16x16x32_bf16 v[50:53], v[162:165], v[170:173], v[50:53]
	v_mfma_f32_16x16x32_bf16 v[38:41], v[150:153], v[194:197], v[38:41]
	v_mfma_f32_16x16x32_bf16 v[34:37], v[162:165], v[194:197], v[34:37]
	v_mfma_f32_16x16x32_bf16 v[22:25], v[150:153], v[202:205], v[22:25]
	v_mfma_f32_16x16x32_bf16 v[18:21], v[162:165], v[202:205], v[18:21]
	v_mfma_f32_16x16x32_bf16 v[6:9], v[150:153], v[210:213], v[6:9]
	v_mfma_f32_16x16x32_bf16 v[2:5], v[162:165], v[210:213], v[2:5]
	s_setprio 0
	s_barrier
	s_add_i32 s86, s86, 2
	s_add_u32 s63, s63, 0x100
	s_addc_u32 s65, s65, 0
	s_add_u32 s84, s84, 0x100
	s_addc_u32 s85, s85, 0
	s_add_u32 s12, s12, 0x100
	s_addc_u32 s13, s13, 0
	s_cmp_gt_u32 s86, 13
	s_cbranch_scc0 .LBB0_1002
	s_and_b64 vcc, exec, s[60:61]
	s_cbranch_vccz .LBB0_1005
	s_barrier

; #define PG8_STAGE(bufoff, gbase, voff) do { if constexpr (VAR != 1 && VAR != 3) { _Pragma("unroll") for (int _i = 0; _i < 2; ++_i) \
;         asm volatile("s_mov_b32 m0, %2\n\ts_nop 0\n\tglobal_load_lds_dwordx4 %0, %1" :: "v"((voff)[_i]), "s"((const char*)(gbase)), "s"(ldsbase + (unsigned)((bufoff) + _i * 8192)) : "memory", "m0"); } } while (0)
; #define PG8_LDA(dst, b, h) do { if constexpr (VAR < 2) _Pragma("unroll") for (int m = 0; m < 4; ++m) _Pragma("unroll") for (int k = 0; k < 2; ++k) dst[m][k] = *(const LAS bf16x8*)(lds + PG8_SA(b, h) + aoff + m * 2048 + k * 1024); } while (0)
; #define PG8_LDB(dst, b, h) do { if constexpr (VAR < 2) _Pragma("unroll") for (int n = 0; n < 2; ++n) _Pragma("unroll") for (int k = 0; k < 2; ++k) dst[n][k] = *(const LAS bf16x8*)(lds + PG8_SB(b, h) + boff + n * 2048 + k * 1024); } while (0)
; #define PG8_WAIT_V(n) asm volatile("s_waitcnt vmcnt(" #n ")" ::: "memory")
; #define PG8_WAIT_L(n) asm volatile("s_waitcnt lgkmcnt(" #n ")" ::: "memory")
; #define PG8_BAR do { if constexpr (VAR != 3) __builtin_amdgcn_s_barrier(); } while (0)
; #define PG8_SCHED __builtin_amdgcn_sched_barrier(0)
;     ...
;         for (int t = 0; t < nt; t += 2) {
;             const bool last = (t == nt - 2);
;             const char* a1 = cA + (size_t)(t + 1) * kstep;
;             const char* a2 = last ? nA : cA + (size_t)(t + 2) * kstep; const char* b2 = last ? nB : cB + (size_t)(t + 2) * kstep;
;             const char* a3 = a2 + kstep; const char* b3 = b2 + kstep;
;             PG8_LDB(B0, 0, 0); PG8_LDB(B1, 0, 1); PG8_SCHED; PG8_LDA(At, 0, 0); PG8_STAGE(PG8_SA(1, 1), a1 + hstepA, voffA);
;             PG8_WAIT_V(8); PG8_WAIT_L(0); PG8_BAR; PG8_MMA(0, 0, At, B0); PG8_MMA(0, 1, At, B1); PG8_BAR; PG8_SCHED;
;             PG8_LDA(At, 0, 1); PG8_STAGE(PG8_SB(0, 0), b2, voffB); PG8_STAGE(PG8_SB(0, 1), b2 + hstepB, voffB); PG8_STAGE(PG8_SA(0, 0), a2, voffA);
;             PG8_WAIT_V(8); PG8_WAIT_L(0); PG8_BAR; PG8_MMA(1, 0, At, B0); PG8_MMA(1, 1, At, B1); PG8_BAR; PG8_SCHED;
.LBB0_1191:
	ds_read_b128 v[2:5], v231
	ds_read_b128 v[6:9], v231 offset:1024
	ds_read_b128 v[10:13], v231 offset:2048
	ds_read_b128 v[14:17], v231 offset:3072
	ds_read_b128 v[18:21], v232
	ds_read_b128 v[26:29], v232 offset:1024
	ds_read_b128 v[154:157], v232 offset:2048
	ds_read_b128 v[158:161], v232 offset:3072
	s_cmp_eq_u32 s71, 28
	s_cselect_b32 s82, s72, s25
	s_cselect_b32 s83, s73, s26
	s_cselect_b32 s80, s24, s27
	s_cselect_b32 s81, s11, s69
	s_add_u32 s78, s82, 0x80
	s_addc_u32 s79, s83, 0
	ds_read_b128 v[162:165], v233
	ds_read_b128 v[166:169], v233 offset:1024
	ds_read_b128 v[178:181], v233 offset:2048
	ds_read_b128 v[182:185], v233 offset:3072
	ds_read_b128 v[186:189], v233 offset:4096
	ds_read_b128 v[190:193], v233 offset:5120
	ds_read_b128 v[194:197], v233 offset:6144
	ds_read_b128 v[198:201], v233 offset:7168
	s_mov_b32 m0, s90
	s_nop 0
	global_load_lds_dwordx4 v208, s[0:1]
	s_mov_b32 m0, s91
	s_nop 0
	global_load_lds_dwordx4 v210, s[0:1]
	s_waitcnt vmcnt(8)
	s_waitcnt lgkmcnt(0)
	s_barrier
	s_setprio 1
	v_mfma_i32_16x16x64_i8 v[150:153], v[2:5], v[162:165], v[150:153]
	v_mfma_i32_16x16x64_i8 v[142:145], v[10:13], v[162:165], v[142:145]
	v_mfma_i32_16x16x64_i8 v[126:129], v[2:5], v[178:181], v[126:129]
	v_mfma_i32_16x16x64_i8 v[122:125], v[10:13], v[178:181], v[122:125]
	v_mfma_i32_16x16x64_i8 v[114:117], v[2:5], v[186:189], v[114:117]
	v_mfma_i32_16x16x64_i8 v[106:109], v[10:13], v[186:189], v[106:109]
	v_mfma_i32_16x16x64_i8 v[146:149], v[2:5], v[194:197], v[146:149]
	v_mfma_i32_16x16x64_i8 v[138:141], v[10:13], v[194:197], v[138:141]
	v_mfma_i32_16x16x64_i8 v[150:153], v[6:9], v[166:169], v[150:153]
	v_mfma_i32_16x16x64_i8 v[142:145], v[14:17], v[166:169], v[142:145]
	v_mfma_i32_16x16x64_i8 v[126:129], v[6:9], v[182:185], v[126:129]
	v_mfma_i32_16x16x64_i8 v[122:125], v[14:17], v[182:185], v[122:125]
	v_mfma_i32_16x16x64_i8 v[114:117], v[6:9], v[190:193], v[114:117]
	v_mfma_i32_16x16x64_i8 v[106:109], v[14:17], v[190:193], v[106:109]
	v_mfma_i32_16x16x64_i8 v[146:149], v[6:9], v[198:201], v[146:149]
	v_mfma_i32_16x16x64_i8 v[138:141], v[14:17], v[198:201], v[138:141]
	s_setprio 0
	s_setprio 1
	v_mfma_i32_16x16x64_i8 v[134:137], v[18:21], v[162:165], v[134:137]
	v_mfma_i32_16x16x64_i8 v[130:133], v[154:157], v[162:165], v[130:133]
	v_mfma_i32_16x16x64_i8 v[118:121], v[18:21], v[178:181], v[118:121]
	v_mfma_i32_16x16x64_i8 v[110:113], v[154:157], v[178:181], v[110:113]
	v_mfma_i32_16x16x64_i8 v[102:105], v[18:21], v[186:189], v[102:105]
	v_mfma_i32_16x16x64_i8 v[98:101], v[154:157], v[186:189], v[98:101]
	v_mfma_i32_16x16x64_i8 v[94:97], v[18:21], v[194:197], v[94:97]
	v_mfma_i32_16x16x64_i8 v[90:93], v[154:157], v[194:197], v[90:93]
	v_mfma_i32_16x16x64_i8 v[134:137], v[26:29], v[166:169], v[134:137]
	v_mfma_i32_16x16x64_i8 v[130:133], v[158:161], v[166:169], v[130:133]
	v_mfma_i32_16x16x64_i8 v[118:121], v[26:29], v[182:185], v[118:121]
	v_mfma_i32_16x16x64_i8 v[110:113], v[158:161], v[182:185], v[110:113]
	v_mfma_i32_16x16x64_i8 v[102:105], v[26:29], v[190:193], v[102:105]
	v_mfma_i32_16x16x64_i8 v[98:101], v[158:161], v[190:193], v[98:101]
	v_mfma_i32_16x16x64_i8 v[94:97], v[26:29], v[198:201], v[94:97]
	v_mfma_i32_16x16x64_i8 v[90:93], v[158:161], v[198:201], v[90:93]
	s_setprio 0
	s_barrier
	ds_read_b128 v[162:165], v233 offset:16384
	ds_read_b128 v[166:169], v233 offset:17408
	ds_read_b128 v[178:181], v233 offset:18432
	ds_read_b128 v[182:185], v233 offset:19456
	ds_read_b128 v[186:189], v233 offset:20480
	ds_read_b128 v[190:193], v233 offset:21504
	ds_read_b128 v[194:197], v233 offset:22528
	ds_read_b128 v[198:201], v233 offset:23552
	s_mov_b32 m0, s21
	s_nop 0
	global_load_lds_dwordx4 v209, s[80:81]
	s_add_u32 s96, s80, 0x80000
	s_mov_b32 m0, s23
	s_nop 0
	global_load_lds_dwordx4 v211, s[80:81]
	s_addc_u32 s97, s81, 0
	s_mov_b32 m0, s28
	s_nop 0
	global_load_lds_dwordx4 v209, s[96:97]
	s_mov_b32 m0, s29
	s_nop 0
	global_load_lds_dwordx4 v211, s[96:97]
	s_mov_b32 m0, s15
	s_nop 0
	global_load_lds_dwordx4 v208, s[82:83]
	s_mov_b32 m0, s30
	s_nop 0
	global_load_lds_dwordx4 v210, s[82:83]
	s_waitcnt vmcnt(8)
	s_waitcnt lgkmcnt(0)
	s_barrier
	s_setprio 1
	v_mfma_i32_16x16x64_i8 v[86:89], v[2:5], v[162:165], v[86:89]
	v_mfma_i32_16x16x64_i8 v[82:85], v[10:13], v[162:165], v[82:85]
	v_mfma_i32_16x16x64_i8 v[74:77], v[2:5], v[178:181], v[74:77]
	v_mfma_i32_16x16x64_i8 v[66:69], v[10:13], v[178:181], v[66:69]
	v_mfma_i32_16x16x64_i8 v[58:61], v[2:5], v[186:189], v[58:61]
	v_mfma_i32_16x16x64_i8 v[50:53], v[10:13], v[186:189], v[50:53]
	v_mfma_i32_16x16x64_i8 v[2:5], v[2:5], v[194:197], v[30:33]
	v_mfma_i32_16x16x64_i8 v[86:89], v[6:9], v[166:169], v[86:89]
	v_mfma_i32_16x16x64_i8 v[82:85], v[14:17], v[166:169], v[82:85]
	v_mfma_i32_16x16x64_i8 v[74:77], v[6:9], v[182:185], v[74:77]
	v_mfma_i32_16x16x64_i8 v[66:69], v[14:17], v[182:185], v[66:69]
	v_mfma_i32_16x16x64_i8 v[58:61], v[6:9], v[190:193], v[58:61]
	v_mfma_i32_16x16x64_i8 v[50:53], v[14:17], v[190:193], v[50:53]
	v_mfma_i32_16x16x64_i8 v[2:5], v[6:9], v[198:201], v[2:5]
	v_mfma_i32_16x16x64_i8 v[6:9], v[10:13], v[194:197], v[22:25]
	v_mfma_i32_16x16x64_i8 v[6:9], v[14:17], v[198:201], v[6:9]
	s_setprio 0
	s_setprio 1
	v_mfma_i32_16x16x64_i8 v[22:25], v[18:21], v[178:181], v[62:65]
	v_mfma_i32_16x16x64_i8 v[62:65], v[26:29], v[182:185], v[22:25]
	v_mfma_i32_16x16x64_i8 v[22:25], v[154:157], v[178:181], v[54:57]
	v_mfma_i32_16x16x64_i8 v[54:57], v[158:161], v[182:185], v[22:25]
	v_mfma_i32_16x16x64_i8 v[22:25], v[18:21], v[186:189], v[46:49]
	v_mfma_i32_16x16x64_i8 v[46:49], v[26:29], v[190:193], v[22:25]
	v_mfma_i32_16x16x64_i8 v[22:25], v[154:157], v[186:189], v[42:45]
	v_mfma_i32_16x16x64_i8 v[10:13], v[18:21], v[162:165], v[78:81]
	v_mfma_i32_16x16x64_i8 v[14:17], v[154:157], v[162:165], v[70:73]
	v_mfma_i32_16x16x64_i8 v[42:45], v[158:161], v[190:193], v[22:25]
	v_mfma_i32_16x16x64_i8 v[18:21], v[18:21], v[194:197], v[38:41]
	v_mfma_i32_16x16x64_i8 v[22:25], v[154:157], v[194:197], v[34:37]
	v_mfma_i32_16x16x64_i8 v[10:13], v[26:29], v[166:169], v[10:13]
	v_mfma_i32_16x16x64_i8 v[14:17], v[158:161], v[166:169], v[14:17]
	v_mfma_i32_16x16x64_i8 v[18:21], v[26:29], v[198:201], v[18:21]
	v_mfma_i32_16x16x64_i8 v[26:29], v[158:161], v[198:201], v[22:25]
	s_setprio 0
	s_barrier
; #define PG8_STAGE(bufoff, gbase, voff) do { if constexpr (VAR != 1 && VAR != 3) { _Pragma("unroll") for (int _i = 0; _i < 2; ++_i) \
;         asm volatile("s_mov_b32 m0, %2\n\ts_nop 0\n\tglobal_load_lds_dwordx4 %0, %1" :: "v"((voff)[_i]), "s"((const char*)(gbase)), "s"(ldsbase + (unsigned)((bufoff) + _i * 8192)) : "memory", "m0"); } } while (0)
; #define PG8_LDA(dst, b, h) do { if constexpr (VAR < 2) _Pragma("unroll") for (int m = 0; m < 4; ++m) _Pragma("unroll") for (int k = 0; k < 2; ++k) dst[m][k] = *(const LAS bf16x8*)(lds + PG8_SA(b, h) + aoff + m * 2048 + k * 1024); } while (0)
; #define PG8_LDB(dst, b, h) do { if constexpr (VAR < 2) _Pragma("unroll") for (int n = 0; n < 2; ++n) _Pragma("unroll") for (int k = 0; k < 2; ++k) dst[n][k] = *(const LAS bf16x8*)(lds + PG8_SB(b, h) + boff + n * 2048 + k * 1024); } while (0)
; #define PG8_WAIT_V(n) asm volatile("s_waitcnt vmcnt(" #n ")" ::: "memory")
; #define PG8_WAIT_L(n) asm volatile("s_waitcnt lgkmcnt(" #n ")" ::: "memory")
; #define PG8_BAR do { if constexpr (VAR != 3) __builtin_amdgcn_s_barrier(); } while (0)
; #define PG8_SCHED __builtin_amdgcn_sched_barrier(0)
;     ...
;             PG8_LDB(B0, 1, 0); PG8_LDB(B1, 1, 1); PG8_SCHED; PG8_LDA(At, 1, 0); PG8_STAGE(PG8_SA(0, 1), a2 + hstepA, voffA);
;             PG8_WAIT_V(8); PG8_WAIT_L(0); PG8_BAR; PG8_MMA(0, 0, At, B0); PG8_MMA(0, 1, At, B1); PG8_BAR; PG8_SCHED;
;             PG8_LDA(At, 1, 1); PG8_STAGE(PG8_SB(1, 0), b3, voffB); PG8_STAGE(PG8_SB(1, 1), b3 + hstepB, voffB); PG8_STAGE(PG8_SA(1, 0), a3, voffA);
;             PG8_WAIT_V(8); PG8_WAIT_L(0); PG8_BAR; PG8_MMA(1, 0, At, B0); PG8_MMA(1, 1, At, B1); PG8_BAR; PG8_SCHED;
;         }
	s_nop 1
	ds_read_b128 v[22:25], v234
	ds_read_b128 v[30:33], v234 offset:1024
	ds_read_b128 v[34:37], v234 offset:2048
	ds_read_b128 v[38:41], v234 offset:3072
	ds_read_b128 v[154:157], v235
	ds_read_b128 v[158:161], v235 offset:1024
	ds_read_b128 v[162:165], v235 offset:2048
	ds_read_b128 v[166:169], v235 offset:3072
	ds_read_b128 v[70:73], v233 offset:32768
	ds_read_b128 v[78:81], v233 offset:33792
	ds_read_b128 v[178:181], v233 offset:34816
	ds_read_b128 v[182:185], v233 offset:35840
	ds_read_b128 v[186:189], v233 offset:36864
	ds_read_b128 v[190:193], v233 offset:37888
	ds_read_b128 v[194:197], v233 offset:38912
	ds_read_b128 v[198:201], v233 offset:39936
	s_add_u32 s82, s82, 0x80000
	s_addc_u32 s83, s83, 0
	s_mov_b32 m0, s31
	s_nop 0
	global_load_lds_dwordx4 v208, s[82:83]
	s_mov_b32 m0, s33
	s_nop 0
	global_load_lds_dwordx4 v210, s[82:83]
	s_waitcnt vmcnt(8)
	s_waitcnt lgkmcnt(0)
	s_barrier
	s_setprio 1
	v_mfma_i32_16x16x64_i8 v[150:153], v[22:25], v[70:73], v[150:153]
	v_mfma_i32_16x16x64_i8 v[142:145], v[34:37], v[70:73], v[142:145]
	v_mfma_i32_16x16x64_i8 v[126:129], v[22:25], v[178:181], v[126:129]
	v_mfma_i32_16x16x64_i8 v[122:125], v[34:37], v[178:181], v[122:125]
	v_mfma_i32_16x16x64_i8 v[114:117], v[22:25], v[186:189], v[114:117]
	v_mfma_i32_16x16x64_i8 v[106:109], v[34:37], v[186:189], v[106:109]
	v_mfma_i32_16x16x64_i8 v[146:149], v[22:25], v[194:197], v[146:149]
	v_mfma_i32_16x16x64_i8 v[138:141], v[34:37], v[194:197], v[138:141]
	v_mfma_i32_16x16x64_i8 v[150:153], v[30:33], v[78:81], v[150:153]
	v_mfma_i32_16x16x64_i8 v[142:145], v[38:41], v[78:81], v[142:145]
	v_mfma_i32_16x16x64_i8 v[126:129], v[30:33], v[182:185], v[126:129]
	v_mfma_i32_16x16x64_i8 v[122:125], v[38:41], v[182:185], v[122:125]
	v_mfma_i32_16x16x64_i8 v[114:117], v[30:33], v[190:193], v[114:117]
	v_mfma_i32_16x16x64_i8 v[106:109], v[38:41], v[190:193], v[106:109]
	v_mfma_i32_16x16x64_i8 v[146:149], v[30:33], v[198:201], v[146:149]
	v_mfma_i32_16x16x64_i8 v[138:141], v[38:41], v[198:201], v[138:141]
	s_setprio 0
	s_setprio 1
	v_mfma_i32_16x16x64_i8 v[134:137], v[154:157], v[70:73], v[134:137]
	v_mfma_i32_16x16x64_i8 v[70:73], v[162:165], v[70:73], v[130:133]
	v_mfma_i32_16x16x64_i8 v[130:133], v[166:169], v[78:81], v[70:73]
	v_mfma_i32_16x16x64_i8 v[70:73], v[154:157], v[178:181], v[118:121]
	v_mfma_i32_16x16x64_i8 v[118:121], v[158:161], v[182:185], v[70:73]
	v_mfma_i32_16x16x64_i8 v[70:73], v[162:165], v[178:181], v[110:113]
	v_mfma_i32_16x16x64_i8 v[110:113], v[166:169], v[182:185], v[70:73]
	v_mfma_i32_16x16x64_i8 v[70:73], v[154:157], v[186:189], v[102:105]
	v_mfma_i32_16x16x64_i8 v[102:105], v[158:161], v[190:193], v[70:73]
	v_mfma_i32_16x16x64_i8 v[70:73], v[162:165], v[186:189], v[98:101]
	v_mfma_i32_16x16x64_i8 v[98:101], v[166:169], v[190:193], v[70:73]
	v_mfma_i32_16x16x64_i8 v[70:73], v[154:157], v[194:197], v[94:97]
	v_mfma_i32_16x16x64_i8 v[94:97], v[158:161], v[198:201], v[70:73]
	v_mfma_i32_16x16x64_i8 v[70:73], v[162:165], v[194:197], v[90:93]
	v_mfma_i32_16x16x64_i8 v[134:137], v[158:161], v[78:81], v[134:137]
	v_mfma_i32_16x16x64_i8 v[90:93], v[166:169], v[198:201], v[70:73]
	s_setprio 0
	s_barrier
	s_nop 3
	ds_read_b128 v[70:73], v233 offset:49152
	ds_read_b128 v[178:181], v233 offset:50176
	ds_read_b128 v[182:185], v233 offset:51200
	ds_read_b128 v[186:189], v233 offset:52224
	ds_read_b128 v[190:193], v233 offset:53248
	ds_read_b128 v[194:197], v233 offset:54272
	ds_read_b128 v[198:201], v233 offset:55296
	ds_read_b128 v[202:205], v233 offset:56320
	s_add_u32 s82, s80, 0x80
	s_addc_u32 s83, s81, 0
	s_mov_b32 m0, s84
	s_nop 0
	global_load_lds_dwordx4 v209, s[82:83]
	s_add_u32 s80, s80, 0x80080
	s_mov_b32 m0, s85
	s_nop 0
	global_load_lds_dwordx4 v211, s[82:83]
	s_addc_u32 s81, s81, 0
	s_mov_b32 m0, s88
	s_nop 0
	global_load_lds_dwordx4 v209, s[80:81]
	s_mov_b32 m0, s89
	s_nop 0
	global_load_lds_dwordx4 v211, s[80:81]
	s_mov_b32 m0, s86
	s_nop 0
	global_load_lds_dwordx4 v208, s[78:79]
	s_mov_b32 m0, s87
	s_nop 0
	global_load_lds_dwordx4 v210, s[78:79]
	s_waitcnt vmcnt(8)
	s_waitcnt lgkmcnt(0)
	s_barrier
	s_setprio 1
	v_mfma_i32_16x16x64_i8 v[78:81], v[22:25], v[70:73], v[86:89]
	v_mfma_i32_16x16x64_i8 v[74:77], v[22:25], v[182:185], v[74:77]
	v_mfma_i32_16x16x64_i8 v[58:61], v[22:25], v[190:193], v[58:61]
	v_mfma_i32_16x16x64_i8 v[2:5], v[22:25], v[198:201], v[2:5]
	v_mfma_i32_16x16x64_i8 v[86:89], v[30:33], v[178:181], v[78:81]
	v_mfma_i32_16x16x64_i8 v[78:81], v[34:37], v[70:73], v[82:85]
	v_mfma_i32_16x16x64_i8 v[74:77], v[30:33], v[186:189], v[74:77]
	v_mfma_i32_16x16x64_i8 v[66:69], v[34:37], v[182:185], v[66:69]
	v_mfma_i32_16x16x64_i8 v[58:61], v[30:33], v[194:197], v[58:61]
	v_mfma_i32_16x16x64_i8 v[50:53], v[34:37], v[190:193], v[50:53]
	v_mfma_i32_16x16x64_i8 v[30:33], v[30:33], v[202:205], v[2:5]
	v_mfma_i32_16x16x64_i8 v[2:5], v[34:37], v[198:201], v[6:9]
	v_mfma_i32_16x16x64_i8 v[82:85], v[38:41], v[178:181], v[78:81]
	v_mfma_i32_16x16x64_i8 v[66:69], v[38:41], v[186:189], v[66:69]
	v_mfma_i32_16x16x64_i8 v[50:53], v[38:41], v[194:197], v[50:53]
	v_mfma_i32_16x16x64_i8 v[22:25], v[38:41], v[202:205], v[2:5]
	s_setprio 0
	s_setprio 1
	v_mfma_i32_16x16x64_i8 v[2:5], v[154:157], v[70:73], v[10:13]
	v_mfma_i32_16x16x64_i8 v[78:81], v[158:161], v[178:181], v[2:5]
	v_mfma_i32_16x16x64_i8 v[2:5], v[162:165], v[70:73], v[14:17]
	v_mfma_i32_16x16x64_i8 v[70:73], v[166:169], v[178:181], v[2:5]
	v_mfma_i32_16x16x64_i8 v[2:5], v[154:157], v[182:185], v[62:65]
	v_mfma_i32_16x16x64_i8 v[62:65], v[158:161], v[186:189], v[2:5]
	v_mfma_i32_16x16x64_i8 v[2:5], v[162:165], v[182:185], v[54:57]
	v_mfma_i32_16x16x64_i8 v[54:57], v[166:169], v[186:189], v[2:5]
	v_mfma_i32_16x16x64_i8 v[2:5], v[154:157], v[190:193], v[46:49]
	v_mfma_i32_16x16x64_i8 v[46:49], v[158:161], v[194:197], v[2:5]
	v_mfma_i32_16x16x64_i8 v[2:5], v[162:165], v[190:193], v[42:45]
	v_mfma_i32_16x16x64_i8 v[42:45], v[166:169], v[194:197], v[2:5]
	v_mfma_i32_16x16x64_i8 v[2:5], v[154:157], v[198:201], v[18:21]
	v_mfma_i32_16x16x64_i8 v[38:41], v[158:161], v[202:205], v[2:5]
	v_mfma_i32_16x16x64_i8 v[2:5], v[162:165], v[198:201], v[26:29]
	v_mfma_i32_16x16x64_i8 v[34:37], v[166:169], v[202:205], v[2:5]
	s_setprio 0
	s_barrier
	s_add_i32 s71, s71, 2
	s_add_u32 s25, s25, 0x100
	s_addc_u32 s26, s26, 0
	s_add_u32 s27, s27, 0x100
	s_addc_u32 s69, s69, 0
	s_add_u32 s0, s0, 0x100
	s_addc_u32 s1, s1, 0
	s_cmp_gt_u32 s71, 29
	s_cbranch_scc0 .LBB0_1191
	s_and_b64 vcc, exec, s[64:65]
	s_cbranch_vccz .LBB0_1194
	s_barrier

; #define PG8_STAGE(bufoff, gbase, voff) do { if constexpr (VAR != 1 && VAR != 3) { _Pragma("unroll") for (int _i = 0; _i < 2; ++_i) \
;         asm volatile("s_mov_b32 m0, %2\n\ts_nop 0\n\tglobal_load_lds_dwordx4 %0, %1" :: "v"((voff)[_i]), "s"((const char*)(gbase)), "s"(ldsbase + (unsigned)((bufoff) + _i * 8192)) : "memory", "m0"); } } while (0)
; #define PG8_LDA(dst, b, h) do { if constexpr (VAR < 2) _Pragma("unroll") for (int m = 0; m < 4; ++m) _Pragma("unroll") for (int k = 0; k < 2; ++k) dst[m][k] = *(const LAS bf16x8*)(lds + PG8_SA(b, h) + aoff + m * 2048 + k * 1024); } while (0)
; #define PG8_LDB(dst, b, h) do { if constexpr (VAR < 2) _Pragma("unroll") for (int n = 0; n < 2; ++n) _Pragma("unroll") for (int k = 0; k < 2; ++k) dst[n][k] = *(const LAS bf16x8*)(lds + PG8_SB(b, h) + boff + n * 2048 + k * 1024); } while (0)
; #define PG8_WAIT_V(n) asm volatile("s_waitcnt vmcnt(" #n ")" ::: "memory")
; #define PG8_WAIT_L(n) asm volatile("s_waitcnt lgkmcnt(" #n ")" ::: "memory")
; #define PG8_BAR do { if constexpr (VAR != 3) __builtin_amdgcn_s_barrier(); } while (0)
; #define PG8_SCHED __builtin_amdgcn_sched_barrier(0)
;     ...
;         for (int t = 0; t < nt; t += 2) {
;             const bool last = (t == nt - 2);
;             const char* a1 = cA + (size_t)(t + 1) * kstep;
;             const char* a2 = last ? nA : cA + (size_t)(t + 2) * kstep; const char* b2 = last ? nB : cB + (size_t)(t + 2) * kstep;
;             const char* a3 = a2 + kstep; const char* b3 = b2 + kstep;
;             PG8_LDB(B0, 0, 0); PG8_LDB(B1, 0, 1); PG8_SCHED; PG8_LDA(At, 0, 0); PG8_STAGE(PG8_SA(1, 1), a1 + hstepA, voffA);
;             PG8_WAIT_V(8); PG8_WAIT_L(0); PG8_BAR; PG8_MMA(0, 0, At, B0); PG8_MMA(0, 1, At, B1); PG8_BAR; PG8_SCHED;
;             PG8_LDA(At, 0, 1); PG8_STAGE(PG8_SB(0, 0), b2, voffB); PG8_STAGE(PG8_SB(0, 1), b2 + hstepB, voffB); PG8_STAGE(PG8_SA(0, 0), a2, voffA);
;             PG8_WAIT_V(8); PG8_WAIT_L(0); PG8_BAR; PG8_MMA(1, 0, At, B0); PG8_MMA(1, 1, At, B1); PG8_BAR; PG8_SCHED;
.LBB0_1361:
	ds_read_b128 v[130:133], v160
	ds_read_b128 v[134:137], v160 offset:1024
	ds_read_b128 v[142:145], v160 offset:2048
	ds_read_b128 v[146:149], v160 offset:3072
	ds_read_b128 v[150:153], v161
	ds_read_b128 v[166:169], v161 offset:1024
	ds_read_b128 v[170:173], v161 offset:2048
	ds_read_b128 v[174:177], v161 offset:3072
	s_cmpk_eq_i32 s78, 0xa8
	s_cselect_b32 s64, s12, s74
	s_cselect_b32 s65, s13, s75
	s_cselect_b32 s62, s56, s76
	s_cselect_b32 s63, s57, s77
	s_add_u32 s60, s64, 0x80
	s_addc_u32 s61, s65, 0
	ds_read_b128 v[178:181], v162
	ds_read_b128 v[182:185], v162 offset:1024
	ds_read_b128 v[186:189], v162 offset:2048
	ds_read_b128 v[190:193], v162 offset:3072
	ds_read_b128 v[194:197], v162 offset:4096
	ds_read_b128 v[198:201], v162 offset:5120
	ds_read_b128 v[202:205], v162 offset:6144
	ds_read_b128 v[206:209], v162 offset:7168
	s_mov_b32 m0, s69
	s_nop 0
	global_load_lds_dwordx4 v1, s[58:59]
	s_mov_b32 m0, s70
	s_nop 0
	global_load_lds_dwordx4 v155, s[58:59]
	s_waitcnt vmcnt(8)
	s_waitcnt lgkmcnt(0)
	s_barrier
	s_setprio 1
	v_mfma_f32_16x16x32_bf16 v[126:129], v[130:133], v[178:181], v[126:129]
	v_mfma_f32_16x16x32_bf16 v[122:125], v[142:145], v[178:181], v[122:125]
	v_mfma_f32_16x16x32_bf16 v[110:113], v[130:133], v[186:189], v[110:113]
	v_mfma_f32_16x16x32_bf16 v[106:109], v[142:145], v[186:189], v[106:109]
	v_mfma_f32_16x16x32_bf16 v[94:97], v[130:133], v[194:197], v[94:97]
	v_mfma_f32_16x16x32_bf16 v[90:93], v[142:145], v[194:197], v[90:93]
	v_mfma_f32_16x16x32_bf16 v[78:81], v[130:133], v[202:205], v[78:81]
	v_mfma_f32_16x16x32_bf16 v[74:77], v[142:145], v[202:205], v[74:77]
	v_mfma_f32_16x16x32_bf16 v[126:129], v[134:137], v[182:185], v[126:129]
	v_mfma_f32_16x16x32_bf16 v[122:125], v[146:149], v[182:185], v[122:125]
	v_mfma_f32_16x16x32_bf16 v[110:113], v[134:137], v[190:193], v[110:113]
	v_mfma_f32_16x16x32_bf16 v[106:109], v[146:149], v[190:193], v[106:109]
	v_mfma_f32_16x16x32_bf16 v[94:97], v[134:137], v[198:201], v[94:97]
	v_mfma_f32_16x16x32_bf16 v[90:93], v[146:149], v[198:201], v[90:93]
	v_mfma_f32_16x16x32_bf16 v[78:81], v[134:137], v[206:209], v[78:81]
	v_mfma_f32_16x16x32_bf16 v[74:77], v[146:149], v[206:209], v[74:77]
	s_setprio 0
	s_setprio 1
	v_mfma_f32_16x16x32_bf16 v[118:121], v[150:153], v[178:181], v[118:121]
	v_mfma_f32_16x16x32_bf16 v[114:117], v[170:173], v[178:181], v[114:117]
	v_mfma_f32_16x16x32_bf16 v[102:105], v[150:153], v[186:189], v[102:105]
	v_mfma_f32_16x16x32_bf16 v[98:101], v[170:173], v[186:189], v[98:101]
	v_mfma_f32_16x16x32_bf16 v[86:89], v[150:153], v[194:197], v[86:89]
	v_mfma_f32_16x16x32_bf16 v[82:85], v[170:173], v[194:197], v[82:85]
	v_mfma_f32_16x16x32_bf16 v[70:73], v[150:153], v[202:205], v[70:73]
	v_mfma_f32_16x16x32_bf16 v[66:69], v[170:173], v[202:205], v[66:69]
	v_mfma_f32_16x16x32_bf16 v[118:121], v[166:169], v[182:185], v[118:121]
	v_mfma_f32_16x16x32_bf16 v[114:117], v[174:177], v[182:185], v[114:117]
	v_mfma_f32_16x16x32_bf16 v[102:105], v[166:169], v[190:193], v[102:105]
	v_mfma_f32_16x16x32_bf16 v[98:101], v[174:177], v[190:193], v[98:101]
	v_mfma_f32_16x16x32_bf16 v[86:89], v[166:169], v[198:201], v[86:89]
	v_mfma_f32_16x16x32_bf16 v[82:85], v[174:177], v[198:201], v[82:85]
	v_mfma_f32_16x16x32_bf16 v[70:73], v[166:169], v[206:209], v[70:73]
	v_mfma_f32_16x16x32_bf16 v[66:69], v[174:177], v[206:209], v[66:69]
	s_setprio 0
	s_barrier
	ds_read_b128 v[178:181], v162 offset:16384
	ds_read_b128 v[182:185], v162 offset:17408
	ds_read_b128 v[186:189], v162 offset:18432
	ds_read_b128 v[190:193], v162 offset:19456
	ds_read_b128 v[194:197], v162 offset:20480
	ds_read_b128 v[198:201], v162 offset:21504
	ds_read_b128 v[202:205], v162 offset:22528
	ds_read_b128 v[206:209], v162 offset:23552
	s_mov_b32 m0, s19
	s_nop 0
	global_load_lds_dwordx4 v154, s[62:63]
	s_add_u32 s80, s62, 0x2b0000
	s_mov_b32 m0, s21
	s_nop 0
	global_load_lds_dwordx4 v156, s[62:63]
	s_addc_u32 s81, s63, 0
	s_mov_b32 m0, s23
	s_nop 0
	global_load_lds_dwordx4 v154, s[80:81]
	s_mov_b32 m0, s26
	s_nop 0
	global_load_lds_dwordx4 v156, s[80:81]
	s_mov_b32 m0, s17
	s_nop 0
	global_load_lds_dwordx4 v1, s[64:65]
	s_mov_b32 m0, s27
	s_nop 0
	global_load_lds_dwordx4 v155, s[64:65]
	s_waitcnt vmcnt(8)
	s_waitcnt lgkmcnt(0)
	s_barrier
	s_setprio 1
	v_mfma_f32_16x16x32_bf16 v[62:65], v[130:133], v[178:181], v[62:65]
	v_mfma_f32_16x16x32_bf16 v[58:61], v[142:145], v[178:181], v[58:61]
	v_mfma_f32_16x16x32_bf16 v[46:49], v[130:133], v[186:189], v[46:49]
	v_mfma_f32_16x16x32_bf16 v[42:45], v[142:145], v[186:189], v[42:45]
	v_mfma_f32_16x16x32_bf16 v[30:33], v[130:133], v[194:197], v[30:33]
	v_mfma_f32_16x16x32_bf16 v[26:29], v[142:145], v[194:197], v[26:29]
	v_mfma_f32_16x16x32_bf16 v[14:17], v[130:133], v[202:205], v[14:17]
	v_mfma_f32_16x16x32_bf16 v[10:13], v[142:145], v[202:205], v[10:13]
	v_mfma_f32_16x16x32_bf16 v[62:65], v[134:137], v[182:185], v[62:65]
	v_mfma_f32_16x16x32_bf16 v[58:61], v[146:149], v[182:185], v[58:61]
	v_mfma_f32_16x16x32_bf16 v[46:49], v[134:137], v[190:193], v[46:49]
	v_mfma_f32_16x16x32_bf16 v[42:45], v[146:149], v[190:193], v[42:45]
	v_mfma_f32_16x16x32_bf16 v[30:33], v[134:137], v[198:201], v[30:33]
	v_mfma_f32_16x16x32_bf16 v[26:29], v[146:149], v[198:201], v[26:29]
	v_mfma_f32_16x16x32_bf16 v[14:17], v[134:137], v[206:209], v[14:17]
	v_mfma_f32_16x16x32_bf16 v[10:13], v[146:149], v[206:209], v[10:13]
	s_setprio 0
	s_setprio 1
	v_mfma_f32_16x16x32_bf16 v[54:57], v[150:153], v[178:181], v[54:57]
	v_mfma_f32_16x16x32_bf16 v[50:53], v[170:173], v[178:181], v[50:53]
	v_mfma_f32_16x16x32_bf16 v[38:41], v[150:153], v[186:189], v[38:41]
	v_mfma_f32_16x16x32_bf16 v[34:37], v[170:173], v[186:189], v[34:37]
	v_mfma_f32_16x16x32_bf16 v[22:25], v[150:153], v[194:197], v[22:25]
	v_mfma_f32_16x16x32_bf16 v[18:21], v[170:173], v[194:197], v[18:21]
	v_mfma_f32_16x16x32_bf16 v[6:9], v[150:153], v[202:205], v[6:9]
	v_mfma_f32_16x16x32_bf16 v[2:5], v[170:173], v[202:205], v[2:5]
	v_mfma_f32_16x16x32_bf16 v[54:57], v[166:169], v[182:185], v[54:57]
	v_mfma_f32_16x16x32_bf16 v[50:53], v[174:177], v[182:185], v[50:53]
	v_mfma_f32_16x16x32_bf16 v[38:41], v[166:169], v[190:193], v[38:41]
	v_mfma_f32_16x16x32_bf16 v[34:37], v[174:177], v[190:193], v[34:37]
	v_mfma_f32_16x16x32_bf16 v[22:25], v[166:169], v[198:201], v[22:25]
	v_mfma_f32_16x16x32_bf16 v[18:21], v[174:177], v[198:201], v[18:21]
	v_mfma_f32_16x16x32_bf16 v[6:9], v[166:169], v[206:209], v[6:9]
	v_mfma_f32_16x16x32_bf16 v[2:5], v[174:177], v[206:209], v[2:5]
	s_setprio 0
	s_barrier
; #define PG8_STAGE(bufoff, gbase, voff) do { if constexpr (VAR != 1 && VAR != 3) { _Pragma("unroll") for (int _i = 0; _i < 2; ++_i) \
;         asm volatile("s_mov_b32 m0, %2\n\ts_nop 0\n\tglobal_load_lds_dwordx4 %0, %1" :: "v"((voff)[_i]), "s"((const char*)(gbase)), "s"(ldsbase + (unsigned)((bufoff) + _i * 8192)) : "memory", "m0"); } } while (0)
; #define PG8_LDA(dst, b, h) do { if constexpr (VAR < 2) _Pragma("unroll") for (int m = 0; m < 4; ++m) _Pragma("unroll") for (int k = 0; k < 2; ++k) dst[m][k] = *(const LAS bf16x8*)(lds + PG8_SA(b, h) + aoff + m * 2048 + k * 1024); } while (0)
; #define PG8_LDB(dst, b, h) do { if constexpr (VAR < 2) _Pragma("unroll") for (int n = 0; n < 2; ++n) _Pragma("unroll") for (int k = 0; k < 2; ++k) dst[n][k] = *(const LAS bf16x8*)(lds + PG8_SB(b, h) + boff + n * 2048 + k * 1024); } while (0)
; #define PG8_WAIT_V(n) asm volatile("s_waitcnt vmcnt(" #n ")" ::: "memory")
; #define PG8_WAIT_L(n) asm volatile("s_waitcnt lgkmcnt(" #n ")" ::: "memory")
; #define PG8_BAR do { if constexpr (VAR != 3) __builtin_amdgcn_s_barrier(); } while (0)
; #define PG8_SCHED __builtin_amdgcn_sched_barrier(0)
;     ...
;             PG8_LDB(B0, 1, 0); PG8_LDB(B1, 1, 1); PG8_SCHED; PG8_LDA(At, 1, 0); PG8_STAGE(PG8_SA(0, 1), a2 + hstepA, voffA);
;             PG8_WAIT_V(8); PG8_WAIT_L(0); PG8_BAR; PG8_MMA(0, 0, At, B0); PG8_MMA(0, 1, At, B1); PG8_BAR; PG8_SCHED;
;             PG8_LDA(At, 1, 1); PG8_STAGE(PG8_SB(1, 0), b3, voffB); PG8_STAGE(PG8_SB(1, 1), b3 + hstepB, voffB); PG8_STAGE(PG8_SA(1, 0), a3, voffA);
;             PG8_WAIT_V(8); PG8_WAIT_L(0); PG8_BAR; PG8_MMA(1, 0, At, B0); PG8_MMA(1, 1, At, B1); PG8_BAR; PG8_SCHED;
;         }
	ds_read_b128 v[130:133], v163
	ds_read_b128 v[134:137], v163 offset:1024
	ds_read_b128 v[142:145], v163 offset:2048
	ds_read_b128 v[146:149], v163 offset:3072
	ds_read_b128 v[150:153], v164
	ds_read_b128 v[166:169], v164 offset:1024
	ds_read_b128 v[170:173], v164 offset:2048
	ds_read_b128 v[174:177], v164 offset:3072
	ds_read_b128 v[178:181], v162 offset:32768
	ds_read_b128 v[182:185], v162 offset:33792
	ds_read_b128 v[186:189], v162 offset:34816
	ds_read_b128 v[190:193], v162 offset:35840
	ds_read_b128 v[194:197], v162 offset:36864
	ds_read_b128 v[198:201], v162 offset:37888
	ds_read_b128 v[202:205], v162 offset:38912
	ds_read_b128 v[206:209], v162 offset:39936
	s_add_u32 s64, s64, 0x2b0000
	s_addc_u32 s65, s65, 0
	s_mov_b32 m0, s28
	s_nop 0
	global_load_lds_dwordx4 v1, s[64:65]
	s_mov_b32 m0, s29
	s_nop 0
	global_load_lds_dwordx4 v155, s[64:65]
	s_waitcnt vmcnt(8)
	s_waitcnt lgkmcnt(0)
	s_barrier
	s_setprio 1
	v_mfma_f32_16x16x32_bf16 v[126:129], v[130:133], v[178:181], v[126:129]
	v_mfma_f32_16x16x32_bf16 v[122:125], v[142:145], v[178:181], v[122:125]
	v_mfma_f32_16x16x32_bf16 v[110:113], v[130:133], v[186:189], v[110:113]
	v_mfma_f32_16x16x32_bf16 v[106:109], v[142:145], v[186:189], v[106:109]
	v_mfma_f32_16x16x32_bf16 v[94:97], v[130:133], v[194:197], v[94:97]
	v_mfma_f32_16x16x32_bf16 v[90:93], v[142:145], v[194:197], v[90:93]
	v_mfma_f32_16x16x32_bf16 v[78:81], v[130:133], v[202:205], v[78:81]
	v_mfma_f32_16x16x32_bf16 v[74:77], v[142:145], v[202:205], v[74:77]
	v_mfma_f32_16x16x32_bf16 v[126:129], v[134:137], v[182:185], v[126:129]
	v_mfma_f32_16x16x32_bf16 v[122:125], v[146:149], v[182:185], v[122:125]
	v_mfma_f32_16x16x32_bf16 v[110:113], v[134:137], v[190:193], v[110:113]
	v_mfma_f32_16x16x32_bf16 v[106:109], v[146:149], v[190:193], v[106:109]
	v_mfma_f32_16x16x32_bf16 v[94:97], v[134:137], v[198:201], v[94:97]
	v_mfma_f32_16x16x32_bf16 v[90:93], v[146:149], v[198:201], v[90:93]
	v_mfma_f32_16x16x32_bf16 v[78:81], v[134:137], v[206:209], v[78:81]
	v_mfma_f32_16x16x32_bf16 v[74:77], v[146:149], v[206:209], v[74:77]
	s_setprio 0
	s_setprio 1
	v_mfma_f32_16x16x32_bf16 v[118:121], v[150:153], v[178:181], v[118:121]
	v_mfma_f32_16x16x32_bf16 v[114:117], v[170:173], v[178:181], v[114:117]
	v_mfma_f32_16x16x32_bf16 v[102:105], v[150:153], v[186:189], v[102:105]
	v_mfma_f32_16x16x32_bf16 v[98:101], v[170:173], v[186:189], v[98:101]
	v_mfma_f32_16x16x32_bf16 v[86:89], v[150:153], v[194:197], v[86:89]
	v_mfma_f32_16x16x32_bf16 v[82:85], v[170:173], v[194:197], v[82:85]
	v_mfma_f32_16x16x32_bf16 v[70:73], v[150:153], v[202:205], v[70:73]
	v_mfma_f32_16x16x32_bf16 v[66:69], v[170:173], v[202:205], v[66:69]
	v_mfma_f32_16x16x32_bf16 v[118:121], v[166:169], v[182:185], v[118:121]
	v_mfma_f32_16x16x32_bf16 v[114:117], v[174:177], v[182:185], v[114:117]
	v_mfma_f32_16x16x32_bf16 v[102:105], v[166:169], v[190:193], v[102:105]
	v_mfma_f32_16x16x32_bf16 v[98:101], v[174:177], v[190:193], v[98:101]
	v_mfma_f32_16x16x32_bf16 v[86:89], v[166:169], v[198:201], v[86:89]
	v_mfma_f32_16x16x32_bf16 v[82:85], v[174:177], v[198:201], v[82:85]
	v_mfma_f32_16x16x32_bf16 v[70:73], v[166:169], v[206:209], v[70:73]
	v_mfma_f32_16x16x32_bf16 v[66:69], v[174:177], v[206:209], v[66:69]
	s_setprio 0
	s_barrier
	ds_read_b128 v[178:181], v162 offset:49152
	ds_read_b128 v[182:185], v162 offset:50176
	ds_read_b128 v[186:189], v162 offset:51200
	ds_read_b128 v[190:193], v162 offset:52224
	ds_read_b128 v[194:197], v162 offset:53248
	ds_read_b128 v[198:201], v162 offset:54272
	ds_read_b128 v[202:205], v162 offset:55296
	ds_read_b128 v[206:209], v162 offset:56320
	s_add_u32 s64, s62, 0x80
	s_addc_u32 s65, s63, 0
	s_mov_b32 m0, s30
	s_nop 0
	global_load_lds_dwordx4 v154, s[64:65]
	s_add_u32 s62, s62, 0x2b0080
	s_mov_b32 m0, s31
	s_nop 0
	global_load_lds_dwordx4 v156, s[64:65]
	s_addc_u32 s63, s63, 0
	s_mov_b32 m0, s67
	s_nop 0
	global_load_lds_dwordx4 v154, s[62:63]
	s_mov_b32 m0, s68
	s_nop 0
	global_load_lds_dwordx4 v156, s[62:63]
	s_mov_b32 m0, s33
	s_nop 0
	global_load_lds_dwordx4 v1, s[60:61]
	s_mov_b32 m0, s66
	s_nop 0
	global_load_lds_dwordx4 v155, s[60:61]
	s_waitcnt vmcnt(8)
	s_waitcnt lgkmcnt(0)
	s_barrier
	s_setprio 1
	v_mfma_f32_16x16x32_bf16 v[62:65], v[130:133], v[178:181], v[62:65]
	v_mfma_f32_16x16x32_bf16 v[58:61], v[142:145], v[178:181], v[58:61]
	v_mfma_f32_16x16x32_bf16 v[46:49], v[130:133], v[186:189], v[46:49]
	v_mfma_f32_16x16x32_bf16 v[42:45], v[142:145], v[186:189], v[42:45]
	v_mfma_f32_16x16x32_bf16 v[30:33], v[130:133], v[194:197], v[30:33]
	v_mfma_f32_16x16x32_bf16 v[26:29], v[142:145], v[194:197], v[26:29]
	v_mfma_f32_16x16x32_bf16 v[14:17], v[130:133], v[202:205], v[14:17]
	v_mfma_f32_16x16x32_bf16 v[10:13], v[142:145], v[202:205], v[10:13]
	v_mfma_f32_16x16x32_bf16 v[62:65], v[134:137], v[182:185], v[62:65]
	v_mfma_f32_16x16x32_bf16 v[58:61], v[146:149], v[182:185], v[58:61]
	v_mfma_f32_16x16x32_bf16 v[46:49], v[134:137], v[190:193], v[46:49]
	v_mfma_f32_16x16x32_bf16 v[42:45], v[146:149], v[190:193], v[42:45]
	v_mfma_f32_16x16x32_bf16 v[30:33], v[134:137], v[198:201], v[30:33]
	v_mfma_f32_16x16x32_bf16 v[26:29], v[146:149], v[198:201], v[26:29]
	v_mfma_f32_16x16x32_bf16 v[14:17], v[134:137], v[206:209], v[14:17]
	v_mfma_f32_16x16x32_bf16 v[10:13], v[146:149], v[206:209], v[10:13]
	s_setprio 0
	s_setprio 1
	v_mfma_f32_16x16x32_bf16 v[54:57], v[150:153], v[178:181], v[54:57]
	v_mfma_f32_16x16x32_bf16 v[50:53], v[170:173], v[178:181], v[50:53]
	v_mfma_f32_16x16x32_bf16 v[38:41], v[150:153], v[186:189], v[38:41]
	v_mfma_f32_16x16x32_bf16 v[34:37], v[170:173], v[186:189], v[34:37]
	v_mfma_f32_16x16x32_bf16 v[22:25], v[150:153], v[194:197], v[22:25]
	v_mfma_f32_16x16x32_bf16 v[18:21], v[170:173], v[194:197], v[18:21]
	v_mfma_f32_16x16x32_bf16 v[6:9], v[150:153], v[202:205], v[6:9]
	v_mfma_f32_16x16x32_bf16 v[2:5], v[170:173], v[202:205], v[2:5]
	v_mfma_f32_16x16x32_bf16 v[54:57], v[166:169], v[182:185], v[54:57]
	v_mfma_f32_16x16x32_bf16 v[50:53], v[174:177], v[182:185], v[50:53]
	v_mfma_f32_16x16x32_bf16 v[38:41], v[166:169], v[190:193], v[38:41]
	v_mfma_f32_16x16x32_bf16 v[34:37], v[174:177], v[190:193], v[34:37]
	v_mfma_f32_16x16x32_bf16 v[22:25], v[166:169], v[198:201], v[22:25]
	v_mfma_f32_16x16x32_bf16 v[18:21], v[174:177], v[198:201], v[18:21]
	v_mfma_f32_16x16x32_bf16 v[6:9], v[166:169], v[206:209], v[6:9]
	v_mfma_f32_16x16x32_bf16 v[2:5], v[174:177], v[206:209], v[2:5]
	s_setprio 0
	s_barrier
	s_add_i32 s78, s78, 2
	s_add_u32 s74, s74, 0x100
	s_addc_u32 s75, s75, 0
	s_add_u32 s76, s76, 0x100
	s_addc_u32 s77, s77, 0
	s_add_u32 s58, s58, 0x100
	s_addc_u32 s59, s59, 0
	s_cmpk_gt_u32 s78, 0xa9
	s_cbranch_scc0 .LBB0_1361
	s_and_b64 vcc, exec, s[36:37]
	s_cbranch_vccz .LBB0_1364
	s_barrier
